# P5: bucket-sort each token's (expert,gate) list by expert-id range, then run u-pass round-major across tokens so all waves touch the same 2MB id range at a time (L2-resident); act sums via per-wave LD
# speedup vs baseline: 1.0887x; 1.0322x over previous
; __global__ void __launch_bounds__(256, 2) mega(Params P) {
;     ...
;             unsigned nxt_ = 0u;
;             if (wave_u == 0) nxt_ = atomicAdd(&ctl[2], lane == 0 ? 1u : 0u);
.LBB0_347:
	s_mov_b32 s6, 1
	v_sub_u32_e32 v2, 1, v147
	v_mbcnt_lo_u32_b32 v4, exec_lo, 0
	v_mbcnt_hi_u32_b32 v4, exec_hi, v4
	v_cmp_eq_u32_e32 vcc, 0, v4
	s_and_saveexec_b64 s[0:1], vcc
	s_xor_b64 s[0:1], exec, s[0:1]
	s_cbranch_execz .LBB0_351
	v_mov_b32_e32 v4, s6
	global_atomic_add v4, v3, v4, s[28:29] offset:8 sc0

; __device__ __forceinline__ void peer_token(const Params& P, int t, int lane, int* sidx, float* sval, const int* sid, const float* sgate, const unsigned* szero) {
;     ...
;     {
;         typedef int v8i __attribute__((ext_vector_type(8)));
;         const unsigned char* Ub = P.ws + WS_U;
;         const unsigned lofs = 64u * (unsigned)(lr >> 3) + 16u * (unsigned)g;
;         const unsigned char* bsrc = (lr < 4) ? (((lr & 2) ? slo : shi) + 128 * (lr & 1) + 16 * g) : (const unsigned char*)szero;
;         const int bstep = (lr < 4) ? 256 : 0, bhalf = (lr < 4) ? 64 : 16;
;         v8i Bv[4];
; #pragma unroll
;         for (int st = 0; st < 4; ++st) {
;             const uint4 b0 = *(const uint4*)(bsrc + bstep * st), b1 = *(const uint4*)(bsrc + bstep * st + bhalf);
;             Bv[st] = (v8i){(int)b0.x, (int)b0.y, (int)b0.z, (int)b0.w, (int)b1.x, (int)b1.y, (int)b1.z, (int)b1.w};
;         }
;         __builtin_amdgcn_s_waitcnt(0xc07f);
;         __builtin_amdgcn_wave_barrier();
;         float* sact = (float*)sidx + 128 * (lr & 3) + 4 * (g & 1);
;         const bool owner = (lr < 4) && ((g >> 1) == (lr & 1));
; __global__ void __launch_bounds__(256, 2) mega(Params P) {
;     ...
;     {
;         unsigned* szero = (unsigned*)(smem + 40960);
;         if (tid < 16) szero[tid] = 0u;
;         __syncthreads();
;         unsigned char* res = smem + wave * 10240; unsigned char* work = res + 8192;
;         int* sidx = (int*)work; float* sval = (float*)(work + 1024);
;         int lane5 = lane;
;         asm volatile("" : "+v"(lane5));
;         const int tstride = G * 4;
;         for (int tb = bid * 4 + wave; tb < T2; tb += tstride * 8) {
.LBB0_1375:
	s_or_b64 exec, exec, s[18:19]
	v_cmp_gt_u32_e32 vcc, 16, v0
	s_barrier
	s_and_saveexec_b64 s[0:1], vcc
	v_lshl_add_u32 v0, v0, 2, 0
	v_mov_b32_e32 v2, 0
	ds_write_b32 v0, v2 offset:40960
	s_or_b64 exec, exec, s[0:1]
	s_movk_i32 s20, 0x4000
	v_cmp_gt_i32_e32 vcc, s20, v130
	s_waitcnt lgkmcnt(0)
	s_barrier
	s_and_saveexec_b64 s[0:1], vcc
	s_cbranch_execz .LBB0_1426
	s_movk_i32 s0, 0x2800
	v_and_b32_e32 v115, 7, v131
	v_mad_u32_u24 v114, v1, s0, 0
	v_lshlrev_b32_e32 v0, 7, v115
	v_mov_b32_e32 v1, 0
	v_ashrrev_i32_e32 v2, 3, v131
	v_lshl_add_u64 v[0:1], s[28:29], 0, v[0:1]
	s_mov_b64 s[0:1], 0xc075800
	v_lshl_add_u64 v[100:101], v[0:1], 0, s[0:1]
	v_lshlrev_b32_e32 v0, 10, v2
	v_lshlrev_b32_e32 v1, 6, v115
	s_add_u32 s4, s28, 0x93b3000
	v_add3_u32 v118, v114, v0, v1
	s_addc_u32 s5, s29, 0
	v_lshlrev_b32_e32 v1, 3, v131
	v_and_b32_e32 v3, 2, v131
	v_mul_lo_u32 v116, v2, s22
	s_add_u32 s6, s28, 0xf5a5800
	v_and_b32_e32 v1, 64, v1
	v_and_b32_e32 v2, -16, v131
	v_mov_b32_e32 v4, 0x2000
	v_mov_b32_e32 v5, 0x2400
	v_cmp_eq_u32_e32 vcc, 0, v3
	s_addc_u32 s7, s29, 0
	v_add_u32_e32 v120, v1, v2
	v_lshlrev_b32_e32 v1, 7, v131
	v_cndmask_b32_e32 v3, v4, v5, vcc
	s_add_u32 s8, s28, 0xf595800
	v_add_u32_e32 v3, v114, v3
	v_and_b32_e32 v1, 0x80, v1
	s_addc_u32 s9, s29, 0
	v_and_b32_e32 v0, 15, v131
	v_add3_u32 v2, v3, v1, v2
	v_ashrrev_i32_e32 v3, 5, v131
	v_and_b32_e32 v1, 1, v131
	s_add_u32 s10, s28, 0xe595800
	v_cmp_eq_u32_e32 vcc, v3, v1
	v_cmp_gt_u32_e64 s[2:3], 4, v0
	v_and_b32_e32 v0, 31, v131
	v_lshlrev_b32_e32 v1, 4, v3
	s_addc_u32 s11, s29, 0
	s_and_b64 s[12:13], s[2:3], vcc
	v_lshl_add_u32 v104, v0, 5, v1
	s_add_u32 s14, s28, 0xed95800
	v_ashrrev_i32_e32 v105, 31, v104
	s_addc_u32 s15, s29, 0
	v_lshlrev_b32_e32 v122, 4, v0
	v_lshlrev_b64 v[0:1], 2, v[104:105]
	s_add_i32 s16, 0, 0xa000
	v_lshl_add_u64 v[106:107], s[26:27], 0, v[0:1]
	v_lshl_add_u64 v[108:109], s[44:45], 0, v[0:1]
	v_mov_b32_e32 v0, 0x100
	v_mov_b32_e32 v1, s16
	v_cndmask_b32_e64 v0, 0, v0, s[2:3]
	v_cndmask_b32_e64 v123, v1, v2, s[2:3]
	v_lshlrev_b32_e32 v102, 4, v131
	v_add_u32_e32 v124, v123, v0
	v_lshl_add_u32 v125, v0, 1, v123
	v_mad_u32_u24 v126, v0, 3, v123
	v_lshlrev_b32_e32 v0, 9, v131
	v_add_u32_e32 v119, v114, v102
	v_and_b32_e32 v4, 16, v131
	v_mul_lo_u32 v5, v131, -12
	v_and_b32_e32 v0, 0x600, v0
	v_lshl_add_u32 v117, v131, 5, v114
	v_ashrrev_i32_e32 v103, 31, v102
	v_cndmask_b32_e64 v121, 16, 64, s[2:3]
	v_cmp_gt_u32_e64 s[0:1], 32, v131
	s_lshl_b32 s21, s33, 5
	v_add3_u32 v127, v114, v4, v0
	v_lshlrev_b32_e32 v128, 2, v3
	s_mov_b64 s[2:3], 0
	v_bfrev_b32_e32 v129, 1
	s_movk_i32 s23, 0xff80
	s_movk_i32 s24, 0x7f
	s_movk_i32 s25, 0xff00
	v_mov_b32_e32 v132, 0xffffff00
	s_movk_i32 s26, 0xff
	s_movk_i32 s27, 0xfe
	s_movk_i32 s28, 0xfd
	s_movk_i32 s29, 0xfc
	s_movk_i32 s30, 0xfb
	s_movk_i32 s31, 0xfa
	s_movk_i32 s33, 0xf9
	s_movk_i32 s34, 0xf8
	s_movk_i32 s35, 0xf7
	s_movk_i32 s38, 0xf6
	s_movk_i32 s39, 0xf5
	s_movk_i32 s40, 0xf4
	s_movk_i32 s41, 0xf3
	s_movk_i32 s42, 0xf2
	s_movk_i32 s43, 0xf1
	s_movk_i32 s44, 0xf0
	s_movk_i32 s45, 0xef
	s_movk_i32 s46, 0xee
	s_movk_i32 s47, 0xed
	s_movk_i32 s48, 0xec
	s_movk_i32 s49, 0xeb
	s_movk_i32 s50, 0xea
	s_movk_i32 s51, 0xe9
	s_movk_i32 s52, 0xe8
	s_movk_i32 s53, 0xdf
	s_movk_i32 s54, 0xde
	s_movk_i32 s55, 0xdd
	s_movk_i32 s56, 0xdc
	s_movk_i32 s57, 0xdb
	s_movk_i32 s58, 0xcf
	s_movk_i32 s59, 0xce
	s_movk_i32 s60, 0xcd
	s_movk_i32 s61, 0xcc
	s_movk_i32 s62, 0xbf
	s_movk_i32 s63, 0xbe
	s_movk_i32 s64, 0xbd
	s_movk_i32 s65, 0xaf
	s_movk_i32 s66, 0xae
	s_movk_i32 s67, 0x9f
	s_movk_i32 s68, 0x9e
	s_movk_i32 s69, 0x8f
	s_movk_i32 s70, 0x8e
	s_movk_i32 s71, 0x6f
	s_movk_i32 s72, 0x5f
	s_movk_i32 s73, 0x4f
	v_mov_b32_e32 v133, 0x7f7f7f7f
	s_mov_b32 s74, 0x378e98ab
	s_mov_b32 s75, 0x3b7cd369
	s_mov_b32 s76, 0xbcc618b2
	s_mov_b32 s77, 0x3dda74e4
	s_mov_b32 s78, 0x3f228afd
	s_mov_b32 s79, 0x3e03c728
	s_mov_b32 s80, 0xbfb8aa3b
	s_mov_b32 s81, 0x42ce8ed0
	s_mov_b32 s82, 0xc2b17218
	v_mov_b32_e32 v134, 0x3ba10414
	s_brev_b32 s83, -2
	s_movk_i32 s84, 0x3fff
	v_add_u32_e32 v135, v119, v5
	v_mov_b32_e32 v136, 0xb9c68948
	v_mov_b32_e32 v137, 0x7f800000
	v_lshrrev_b32_e32 v142, 4, v131
	v_and_b32_e32 v143, 3, v131
	v_lshlrev_b32_e32 v144, 6, v142
	v_lshl_add_u32 v144, v143, 4, v144
	v_and_b32_e32 v145, 12, v131
	v_and_b32_e32 v146, 15, v131
	v_lshrrev_b32_e32 v147, 1, v142
	v_lshlrev_b32_e32 v147, 7, v147
	v_and_b32_e32 v148, 1, v142
	v_lshl_add_u32 v147, v148, 4, v147
	v_lshl_add_u32 v147, v143, 5, v147
	v_and_b32_e32 v148, 4, v146
	v_cmp_eq_u32_e32 vcc, 0, v148
	v_mov_b32_e32 v149, 0x400
	s_nop 1
	v_cndmask_b32_e32 v148, 0, v149, vcc
	v_add3_u32 v147, v147, v148, v114
	v_add_u32_e32 v147, 0x2000, v147
	v_cmp_gt_u32_e32 vcc, 8, v146
	v_mov_b32_e32 v149, 0xa000
	v_add_u32_e32 v148, 16, v149
	v_add_u32_e32 v151, 0x100, v147
	v_add_u32_e32 v152, 0x200, v147
	v_add_u32_e32 v153, 0x300, v147
	v_cndmask_b32_e32 v150, v149, v147, vcc
	v_cndmask_b32_e32 v151, v148, v151, vcc
	v_cndmask_b32_e32 v152, v149, v152, vcc
	v_cndmask_b32_e32 v153, v148, v153, vcc
	v_add_u32_e32 v154, 0x2000, v114
	v_lshl_add_u32 v155, v142, 2, v154
	v_lshl_add_u32 v156, v131, 2, v154
	v_add_u32_e32 v156, 0x400, v156
	v_and_b32_e32 v157, 11, v146
	v_lshrrev_b32_e32 v156, 11, v114
	v_mul_u32_u24_e32 v156, 52, v156
	v_lshrrev_b32_e32 v156, 8, v156
	v_lshlrev_b32_e32 v156, 12, v156
	v_add_u32_e32 v156, 0xa800, v156
	v_lshl_add_u32 v155, v142, 2, v156
	v_lshl_add_u32 v156, v131, 2, v156
	v_cmp_eq_u32_e32 vcc, 0, v157
	s_nop 1
	v_cndmask_b32_e64 v158, 0, 1.0, vcc
	v_cmp_eq_u32_e32 vcc, 1, v157
	s_nop 1
	v_cndmask_b32_e64 v159, 0, 1.0, vcc
	v_cmp_eq_u32_e32 vcc, 2, v157
	s_nop 1
	v_cndmask_b32_e64 v160, 0, 1.0, vcc
	v_cmp_eq_u32_e32 vcc, 3, v157
	s_nop 1
	v_cndmask_b32_e64 v161, 0, 1.0, vcc
	s_branch .LBB0_1380

; __device__ __forceinline__ unsigned ord_key(float f) { unsigned u = __float_as_uint(f); return u ^ ((u >> 31) ? 0xffffffffu : 0x80000000u); }
; __device__ __forceinline__ void peer_stage2_batch(const Params& P, int tbase, int tstride, int lane, unsigned char* res, unsigned char* scr) {
;     const int tau = lane >> 3, hd = lane & 7;
;     const int t = tbase + tau * tstride;
;     const uint4* lp = (const uint4*)((const unsigned*)(P.ws + WS_TK) + (size_t)(t < T2 ? t : tbase) * 256 + hd * 32);
;     const uint4 L0 = lp[0], L1 = lp[1], L2 = lp[2], L3 = lp[3], L4 = lp[4], L5 = lp[5], L6 = lp[6], L7 = lp[7];
;     const unsigned ka[16] = {L0.x, L0.y, L0.z, L0.w, L1.x, L1.y, L1.z, L1.w, L2.x, L2.y, L2.z, L2.w, L3.x, L3.y, L3.z, L3.w};
;     const unsigned kb[16] = {L4.x, L4.y, L4.z, L4.w, L5.x, L5.y, L5.z, L5.w, L6.x, L6.y, L6.z, L6.w, L7.x, L7.y, L7.z, L7.w};
;     float va[16], vb[16];
; #pragma unroll
;     for (int i = 0; i < 16; ++i) { va[i] = unord_key(ka[i] & ~127u); vb[i] = unord_key(kb[i] & ~127u); }
;     {
;         unsigned w[8];
; #pragma unroll
;         for (int q = 0; q < 4; ++q) {
;             w[q]     = (127u - (ka[4 * q] & 127u)) | ((127u - (ka[4 * q + 1] & 127u)) << 8) | ((127u - (ka[4 * q + 2] & 127u)) << 16) | ((127u - (ka[4 * q + 3] & 127u)) << 24);
;             w[4 + q] = (127u - (kb[4 * q] & 127u)) | ((127u - (kb[4 * q + 1] & 127u)) << 8) | ((127u - (kb[4 * q + 2] & 127u)) << 16) | ((127u - (kb[4 * q + 3] & 127u)) << 24);
;         }
;         *(uint4*)(scr + lane * 32) = make_uint4(w[0], w[1], w[2], w[3]);
;         *(uint4*)(scr + lane * 32 + 16) = make_uint4(w[4], w[5], w[6], w[7]);
;     }
;     unsigned top[16] = {((ord_key(va[0] + vb[0]) & ~255u) | 255u), ((ord_key(va[0] + vb[1]) & ~255u) | 254u), ((ord_key(va[0] + vb[2]) & ~255u) | 253u), ((ord_key(va[0] + vb[3]) & ~255u) | 252u), ((ord_key(va[0] + vb[4]) & ~255u) | 251u), ((ord_key(va[0] + vb[5]) & ~255u) | 250u), ((ord_key(va[0] + vb[6]) & ~255u) | 249u), ((ord_key(va[0] + vb[7]) & ~255u) | 248u), ((ord_key(va[0] + vb[8]) & ~255u) | 247u), ((ord_key(va[0] + vb[9]) & ~255u) | 246u), ((ord_key(va[0] + vb[10]) & ~255u) | 245u), ((ord_key(va[0] + vb[11]) & ~255u) | 244u), ((ord_key(va[0] + vb[12]) & ~255u) | 243u), ((ord_key(va[0] + vb[13]) & ~255u) | 242u), ((ord_key(va[0] + vb[14]) & ~255u) | 241u), ((ord_key(va[0] + vb[15]) & ~255u) | 240u)};
.LBB0_1380:
	v_add_u32_e32 v0, v130, v116
	v_cmp_gt_i32_e32 vcc, s20, v0
	v_mov_b32_e32 v138, v128
	s_mov_b32 s85, 0
	v_cndmask_b32_e32 v0, v130, v0, vcc
	v_ashrrev_i32_e32 v1, 31, v0
	v_lshlrev_b64 v[0:1], 10, v[0:1]
	v_lshl_add_u64 v[8:9], v[100:101], 0, v[0:1]
	global_load_dwordx4 v[16:19], v[8:9], off offset:16
	global_load_dwordx4 v[30:33], v[8:9], off
	global_load_dwordx4 v[0:3], v[8:9], off offset:48
	global_load_dwordx4 v[4:7], v[8:9], off offset:32
	global_load_dwordx4 v[34:37], v[8:9], off offset:64
	global_load_dwordx4 v[38:41], v[8:9], off offset:80
	global_load_dwordx4 v[12:15], v[8:9], off offset:96
	s_nop 0
	global_load_dwordx4 v[8:11], v[8:9], off offset:112
	s_waitcnt vmcnt(7)
	v_cmp_lt_i32_e32 vcc, -1, v17
	s_nop 1
	v_cndmask_b32_e64 v20, v129, -1, vcc
	v_cmp_lt_i32_e32 vcc, -1, v18
	v_lshlrev_b32_e32 v24, 8, v17
	s_waitcnt vmcnt(6)
	v_lshlrev_b32_e32 v25, 8, v31
	v_cndmask_b32_e64 v21, v129, -1, vcc
	s_waitcnt vmcnt(5)
	v_cmp_lt_i32_e32 vcc, -1, v3
	v_lshlrev_b32_e32 v46, 8, v1
	s_waitcnt vmcnt(4)
	v_lshlrev_b32_e32 v47, 8, v5
	v_cndmask_b32_e64 v43, v129, -1, vcc
	s_waitcnt vmcnt(3)
	v_cmp_lt_i32_e32 vcc, -1, v34
	v_and_b32_e32 v23, 0x7f, v16
	v_and_b32_e32 v26, 0x7f, v30
	v_cndmask_b32_e64 v54, v129, -1, vcc
	v_cmp_lt_i32_e32 vcc, -1, v2
	v_lshlrev_b32_e32 v27, 16, v18
	v_lshlrev_b32_e32 v28, 16, v32
	v_cndmask_b32_e64 v55, v129, -1, vcc
	v_cmp_lt_i32_e32 vcc, -1, v35
	v_lshlrev_b32_e32 v29, 24, v19
	v_and_b32_e32 v44, 0x7f, v0
	v_cndmask_b32_e64 v58, v129, -1, vcc
	v_cmp_lt_i32_e32 vcc, -1, v19
	v_and_b32_e32 v45, 0x7f, v4
	v_lshlrev_b32_e32 v48, 16, v2
	v_lshlrev_b32_e32 v49, 16, v6
	v_lshlrev_b32_e32 v50, 24, v3
	v_and_b32_e32 v53, 0xffffff80, v2
	v_and_b32_e32 v57, 0xffffff80, v19
	v_cndmask_b32_e64 v19, v129, -1, vcc
	v_and_b32_e32 v63, 0x7f00, v24
	v_and_b32_e32 v64, 0x7f00, v25
	v_bitop3_b32 v2, v43, v3, s23 bitop3:0x78
	v_and_b32_e32 v3, 0x7f00, v46
	v_and_b32_e32 v43, 0x7f00, v47
	v_lshlrev_b32_e32 v42, 24, v33
	v_lshlrev_b32_e32 v51, 24, v7
	v_cmp_lt_i32_e32 vcc, -1, v36
	v_bitop3_b32 v22, v20, v17, s23 bitop3:0x78
	v_and_b32_e32 v27, 0x7f0000, v27
	v_and_b32_e32 v28, 0x7f0000, v28
	v_and_b32_e32 v46, 0x7f0000, v48
	v_and_b32_e32 v47, 0x7f0000, v49
	v_xor_b32_e32 v20, v19, v57
	v_or_b32_e32 v19, v63, v23
	v_or_b32_e32 v23, v64, v26
	v_or_b32_e32 v3, v3, v44
	v_or_b32_e32 v26, v43, v45
	v_cndmask_b32_e64 v61, v129, -1, vcc
	v_cmp_lt_i32_e32 vcc, -1, v16
	v_and_b32_e32 v29, 0x7f000000, v29
	v_and_b32_e32 v42, 0x7f000000, v42
	v_and_b32_e32 v48, 0x7f000000, v50
	v_and_b32_e32 v49, 0x7f000000, v51
	v_or_b32_e32 v19, v19, v27
	v_or_b32_e32 v23, v23, v28
	v_or_b32_e32 v3, v3, v46
	v_or_b32_e32 v26, v26, v47
	v_cndmask_b32_e64 v62, v129, -1, vcc
	v_or_b32_e32 v19, v19, v29
	v_or_b32_e32 v23, v23, v42
	v_or_b32_e32 v3, v3, v48
	v_or_b32_e32 v28, v26, v49
	v_cmp_lt_i32_e32 vcc, -1, v37
	v_xor_b32_e32 v27, 0x7f7f7f7f, v19
	v_xor_b32_e32 v26, 0x7f7f7f7f, v23
	v_xor_b32_e32 v29, 0x7f7f7f7f, v3
	v_xor_b32_e32 v28, 0x7f7f7f7f, v28
	v_cndmask_b32_e64 v23, v129, -1, vcc
	v_cmp_lt_i32_e32 vcc, -1, v33
	ds_write_b128 v117, v[26:29] offset:8192
	v_and_b32_e32 v3, 0xffffff80, v37
	v_cndmask_b32_e64 v26, v129, -1, vcc
	s_waitcnt vmcnt(2)
	v_cmp_lt_i32_e32 vcc, -1, v38
	v_xor_b32_e32 v27, v23, v3
	v_and_b32_e32 v3, 0xffffff80, v38
	v_cndmask_b32_e64 v23, v129, -1, vcc
	v_cmp_lt_i32_e32 vcc, -1, v32
	v_xor_b32_e32 v29, v23, v3
	v_and_b32_e32 v19, 0xffffff80, v33
	v_cndmask_b32_e64 v28, v129, -1, vcc
	v_cmp_lt_i32_e32 vcc, -1, v39
	v_xor_b32_e32 v26, v26, v19
	v_and_b32_e32 v19, 0xffffff80, v32
	v_cndmask_b32_e64 v3, v129, -1, vcc
	v_cmp_lt_i32_e32 vcc, -1, v40
	v_bitop3_b32 v42, v3, v39, s23 bitop3:0x78
	v_xor_b32_e32 v28, v28, v19
	v_cndmask_b32_e64 v3, v129, -1, vcc
	v_cmp_lt_i32_e32 vcc, -1, v41
	v_bitop3_b32 v45, v3, v40, s23 bitop3:0x78
	v_and_b32_e32 v3, 0xffffff80, v41
	v_cndmask_b32_e64 v23, v129, -1, vcc
	v_cmp_lt_i32_e32 vcc, -1, v31
	v_xor_b32_e32 v47, v23, v3
	v_lshlrev_b32_e32 v23, 8, v39
	v_and_b32_e32 v19, 0xffffff80, v31
	v_cndmask_b32_e64 v31, v129, -1, vcc
	v_and_b32_e32 v3, 0x7f, v38
	v_and_b32_e32 v23, 0x7f00, v23
	v_xor_b32_e32 v46, v31, v19
	v_lshlrev_b32_e32 v31, 8, v35
	v_or_b32_e32 v3, v23, v3
	v_lshlrev_b32_e32 v23, 16, v40
	v_and_b32_e32 v19, 0x7f, v34
	v_and_b32_e32 v31, 0x7f00, v31
	v_and_b32_e32 v23, 0x7f0000, v23
	v_or_b32_e32 v19, v31, v19
	v_lshlrev_b32_e32 v31, 16, v36
	v_or_b32_e32 v3, v3, v23
	v_lshlrev_b32_e32 v23, 24, v41
	v_and_b32_e32 v31, 0x7f0000, v31
	v_and_b32_e32 v23, 0x7f000000, v23
	v_or_b32_e32 v19, v19, v31
	v_lshlrev_b32_e32 v31, 24, v37
	v_or_b32_e32 v3, v3, v23
	s_waitcnt vmcnt(0)
; __device__ __forceinline__ unsigned ord_key(float f) { unsigned u = __float_as_uint(f); return u ^ ((u >> 31) ? 0xffffffffu : 0x80000000u); }
; __device__ __forceinline__ void peer_stage2_batch(const Params& P, int tbase, int tstride, int lane, unsigned char* res, unsigned char* scr) {
;     ...
;             w[q]     = (127u - (ka[4 * q] & 127u)) | ((127u - (ka[4 * q + 1] & 127u)) << 8) | ((127u - (ka[4 * q + 2] & 127u)) << 16) | ((127u - (ka[4 * q + 3] & 127u)) << 24);
;             w[4 + q] = (127u - (kb[4 * q] & 127u)) | ((127u - (kb[4 * q + 1] & 127u)) << 8) | ((127u - (kb[4 * q + 2] & 127u)) << 16) | ((127u - (kb[4 * q + 3] & 127u)) << 24);
;         }
;         *(uint4*)(scr + lane * 32) = make_uint4(w[0], w[1], w[2], w[3]);
;         *(uint4*)(scr + lane * 32 + 16) = make_uint4(w[4], w[5], w[6], w[7]);
;     }
;     unsigned top[16] = {((ord_key(va[0] + vb[0]) & ~255u) | 255u), ((ord_key(va[0] + vb[1]) & ~255u) | 254u), ((ord_key(va[0] + vb[2]) & ~255u) | 253u), ((ord_key(va[0] + vb[3]) & ~255u) | 252u), ((ord_key(va[0] + vb[4]) & ~255u) | 251u), ((ord_key(va[0] + vb[5]) & ~255u) | 250u), ((ord_key(va[0] + vb[6]) & ~255u) | 249u), ((ord_key(va[0] + vb[7]) & ~255u) | 248u), ((ord_key(va[0] + vb[8]) & ~255u) | 247u), ((ord_key(va[0] + vb[9]) & ~255u) | 246u), ((ord_key(va[0] + vb[10]) & ~255u) | 245u), ((ord_key(va[0] + vb[11]) & ~255u) | 244u), ((ord_key(va[0] + vb[12]) & ~255u) | 243u), ((ord_key(va[0] + vb[13]) & ~255u) | 242u), ((ord_key(va[0] + vb[14]) & ~255u) | 241u), ((ord_key(va[0] + vb[15]) & ~255u) | 240u)};
;     {
;         unsigned gq[16] = {((ord_key(va[1] + vb[0]) & ~255u) | 239u), ((ord_key(va[1] + vb[1]) & ~255u) | 238u), ((ord_key(va[1] + vb[2]) & ~255u) | 237u), ((ord_key(va[1] + vb[3]) & ~255u) | 236u), ((ord_key(va[1] + vb[4]) & ~255u) | 235u), ((ord_key(va[1] + vb[5]) & ~255u) | 234u), ((ord_key(va[1] + vb[6]) & ~255u) | 233u), ((ord_key(va[1] + vb[7]) & ~255u) | 232u), ((ord_key(va[2] + vb[0]) & ~255u) | 223u), ((ord_key(va[2] + vb[1]) & ~255u) | 222u), ((ord_key(va[2] + vb[2]) & ~255u) | 221u), ((ord_key(va[2] + vb[3]) & ~255u) | 220u), ((ord_key(va[2] + vb[4]) & ~255u) | 219u), ((ord_key(va[3] + vb[0]) & ~255u) | 207u), ((ord_key(va[3] + vb[1]) & ~255u) | 206u), ((ord_key(va[3] + vb[2]) & ~255u) | 205u)};
	v_cmp_lt_i32_e32 vcc, -1, v10
	v_and_b32_e32 v31, 0x7f000000, v31
	v_xor_b32_e32 v33, 0x7f7f7f7f, v3
	v_cndmask_b32_e64 v3, v129, -1, vcc
	v_cmp_lt_i32_e32 vcc, -1, v11
	v_or_b32_e32 v19, v19, v31
	v_bitop3_b32 v31, v3, v10, s23 bitop3:0x78
	v_and_b32_e32 v3, 0xffffff80, v11
	v_cndmask_b32_e64 v23, v129, -1, vcc
	v_cmp_lt_i32_e32 vcc, -1, v30
	v_xor_b32_e32 v32, 0x7f7f7f7f, v19
	v_and_b32_e32 v19, 0xffffff80, v30
	v_cndmask_b32_e64 v30, v129, -1, vcc
	v_xor_b32_e32 v37, v23, v3
	v_lshlrev_b32_e32 v23, 8, v9
	v_and_b32_e32 v59, 0xffffff80, v36
	v_xor_b32_e32 v36, v30, v19
	v_and_b32_e32 v3, 0x7f, v8
	v_lshlrev_b32_e32 v30, 8, v13
	v_and_b32_e32 v23, 0x7f00, v23
	v_and_b32_e32 v19, 0x7f, v12
	v_and_b32_e32 v30, 0x7f00, v30
	v_or_b32_e32 v3, v23, v3
	v_lshlrev_b32_e32 v10, 16, v10
	v_lshlrev_b32_e32 v23, 16, v14
	v_or_b32_e32 v19, v30, v19
	v_and_b32_e32 v10, 0x7f0000, v10
	v_and_b32_e32 v23, 0x7f0000, v23
	v_or_b32_e32 v3, v3, v10
	v_or_b32_e32 v10, v19, v23
	v_lshlrev_b32_e32 v11, 24, v11
	v_lshlrev_b32_e32 v19, 24, v15
	v_and_b32_e32 v52, 0xffffff80, v34
	v_and_b32_e32 v56, 0xffffff80, v35
	v_and_b32_e32 v11, 0x7f000000, v11
	v_and_b32_e32 v19, 0x7f000000, v19
	v_bitop3_b32 v18, v21, v18, s23 bitop3:0x78
	v_xor_b32_e32 v17, v54, v52
	v_xor_b32_e32 v21, v58, v56
	v_or_b32_e32 v3, v3, v11
	v_or_b32_e32 v10, v10, v19
	v_xor_b32_e32 v35, 0x7f7f7f7f, v3
	v_xor_b32_e32 v34, 0x7f7f7f7f, v10
	v_mov_b32_e32 v10, v21
	v_mov_b32_e32 v11, v17
	ds_write_b128 v117, v[32:35] offset:8208
	v_pk_add_f32 v[32:33], v[36:37], v[10:11] op_sel_hi:[0,1]
	v_cmp_lt_i32_e32 vcc, -1, v33
	v_xor_b32_e32 v25, v61, v59
	v_and_b32_e32 v23, 0xffffff00, v32
	v_cndmask_b32_e32 v3, v132, v129, vcc
	v_bitop3_b32 v3, v3, s26, v33 bitop3:0xde
	v_cmp_lt_i32_e32 vcc, -1, v32
	v_mov_b32_e32 v32, v27
	v_mov_b32_e32 v33, v25
	v_pk_add_f32 v[34:35], v[36:37], v[32:33] op_sel_hi:[0,1]
	v_cndmask_b32_e32 v19, v132, v129, vcc
	v_cmp_lt_i32_e32 vcc, -1, v35
	v_bitop3_b32 v19, v19, s27, v23 bitop3:0xde
	v_and_b32_e32 v30, 0xffffff00, v35
	v_cndmask_b32_e32 v23, v132, v129, vcc
	v_cmp_lt_i32_e32 vcc, -1, v34
	v_bitop3_b32 v23, v23, s28, v30 bitop3:0xde
	v_and_b32_e32 v34, 0xffffff00, v34
	v_cndmask_b32_e32 v30, v132, v129, vcc
	v_mov_b32_e32 v43, v29
	v_bitop3_b32 v38, v30, s29, v34 bitop3:0xde
	v_pk_add_f32 v[34:35], v[36:37], v[42:43] op_sel_hi:[0,1]
	v_cmp_lt_i32_e32 vcc, -1, v35
	v_and_b32_e32 v35, 0xffffff00, v35
	v_mov_b32_e32 v44, v47
	v_cndmask_b32_e32 v30, v132, v129, vcc
	v_cmp_lt_i32_e32 vcc, -1, v34
	v_bitop3_b32 v39, v30, s30, v35 bitop3:0xde
	v_and_b32_e32 v34, 0xffffff00, v34
	v_cndmask_b32_e32 v30, v132, v129, vcc
	v_bitop3_b32 v40, v30, s31, v34 bitop3:0xde
	v_pk_add_f32 v[34:35], v[36:37], v[44:45] op_sel_hi:[0,1]
	v_cmp_lt_i32_e32 vcc, -1, v35
	v_and_b32_e32 v35, 0xffffff00, v35
	v_and_b32_e32 v41, 0xffffff80, v12
	v_cndmask_b32_e32 v30, v132, v129, vcc
	v_cmp_lt_i32_e32 vcc, -1, v34
	v_bitop3_b32 v35, v30, s33, v35 bitop3:0xde
	v_and_b32_e32 v34, 0xffffff00, v34
	v_cndmask_b32_e32 v30, v132, v129, vcc
	v_cmp_lt_i32_e32 vcc, -1, v13
	v_bitop3_b32 v34, v30, s34, v34 bitop3:0xde
	v_and_b32_e32 v30, 0xffffff80, v13
	v_cndmask_b32_e64 v13, v129, -1, vcc
	v_cmp_lt_i32_e32 vcc, -1, v12
	v_xor_b32_e32 v13, v13, v30
	v_and_b32_e32 v60, 0xffffff80, v16
	v_cndmask_b32_e64 v12, v129, -1, vcc
	v_xor_b32_e32 v12, v12, v41
	v_pk_add_f32 v[12:13], v[36:37], v[12:13] op_sel_hi:[0,1]
	v_cmp_lt_i32_e32 vcc, -1, v12
	v_and_b32_e32 v12, 0xffffff00, v12
	v_xor_b32_e32 v16, v55, v53
	v_cndmask_b32_e32 v30, v132, v129, vcc
	v_cmp_lt_i32_e32 vcc, -1, v13
	v_bitop3_b32 v41, v30, s35, v12 bitop3:0xde
	v_and_b32_e32 v13, 0xffffff00, v13
	v_cndmask_b32_e32 v12, v132, v129, vcc
	v_cmp_lt_i32_e32 vcc, -1, v15
	v_bitop3_b32 v48, v12, s38, v13 bitop3:0xde
	v_and_b32_e32 v12, 0xffffff80, v15
	v_cndmask_b32_e64 v13, v129, -1, vcc
	v_cmp_lt_i32_e32 vcc, -1, v14
	v_and_b32_e32 v30, 0xffffff80, v14
	v_xor_b32_e32 v13, v13, v12
	v_cndmask_b32_e64 v14, v129, -1, vcc
	v_xor_b32_e32 v12, v14, v30
	v_pk_add_f32 v[12:13], v[36:37], v[12:13] op_sel_hi:[0,1]
	v_cmp_lt_i32_e32 vcc, -1, v12
	v_and_b32_e32 v12, 0xffffff00, v12
	v_mov_b32_e32 v30, v37
	v_cndmask_b32_e32 v14, v132, v129, vcc
	v_cmp_lt_i32_e32 vcc, -1, v13
	v_bitop3_b32 v14, v14, s39, v12 bitop3:0xde
	v_and_b32_e32 v13, 0xffffff00, v13
	v_cndmask_b32_e32 v12, v132, v129, vcc
	v_cmp_lt_i32_e32 vcc, -1, v9
	v_bitop3_b32 v15, v12, s40, v13 bitop3:0xde
	v_and_b32_e32 v12, 0xffffff80, v9
	v_cndmask_b32_e64 v9, v129, -1, vcc
	v_cmp_lt_i32_e32 vcc, -1, v8
	v_and_b32_e32 v13, 0xffffff80, v8
	v_xor_b32_e32 v9, v9, v12
	v_cndmask_b32_e64 v8, v129, -1, vcc
	v_xor_b32_e32 v8, v8, v13
	v_pk_add_f32 v[8:9], v[36:37], v[8:9] op_sel_hi:[0,1]
	v_cmp_lt_i32_e32 vcc, -1, v8
	v_and_b32_e32 v8, 0xffffff00, v8
	v_xor_b32_e32 v24, v62, v60
	v_cndmask_b32_e32 v12, v132, v129, vcc
	v_cmp_lt_i32_e32 vcc, -1, v9
	v_bitop3_b32 v49, v12, s41, v8 bitop3:0xde
	v_and_b32_e32 v9, 0xffffff00, v9
	v_cndmask_b32_e32 v8, v132, v129, vcc
	v_bitop3_b32 v50, v8, s42, v9 bitop3:0xde
	v_pk_add_f32 v[8:9], v[36:37], v[30:31] op_sel_hi:[0,1]
	v_cmp_lt_i32_e32 vcc, -1, v9
	v_and_b32_e32 v9, 0xffffff00, v9
	s_waitcnt lgkmcnt(0)
; __device__ __forceinline__ unsigned ord_key(float f) { unsigned u = __float_as_uint(f); return u ^ ((u >> 31) ? 0xffffffffu : 0x80000000u); }
; __device__ __forceinline__ void bitonic_sort16_desc(unsigned (&v)[16]) {
; #pragma unroll
;     for (int k = 2; k <= 16; k <<= 1)
; #pragma unroll
;         for (int j = k >> 1; j >= 1; j >>= 1)
; #pragma unroll
;             for (int i = 0; i < 16; ++i)
;                 if ((i & j) == 0) {
;                     const int p = i | j;
;                     const bool desc = (k >= 16) ? true : ((i & k) == 0);
;                     const unsigned hi = max(v[i], v[p]), lo = min(v[i], v[p]);
;                     v[i] = desc ? hi : lo; v[p] = desc ? lo : hi;
;                 }
; }
; __device__ __forceinline__ void peer_stage2_batch(const Params& P, int tbase, int tstride, int lane, unsigned char* res, unsigned char* scr) {
;     ...
;     unsigned top[16] = {((ord_key(va[0] + vb[0]) & ~255u) | 255u), ((ord_key(va[0] + vb[1]) & ~255u) | 254u), ((ord_key(va[0] + vb[2]) & ~255u) | 253u), ((ord_key(va[0] + vb[3]) & ~255u) | 252u), ((ord_key(va[0] + vb[4]) & ~255u) | 251u), ((ord_key(va[0] + vb[5]) & ~255u) | 250u), ((ord_key(va[0] + vb[6]) & ~255u) | 249u), ((ord_key(va[0] + vb[7]) & ~255u) | 248u), ((ord_key(va[0] + vb[8]) & ~255u) | 247u), ((ord_key(va[0] + vb[9]) & ~255u) | 246u), ((ord_key(va[0] + vb[10]) & ~255u) | 245u), ((ord_key(va[0] + vb[11]) & ~255u) | 244u), ((ord_key(va[0] + vb[12]) & ~255u) | 243u), ((ord_key(va[0] + vb[13]) & ~255u) | 242u), ((ord_key(va[0] + vb[14]) & ~255u) | 241u), ((ord_key(va[0] + vb[15]) & ~255u) | 240u)};
;     {
;         unsigned gq[16] = {((ord_key(va[1] + vb[0]) & ~255u) | 239u), ((ord_key(va[1] + vb[1]) & ~255u) | 238u), ((ord_key(va[1] + vb[2]) & ~255u) | 237u), ((ord_key(va[1] + vb[3]) & ~255u) | 236u), ((ord_key(va[1] + vb[4]) & ~255u) | 235u), ((ord_key(va[1] + vb[5]) & ~255u) | 234u), ((ord_key(va[1] + vb[6]) & ~255u) | 233u), ((ord_key(va[1] + vb[7]) & ~255u) | 232u), ((ord_key(va[2] + vb[0]) & ~255u) | 223u), ((ord_key(va[2] + vb[1]) & ~255u) | 222u), ((ord_key(va[2] + vb[2]) & ~255u) | 221u), ((ord_key(va[2] + vb[3]) & ~255u) | 220u), ((ord_key(va[2] + vb[4]) & ~255u) | 219u), ((ord_key(va[3] + vb[0]) & ~255u) | 207u), ((ord_key(va[3] + vb[1]) & ~255u) | 206u), ((ord_key(va[3] + vb[2]) & ~255u) | 205u)};
;         bitonic_sort16_desc(gq);
;         bitonic_merge16_top(top, gq);
	v_cndmask_b32_e32 v12, v132, v129, vcc
	v_cmp_lt_i32_e32 vcc, -1, v8
	v_bitop3_b32 v30, v12, s43, v9 bitop3:0xde
	v_and_b32_e32 v8, 0xffffff00, v8
	v_cndmask_b32_e32 v9, v132, v129, vcc
	v_bitop3_b32 v31, v9, s44, v8 bitop3:0xde
	v_pk_add_f32 v[8:9], v[46:47], v[10:11] op_sel_hi:[0,1]
	v_cmp_lt_i32_e32 vcc, -1, v9
	v_and_b32_e32 v9, 0xffffff00, v9
	s_nop 0
	v_cndmask_b32_e32 v12, v132, v129, vcc
	v_cmp_lt_i32_e32 vcc, -1, v8
	v_bitop3_b32 v36, v12, s45, v9 bitop3:0xde
	v_and_b32_e32 v8, 0xffffff00, v8
	v_cndmask_b32_e32 v9, v132, v129, vcc
	v_bitop3_b32 v37, v9, s46, v8 bitop3:0xde
	v_pk_add_f32 v[8:9], v[46:47], v[32:33] op_sel_hi:[0,1]
	v_cmp_lt_i32_e32 vcc, -1, v9
	v_and_b32_e32 v9, 0xffffff00, v9
	s_nop 0
	v_cndmask_b32_e32 v12, v132, v129, vcc
	v_cmp_lt_i32_e32 vcc, -1, v8
	v_bitop3_b32 v51, v12, s47, v9 bitop3:0xde
	v_and_b32_e32 v8, 0xffffff00, v8
	v_cndmask_b32_e32 v9, v132, v129, vcc
	v_bitop3_b32 v52, v9, s48, v8 bitop3:0xde
	v_pk_add_f32 v[8:9], v[46:47], v[42:43] op_sel_hi:[0,1]
	v_cmp_lt_i32_e32 vcc, -1, v9
	v_and_b32_e32 v9, 0xffffff00, v9
	s_nop 0
	v_cndmask_b32_e32 v12, v132, v129, vcc
	v_cmp_lt_i32_e32 vcc, -1, v8
	v_bitop3_b32 v42, v12, s49, v9 bitop3:0xde
	v_and_b32_e32 v8, 0xffffff00, v8
	v_cndmask_b32_e32 v9, v132, v129, vcc
	v_bitop3_b32 v43, v9, s50, v8 bitop3:0xde
	v_pk_add_f32 v[8:9], v[46:47], v[44:45] op_sel_hi:[0,1]
	v_cmp_lt_i32_e32 vcc, -1, v9
	v_and_b32_e32 v9, 0xffffff00, v9
	s_nop 0
	v_cndmask_b32_e32 v12, v132, v129, vcc
	v_cmp_lt_i32_e32 vcc, -1, v8
	v_bitop3_b32 v44, v12, s51, v9 bitop3:0xde
	v_and_b32_e32 v8, 0xffffff00, v8
	v_cndmask_b32_e32 v9, v132, v129, vcc
	v_bitop3_b32 v45, v9, s52, v8 bitop3:0xde
	v_pk_add_f32 v[8:9], v[28:29], v[10:11] op_sel_hi:[0,1]
	v_cmp_lt_i32_e32 vcc, -1, v9
	v_and_b32_e32 v9, 0xffffff00, v9
	s_nop 0
	v_cndmask_b32_e32 v12, v132, v129, vcc
	v_cmp_lt_i32_e32 vcc, -1, v8
	v_bitop3_b32 v46, v12, s53, v9 bitop3:0xde
	v_and_b32_e32 v8, 0xffffff00, v8
	v_cndmask_b32_e32 v9, v132, v129, vcc
	v_bitop3_b32 v47, v9, s54, v8 bitop3:0xde
	v_pk_add_f32 v[8:9], v[28:29], v[32:33] op_sel_hi:[0,1]
	v_cmp_lt_i32_e32 vcc, -1, v9
	v_and_b32_e32 v9, 0xffffff00, v9
	s_nop 0
	v_cndmask_b32_e32 v12, v132, v129, vcc
	v_cmp_lt_i32_e32 vcc, -1, v8
	v_bitop3_b32 v32, v12, s55, v9 bitop3:0xde
	v_and_b32_e32 v8, 0xffffff00, v8
	v_cndmask_b32_e32 v9, v132, v129, vcc
	v_bitop3_b32 v33, v9, s56, v8 bitop3:0xde
	v_mov_b32_e32 v8, v26
	v_mov_b32_e32 v9, v28
	v_mov_b32_e32 v28, v17
	v_pk_add_f32 v[8:9], v[8:9], v[28:29]
	s_nop 0
	v_cmp_lt_i32_e32 vcc, -1, v9
	v_and_b32_e32 v9, 0xffffff00, v9
	s_nop 0
	v_cndmask_b32_e32 v12, v132, v129, vcc
	v_cmp_lt_i32_e32 vcc, -1, v8
	v_bitop3_b32 v28, v12, s57, v9 bitop3:0xde
	v_and_b32_e32 v8, 0xffffff00, v8
	v_cndmask_b32_e32 v9, v132, v129, vcc
	v_bitop3_b32 v29, v9, s58, v8 bitop3:0xde
	v_mov_b32_e32 v8, v25
	v_mov_b32_e32 v9, v21
	v_pk_add_f32 v[12:13], v[26:27], v[8:9] op_sel_hi:[0,1]
	v_cmp_lt_i32_e32 vcc, -1, v13
	v_and_b32_e32 v13, 0xffffff00, v13
	v_pk_add_f32 v[8:9], v[24:25], v[8:9] op_sel_hi:[0,1]
	v_cndmask_b32_e32 v53, v132, v129, vcc
	v_cmp_lt_i32_e32 vcc, -1, v12
	v_bitop3_b32 v13, v53, s59, v13 bitop3:0xde
	v_and_b32_e32 v12, 0xffffff00, v12
	v_cndmask_b32_e32 v53, v132, v129, vcc
	v_bitop3_b32 v12, v53, s60, v12 bitop3:0xde
	v_max_u32_e32 v53, v36, v37
	v_min_u32_e32 v36, v36, v37
	v_max_u32_e32 v37, v51, v52
	v_min_u32_e32 v51, v51, v52
	v_max_u32_e32 v52, v42, v43
	v_min_u32_e32 v42, v42, v43
	v_max_u32_e32 v43, v44, v45
	v_min_u32_e32 v44, v44, v45
	v_max_u32_e32 v45, v46, v47
	v_min_u32_e32 v46, v46, v47
	v_max_u32_e32 v47, v32, v33
	v_min_u32_e32 v32, v32, v33
	v_max_u32_e32 v33, v28, v29
	v_min_u32_e32 v28, v28, v29
	v_max_u32_e32 v29, v13, v12
	v_min_u32_e32 v12, v13, v12
	v_max_u32_e32 v13, v53, v51
	v_min_u32_e32 v51, v53, v51
	v_max_u32_e32 v53, v36, v37
	v_min_u32_e32 v36, v36, v37
	v_max_u32_e32 v37, v52, v44
	v_min_u32_e32 v44, v52, v44
	v_max_u32_e32 v52, v42, v43
	v_min_u32_e32 v42, v42, v43
	v_max_u32_e32 v43, v45, v32
	v_min_u32_e32 v32, v45, v32
	v_max_u32_e32 v45, v46, v47
	v_min_u32_e32 v46, v46, v47
	v_max_u32_e32 v47, v33, v12
	v_min_u32_e32 v12, v33, v12
	v_max_u32_e32 v33, v28, v29
	v_min_u32_e32 v28, v28, v29
	v_max_u32_e32 v29, v13, v53
	v_min_u32_e32 v13, v13, v53
	v_max_u32_e32 v53, v51, v36
	v_min_u32_e32 v36, v51, v36
	v_max_u32_e32 v51, v44, v42
	v_min_u32_e32 v42, v44, v42
	v_max_u32_e32 v44, v37, v52
	v_min_u32_e32 v37, v37, v52
	v_max_u32_e32 v52, v43, v45
	v_min_u32_e32 v43, v43, v45
	v_max_u32_e32 v45, v32, v46
	v_min_u32_e32 v32, v32, v46
	v_max_u32_e32 v46, v12, v28
	v_min_u32_e32 v12, v12, v28
	v_max_u32_e32 v28, v47, v33
	v_min_u32_e32 v33, v47, v33
	v_max_u32_e32 v47, v29, v42
	v_min_u32_e32 v29, v29, v42
	v_max_u32_e32 v42, v13, v51
	v_min_u32_e32 v13, v13, v51
	v_max_u32_e32 v51, v53, v37
	v_min_u32_e32 v37, v53, v37
	v_max_u32_e32 v53, v36, v44
	v_min_u32_e32 v36, v36, v44
	v_max_u32_e32 v44, v52, v12
	v_min_u32_e32 v12, v52, v12
	v_max_u32_e32 v52, v43, v46
	v_min_u32_e32 v43, v43, v46
	v_max_u32_e32 v46, v45, v33
	v_min_u32_e32 v33, v45, v33
	v_max_u32_e32 v45, v32, v28
	v_min_u32_e32 v28, v32, v28
	v_max_u32_e32 v32, v47, v51
	v_min_u32_e32 v47, v47, v51
	v_max_u32_e32 v51, v42, v53
	v_min_u32_e32 v42, v42, v53
	v_max_u32_e32 v53, v29, v37
	v_min_u32_e32 v29, v29, v37
	v_max_u32_e32 v37, v13, v36
	v_min_u32_e32 v13, v13, v36
	v_max_u32_e32 v36, v12, v33
	v_min_u32_e32 v12, v12, v33
	v_max_u32_e32 v33, v43, v28
	v_min_u32_e32 v28, v43, v28
	v_max_u32_e32 v43, v44, v46
	v_min_u32_e32 v44, v44, v46
	v_max_u32_e32 v46, v52, v45
	v_min_u32_e32 v45, v52, v45
	v_max_u32_e32 v52, v32, v51
	v_min_u32_e32 v32, v32, v51
; __device__ __forceinline__ unsigned ord_key(float f) { unsigned u = __float_as_uint(f); return u ^ ((u >> 31) ? 0xffffffffu : 0x80000000u); }
; __device__ __forceinline__ void bitonic_merge16_top(unsigned (&a)[16], const unsigned (&b)[16]) {
; #pragma unroll
;     for (int i = 0; i < 16; ++i) a[i] = max(a[i], b[15 - i]);
; #pragma unroll
;     for (int j = 8; j >= 1; j >>= 1)
; #pragma unroll
;         for (int i = 0; i < 16; ++i)
;             if ((i & j) == 0) { const int p = i | j; const unsigned hi = max(a[i], a[p]), lo = min(a[i], a[p]); a[i] = hi; a[p] = lo; }
; }
; __device__ __forceinline__ void peer_stage2_batch(const Params& P, int tbase, int tstride, int lane, unsigned char* res, unsigned char* scr) {
;     ...
;         unsigned gq[16] = {((ord_key(va[1] + vb[0]) & ~255u) | 239u), ((ord_key(va[1] + vb[1]) & ~255u) | 238u), ((ord_key(va[1] + vb[2]) & ~255u) | 237u), ((ord_key(va[1] + vb[3]) & ~255u) | 236u), ((ord_key(va[1] + vb[4]) & ~255u) | 235u), ((ord_key(va[1] + vb[5]) & ~255u) | 234u), ((ord_key(va[1] + vb[6]) & ~255u) | 233u), ((ord_key(va[1] + vb[7]) & ~255u) | 232u), ((ord_key(va[2] + vb[0]) & ~255u) | 223u), ((ord_key(va[2] + vb[1]) & ~255u) | 222u), ((ord_key(va[2] + vb[2]) & ~255u) | 221u), ((ord_key(va[2] + vb[3]) & ~255u) | 220u), ((ord_key(va[2] + vb[4]) & ~255u) | 219u), ((ord_key(va[3] + vb[0]) & ~255u) | 207u), ((ord_key(va[3] + vb[1]) & ~255u) | 206u), ((ord_key(va[3] + vb[2]) & ~255u) | 205u)};
;         bitonic_sort16_desc(gq);
;         bitonic_merge16_top(top, gq);
;     }
;     {
;         unsigned gq[16] = {((ord_key(va[3] + vb[3]) & ~255u) | 204u), ((ord_key(va[4] + vb[0]) & ~255u) | 191u), ((ord_key(va[4] + vb[1]) & ~255u) | 190u), ((ord_key(va[4] + vb[2]) & ~255u) | 189u), ((ord_key(va[5] + vb[0]) & ~255u) | 175u), ((ord_key(va[5] + vb[1]) & ~255u) | 174u), ((ord_key(va[6] + vb[0]) & ~255u) | 159u), ((ord_key(va[6] + vb[1]) & ~255u) | 158u), ((ord_key(va[7] + vb[0]) & ~255u) | 143u), ((ord_key(va[7] + vb[1]) & ~255u) | 142u), ((ord_key(va[8] + vb[0]) & ~255u) | 127u), ((ord_key(va[9] + vb[0]) & ~255u) | 111u), ((ord_key(va[10] + vb[0]) & ~255u) | 95u), ((ord_key(va[11] + vb[0]) & ~255u) | 79u), ((ord_key(va[12] + vb[0]) & ~255u) | 63u), ((ord_key(va[13] + vb[0]) & ~255u) | 47u)};
;         bitonic_sort16_desc(gq);
;         bitonic_merge16_top(top, gq);
	v_max_u32_e32 v51, v47, v42
	v_min_u32_e32 v42, v47, v42
	v_max_u32_e32 v47, v53, v37
	v_min_u32_e32 v37, v53, v37
	v_max_u32_e32 v53, v29, v13
	v_min_u32_e32 v13, v29, v13
	v_max_u32_e32 v29, v12, v28
	v_min_u32_e32 v12, v12, v28
	v_max_u32_e32 v28, v36, v33
	v_min_u32_e32 v33, v36, v33
	v_max_u32_e32 v36, v44, v45
	v_min_u32_e32 v44, v44, v45
	v_max_u32_e32 v45, v43, v46
	v_min_u32_e32 v43, v43, v46
	v_max_u32_e32 v46, v52, v12
	v_min_u32_e32 v12, v52, v12
	v_max_u32_e32 v52, v32, v29
	v_min_u32_e32 v29, v32, v29
	v_max_u32_e32 v32, v51, v33
	v_min_u32_e32 v33, v51, v33
	v_max_u32_e32 v51, v42, v28
	v_min_u32_e32 v28, v42, v28
	v_max_u32_e32 v42, v47, v44
	v_min_u32_e32 v44, v47, v44
	v_max_u32_e32 v47, v37, v36
	v_min_u32_e32 v36, v37, v36
	v_max_u32_e32 v37, v53, v43
	v_min_u32_e32 v43, v53, v43
	v_max_u32_e32 v53, v13, v45
	v_min_u32_e32 v13, v13, v45
	v_max_u32_e32 v45, v46, v42
	v_min_u32_e32 v42, v46, v42
	v_max_u32_e32 v46, v52, v47
	v_min_u32_e32 v47, v52, v47
	v_max_u32_e32 v52, v32, v37
	v_min_u32_e32 v32, v32, v37
	v_max_u32_e32 v37, v51, v53
	v_min_u32_e32 v51, v51, v53
	v_max_u32_e32 v53, v12, v44
	v_min_u32_e32 v12, v12, v44
	v_max_u32_e32 v44, v29, v36
	v_min_u32_e32 v29, v29, v36
	v_max_u32_e32 v36, v33, v43
	v_min_u32_e32 v33, v33, v43
	v_max_u32_e32 v43, v28, v13
	v_min_u32_e32 v13, v28, v13
	v_max_u32_e32 v28, v45, v52
	v_min_u32_e32 v45, v45, v52
	v_max_u32_e32 v52, v46, v37
	v_min_u32_e32 v37, v46, v37
	v_max_u32_e32 v46, v42, v32
	v_min_u32_e32 v32, v42, v32
	v_max_u32_e32 v42, v47, v51
	v_min_u32_e32 v47, v47, v51
	v_max_u32_e32 v51, v53, v36
	v_min_u32_e32 v36, v53, v36
	v_max_u32_e32 v53, v44, v43
	v_min_u32_e32 v43, v44, v43
	v_max_u32_e32 v44, v12, v33
	v_min_u32_e32 v12, v12, v33
	v_max_u32_e32 v33, v29, v13
	v_min_u32_e32 v13, v29, v13
	v_min_u32_e32 v29, v28, v52
	v_min_u32_e32 v54, v45, v37
	v_min_u32_e32 v55, v46, v42
	v_min_u32_e32 v56, v32, v47
	v_min_u32_e32 v57, v51, v53
	v_min_u32_e32 v58, v36, v43
	v_min_u32_e32 v59, v44, v33
	v_min_u32_e32 v60, v12, v13
	v_max_u32_e32 v3, v3, v60
	v_max3_u32 v12, v19, v12, v13
	v_max_u32_e32 v13, v23, v59
	v_max3_u32 v19, v38, v44, v33
	v_max_u32_e32 v23, v39, v58
	v_max3_u32 v33, v40, v36, v43
	v_max_u32_e32 v35, v35, v57
	v_max3_u32 v34, v34, v51, v53
	v_max_u32_e32 v36, v41, v56
	v_max3_u32 v32, v48, v32, v47
	v_max_u32_e32 v14, v14, v55
	v_max3_u32 v15, v15, v46, v42
	v_max_u32_e32 v38, v49, v54
	v_max3_u32 v37, v50, v45, v37
	v_max_u32_e32 v29, v30, v29
	v_max3_u32 v28, v31, v28, v52
	v_max_u32_e32 v30, v3, v36
	v_min_u32_e32 v3, v3, v36
	v_max_u32_e32 v31, v12, v32
	v_min_u32_e32 v12, v12, v32
	v_max_u32_e32 v32, v13, v14
	v_min_u32_e32 v13, v13, v14
	v_max_u32_e32 v14, v19, v15
	v_min_u32_e32 v15, v19, v15
	v_max_u32_e32 v19, v23, v38
	v_min_u32_e32 v23, v23, v38
	v_max_u32_e32 v36, v33, v37
	v_min_u32_e32 v33, v33, v37
	v_max_u32_e32 v37, v35, v29
	v_min_u32_e32 v29, v35, v29
	v_max_u32_e32 v35, v34, v28
	v_min_u32_e32 v28, v34, v28
	v_max_u32_e32 v34, v30, v19
	v_min_u32_e32 v19, v30, v19
	v_max_u32_e32 v30, v31, v36
	v_min_u32_e32 v31, v31, v36
	v_max_u32_e32 v36, v32, v37
	v_min_u32_e32 v32, v32, v37
	v_max_u32_e32 v37, v14, v35
	v_min_u32_e32 v14, v14, v35
	v_max_u32_e32 v35, v3, v23
	v_min_u32_e32 v3, v3, v23
	v_max_u32_e32 v23, v12, v33
	v_min_u32_e32 v12, v12, v33
	v_max_u32_e32 v33, v13, v29
	v_min_u32_e32 v13, v13, v29
	v_max_u32_e32 v29, v15, v28
	v_min_u32_e32 v15, v15, v28
	v_max_u32_e32 v28, v34, v36
	v_min_u32_e32 v34, v34, v36
	v_max_u32_e32 v36, v30, v37
	v_min_u32_e32 v30, v30, v37
	v_max_u32_e32 v37, v19, v32
	v_min_u32_e32 v19, v19, v32
	v_max_u32_e32 v32, v31, v14
	v_min_u32_e32 v14, v31, v14
	v_max_u32_e32 v31, v35, v33
	v_min_u32_e32 v33, v35, v33
	v_max_u32_e32 v35, v23, v29
	v_min_u32_e32 v23, v23, v29
	v_max_u32_e32 v29, v3, v13
	v_min_u32_e32 v3, v3, v13
	v_max_u32_e32 v38, v12, v15
	v_min_u32_e32 v15, v12, v15
	v_mov_b32_e32 v12, v24
	v_mov_b32_e32 v13, v26
	v_mov_b32_e32 v26, v17
	v_pk_add_f32 v[12:13], v[12:13], v[26:27]
	v_min_u32_e32 v39, v28, v36
	v_cmp_lt_i32_e32 vcc, -1, v13
	v_and_b32_e32 v13, 0xffffff00, v13
	v_min_u32_e32 v40, v34, v30
	v_cndmask_b32_e32 v26, v132, v129, vcc
	v_cmp_lt_i32_e32 vcc, -1, v12
	v_bitop3_b32 v13, v26, s61, v13 bitop3:0xde
	v_and_b32_e32 v12, 0xffffff00, v12
	v_cndmask_b32_e32 v26, v132, v129, vcc
	v_cmp_lt_i32_e32 vcc, -1, v9
	v_and_b32_e32 v9, 0xffffff00, v9
	v_bitop3_b32 v12, v26, s62, v12 bitop3:0xde
	v_cndmask_b32_e32 v24, v132, v129, vcc
	v_cmp_lt_i32_e32 vcc, -1, v8
	v_bitop3_b32 v24, v24, s63, v9 bitop3:0xde
	v_and_b32_e32 v8, 0xffffff00, v8
	v_cndmask_b32_e32 v9, v132, v129, vcc
	v_bitop3_b32 v25, v9, s64, v8 bitop3:0xde
	v_pk_add_f32 v[8:9], v[22:23], v[10:11] op_sel_hi:[0,1]
	v_cmp_lt_i32_e32 vcc, -1, v9
	v_and_b32_e32 v9, 0xffffff00, v9
	v_min_u32_e32 v41, v37, v32
	v_cndmask_b32_e32 v22, v132, v129, vcc
	v_cmp_lt_i32_e32 vcc, -1, v8
	v_bitop3_b32 v22, v22, s65, v9 bitop3:0xde
	v_and_b32_e32 v8, 0xffffff00, v8
	v_cndmask_b32_e32 v9, v132, v129, vcc
	v_bitop3_b32 v26, v9, s66, v8 bitop3:0xde
	v_pk_add_f32 v[8:9], v[18:19], v[10:11] op_sel_hi:[0,1]
	v_cmp_lt_i32_e32 vcc, -1, v9
	v_and_b32_e32 v9, 0xffffff00, v9
	v_min_u32_e32 v42, v19, v14
	v_cndmask_b32_e32 v18, v132, v129, vcc
	v_cmp_lt_i32_e32 vcc, -1, v8
	v_bitop3_b32 v18, v18, s67, v9 bitop3:0xde
	v_and_b32_e32 v8, 0xffffff00, v8
	v_cndmask_b32_e32 v9, v132, v129, vcc
	v_bitop3_b32 v27, v9, s68, v8 bitop3:0xde
	v_pk_add_f32 v[8:9], v[20:21], v[10:11] op_sel_hi:[0,1]
	v_cmp_lt_i32_e32 vcc, -1, v9
	v_and_b32_e32 v9, 0xffffff00, v9
	v_and_b32_e32 v11, 0xffffff80, v4
	v_cndmask_b32_e32 v10, v132, v129, vcc
	v_cmp_lt_i32_e32 vcc, -1, v8
; __device__ __forceinline__ unsigned ord_key(float f) { unsigned u = __float_as_uint(f); return u ^ ((u >> 31) ? 0xffffffffu : 0x80000000u); }
; __device__ __forceinline__ void bitonic_sort16_desc(unsigned (&v)[16]) {
; #pragma unroll
;     for (int k = 2; k <= 16; k <<= 1)
; #pragma unroll
;         for (int j = k >> 1; j >= 1; j >>= 1)
; #pragma unroll
;             for (int i = 0; i < 16; ++i)
;                 if ((i & j) == 0) {
;                     const int p = i | j;
;                     const bool desc = (k >= 16) ? true : ((i & k) == 0);
;                     const unsigned hi = max(v[i], v[p]), lo = min(v[i], v[p]);
;                     v[i] = desc ? hi : lo; v[p] = desc ? lo : hi;
;                 }
; }
; __device__ __forceinline__ void peer_stage2_batch(const Params& P, int tbase, int tstride, int lane, unsigned char* res, unsigned char* scr) {
;     ...
;         unsigned gq[16] = {((ord_key(va[3] + vb[3]) & ~255u) | 204u), ((ord_key(va[4] + vb[0]) & ~255u) | 191u), ((ord_key(va[4] + vb[1]) & ~255u) | 190u), ((ord_key(va[4] + vb[2]) & ~255u) | 189u), ((ord_key(va[5] + vb[0]) & ~255u) | 175u), ((ord_key(va[5] + vb[1]) & ~255u) | 174u), ((ord_key(va[6] + vb[0]) & ~255u) | 159u), ((ord_key(va[6] + vb[1]) & ~255u) | 158u), ((ord_key(va[7] + vb[0]) & ~255u) | 143u), ((ord_key(va[7] + vb[1]) & ~255u) | 142u), ((ord_key(va[8] + vb[0]) & ~255u) | 127u), ((ord_key(va[9] + vb[0]) & ~255u) | 111u), ((ord_key(va[10] + vb[0]) & ~255u) | 95u), ((ord_key(va[11] + vb[0]) & ~255u) | 79u), ((ord_key(va[12] + vb[0]) & ~255u) | 63u), ((ord_key(va[13] + vb[0]) & ~255u) | 47u)};
;         bitonic_sort16_desc(gq);
	v_bitop3_b32 v9, v10, s69, v9 bitop3:0xde
	v_and_b32_e32 v8, 0xffffff00, v8
	v_cndmask_b32_e32 v10, v132, v129, vcc
	v_cmp_lt_i32_e32 vcc, -1, v5
	v_bitop3_b32 v8, v10, s70, v8 bitop3:0xde
	v_and_b32_e32 v10, 0xffffff80, v5
	v_cndmask_b32_e64 v5, v129, -1, vcc
	v_cmp_lt_i32_e32 vcc, -1, v4
	v_xor_b32_e32 v5, v5, v10
	v_and_b32_e32 v20, 0xffffff80, v6
	v_cndmask_b32_e64 v4, v129, -1, vcc
	v_xor_b32_e32 v4, v4, v11
	v_pk_add_f32 v[4:5], v[16:17], v[4:5] op_sel:[1,0]
	v_min_u32_e32 v21, v22, v26
	v_cmp_lt_i32_e32 vcc, -1, v4
	v_and_b32_e32 v4, 0xffffff00, v4
	v_min_u32_e32 v43, v31, v35
	v_cndmask_b32_e32 v10, v132, v129, vcc
	v_cmp_lt_i32_e32 vcc, -1, v5
	v_bitop3_b32 v10, v10, s24, v4 bitop3:0xde
	v_and_b32_e32 v5, 0xffffff00, v5
	v_cndmask_b32_e32 v4, v132, v129, vcc
	v_cmp_lt_i32_e32 vcc, -1, v7
	v_bitop3_b32 v11, v4, s71, v5 bitop3:0xde
	v_and_b32_e32 v4, 0xffffff80, v7
	v_cndmask_b32_e64 v5, v129, -1, vcc
	v_cmp_lt_i32_e32 vcc, -1, v6
	v_xor_b32_e32 v5, v5, v4
	v_and_b32_e32 v7, 0xffffff80, v0
	v_cndmask_b32_e64 v6, v129, -1, vcc
	v_xor_b32_e32 v4, v6, v20
	v_pk_add_f32 v[4:5], v[16:17], v[4:5] op_sel:[1,0]
	v_max_u32_e32 v20, v22, v26
	v_cmp_lt_i32_e32 vcc, -1, v4
	v_and_b32_e32 v4, 0xffffff00, v4
	v_max_u32_e32 v22, v18, v27
	v_cndmask_b32_e32 v6, v132, v129, vcc
	v_cmp_lt_i32_e32 vcc, -1, v5
	v_bitop3_b32 v4, v6, s72, v4 bitop3:0xde
	v_and_b32_e32 v5, 0xffffff00, v5
	v_cndmask_b32_e32 v6, v132, v129, vcc
	v_cmp_lt_i32_e32 vcc, -1, v1
	v_bitop3_b32 v5, v6, s73, v5 bitop3:0xde
	v_and_b32_e32 v6, 0xffffff80, v1
	v_cndmask_b32_e64 v1, v129, -1, vcc
	v_cmp_lt_i32_e32 vcc, -1, v0
	v_xor_b32_e32 v1, v1, v6
	v_min_u32_e32 v18, v18, v27
	v_cndmask_b32_e64 v0, v129, -1, vcc
	v_xor_b32_e32 v0, v0, v7
	v_pk_add_f32 v[0:1], v[16:17], v[0:1] op_sel:[1,0]
	v_min_u32_e32 v7, v13, v12
	v_cmp_lt_i32_e32 vcc, -1, v0
	v_and_b32_e32 v0, 0xffffff00, v0
	v_min_u32_e32 v44, v33, v23
	v_cndmask_b32_e32 v6, v132, v129, vcc
	v_cmp_lt_i32_e32 vcc, -1, v1
	v_bitop3_b32 v0, v6, 63, v0 bitop3:0xde
	v_and_b32_e32 v1, 0xffffff00, v1
	v_cndmask_b32_e32 v6, v132, v129, vcc
	v_bitop3_b32 v1, v6, 47, v1 bitop3:0xde
	v_max_u32_e32 v6, v13, v12
	v_max_u32_e32 v12, v24, v25
	v_min_u32_e32 v13, v24, v25
	v_max_u32_e32 v24, v9, v8
	v_min_u32_e32 v8, v9, v8
	v_max_u32_e32 v9, v10, v11
	v_min_u32_e32 v10, v10, v11
	v_max_u32_e32 v11, v4, v5
	v_min_u32_e32 v4, v4, v5
	v_max_u32_e32 v5, v0, v1
	v_min_u32_e32 v0, v0, v1
	v_max_u32_e32 v1, v6, v13
	v_min_u32_e32 v6, v6, v13
	v_max_u32_e32 v13, v7, v12
	v_min_u32_e32 v7, v7, v12
	v_max_u32_e32 v12, v20, v18
	v_min_u32_e32 v18, v20, v18
	v_max_u32_e32 v20, v21, v22
	v_min_u32_e32 v21, v21, v22
	v_max_u32_e32 v22, v24, v10
	v_min_u32_e32 v10, v24, v10
	v_max_u32_e32 v24, v8, v9
	v_min_u32_e32 v8, v8, v9
	v_max_u32_e32 v9, v11, v0
	v_min_u32_e32 v0, v11, v0
	v_max_u32_e32 v11, v4, v5
	v_min_u32_e32 v4, v4, v5
	v_max_u32_e32 v5, v1, v13
	v_min_u32_e32 v1, v1, v13
	v_max_u32_e32 v13, v6, v7
	v_min_u32_e32 v6, v6, v7
	v_max_u32_e32 v7, v18, v21
	v_min_u32_e32 v18, v18, v21
	v_max_u32_e32 v21, v12, v20
	v_min_u32_e32 v12, v12, v20
	v_max_u32_e32 v20, v22, v24
	v_min_u32_e32 v22, v22, v24
	v_max_u32_e32 v24, v10, v8
	v_min_u32_e32 v8, v10, v8
	v_max_u32_e32 v10, v0, v4
	v_min_u32_e32 v0, v0, v4
	v_max_u32_e32 v4, v9, v11
	v_min_u32_e32 v9, v9, v11
	v_max_u32_e32 v11, v5, v18
	v_min_u32_e32 v5, v5, v18
	v_max_u32_e32 v18, v1, v7
	v_min_u32_e32 v1, v1, v7
	v_max_u32_e32 v7, v13, v12
	v_min_u32_e32 v12, v13, v12
	v_max_u32_e32 v13, v6, v21
	v_min_u32_e32 v6, v6, v21
	v_max_u32_e32 v21, v20, v0
	v_min_u32_e32 v0, v20, v0
	v_max_u32_e32 v20, v22, v10
	v_min_u32_e32 v10, v22, v10
	v_max_u32_e32 v22, v24, v9
	v_min_u32_e32 v9, v24, v9
	v_max_u32_e32 v24, v8, v4
	v_min_u32_e32 v4, v8, v4
	v_max_u32_e32 v8, v11, v7
	v_min_u32_e32 v7, v11, v7
	v_max_u32_e32 v11, v18, v13
	v_min_u32_e32 v13, v18, v13
	v_max_u32_e32 v18, v5, v12
	v_min_u32_e32 v5, v5, v12
	v_max_u32_e32 v12, v1, v6
	v_min_u32_e32 v1, v1, v6
	v_max_u32_e32 v6, v0, v9
	v_min_u32_e32 v0, v0, v9
	v_max_u32_e32 v9, v10, v4
	v_min_u32_e32 v4, v10, v4
	v_max_u32_e32 v10, v21, v22
	v_min_u32_e32 v21, v21, v22
	v_max_u32_e32 v22, v20, v24
	v_min_u32_e32 v20, v20, v24
	v_max_u32_e32 v24, v8, v11
	v_min_u32_e32 v8, v8, v11
	v_max_u32_e32 v11, v7, v13
	v_min_u32_e32 v7, v7, v13
	v_max_u32_e32 v13, v18, v12
	v_min_u32_e32 v12, v18, v12
	v_max_u32_e32 v18, v5, v1
	v_min_u32_e32 v1, v5, v1
	v_max_u32_e32 v5, v0, v4
	v_min_u32_e32 v0, v0, v4
	v_max_u32_e32 v4, v6, v9
	v_min_u32_e32 v6, v6, v9
	v_max_u32_e32 v9, v21, v20
	v_min_u32_e32 v20, v21, v20
	v_max_u32_e32 v21, v10, v22
	v_min_u32_e32 v10, v10, v22
	v_max_u32_e32 v22, v24, v0
	v_min_u32_e32 v0, v24, v0
	v_max_u32_e32 v24, v8, v5
	v_min_u32_e32 v5, v8, v5
	v_max_u32_e32 v8, v11, v6
	v_min_u32_e32 v6, v11, v6
	v_max_u32_e32 v11, v7, v4
	v_min_u32_e32 v4, v7, v4
	v_max_u32_e32 v7, v13, v20
	v_min_u32_e32 v13, v13, v20
	v_max_u32_e32 v20, v12, v9
	v_min_u32_e32 v9, v12, v9
	v_max_u32_e32 v12, v18, v10
	v_min_u32_e32 v10, v18, v10
	v_max_u32_e32 v18, v1, v21
	v_min_u32_e32 v1, v1, v21
	v_max_u32_e32 v21, v22, v7
	v_min_u32_e32 v7, v22, v7
	v_max_u32_e32 v22, v24, v20
	v_min_u32_e32 v20, v24, v20
	v_max_u32_e32 v24, v8, v12
	v_min_u32_e32 v8, v8, v12
	v_max_u32_e32 v12, v11, v18
	v_min_u32_e32 v11, v11, v18
	v_max_u32_e32 v18, v0, v13
	v_min_u32_e32 v0, v0, v13
	v_max_u32_e32 v13, v5, v9
	v_min_u32_e32 v5, v5, v9
	v_max_u32_e32 v9, v6, v10
	v_min_u32_e32 v6, v6, v10
	v_max_u32_e32 v10, v4, v1
	v_min_u32_e32 v1, v4, v1
	v_max_u32_e32 v4, v21, v24
	v_min_u32_e32 v21, v21, v24
	v_max_u32_e32 v24, v22, v12
	v_min_u32_e32 v12, v22, v12
; __device__ __forceinline__ unsigned ord_key(float f) { unsigned u = __float_as_uint(f); return u ^ ((u >> 31) ? 0xffffffffu : 0x80000000u); }
; __device__ __forceinline__ float unord_key(unsigned k) { unsigned u = (k & 0x80000000u) ? (k ^ 0x80000000u) : ~k; return __uint_as_float(u); }
; __device__ __forceinline__ void bitonic_merge16_top(unsigned (&a)[16], const unsigned (&b)[16]) {
; #pragma unroll
;     for (int i = 0; i < 16; ++i) a[i] = max(a[i], b[15 - i]);
; #pragma unroll
;     for (int j = 8; j >= 1; j >>= 1)
; #pragma unroll
;         for (int i = 0; i < 16; ++i)
;             if ((i & j) == 0) { const int p = i | j; const unsigned hi = max(a[i], a[p]), lo = min(a[i], a[p]); a[i] = hi; a[p] = lo; }
; }
; __device__ __forceinline__ void peer_stage2_batch(const Params& P, int tbase, int tstride, int lane, unsigned char* res, unsigned char* scr) {
;     ...
;         bitonic_merge16_top(top, gq);
;     }
;     {
;         const unsigned x48 = ((ord_key(va[14] + vb[0]) & ~255u) | 31u), x49 = ((ord_key(va[15] + vb[0]) & ~255u) | 15u);
;         unsigned gq[16] = {max(x48, x49), min(x48, x49), 0u, 0u, 0u, 0u, 0u, 0u, 0u, 0u, 0u, 0u, 0u, 0u, 0u, 0u};
;         bitonic_merge16_top(top, gq);
;     }
;     const float smax = unord_key(top[0] & ~255u);
	v_max_u32_e32 v22, v7, v8
	v_min_u32_e32 v7, v7, v8
	v_max_u32_e32 v8, v20, v11
	v_min_u32_e32 v11, v20, v11
	v_max_u32_e32 v20, v18, v9
	v_min_u32_e32 v9, v18, v9
	v_max_u32_e32 v18, v13, v10
	v_min_u32_e32 v10, v13, v10
	v_max_u32_e32 v13, v0, v6
	v_min_u32_e32 v0, v0, v6
	v_max_u32_e32 v6, v5, v1
	v_min_u32_e32 v1, v5, v1
	v_min_u32_e32 v45, v29, v38
	v_min_u32_e32 v46, v3, v15
	v_min_u32_e32 v5, v4, v24
	v_min_u32_e32 v25, v21, v12
	v_min_u32_e32 v26, v22, v8
	v_min_u32_e32 v27, v7, v11
	v_min_u32_e32 v47, v20, v18
	v_min_u32_e32 v48, v9, v10
	v_min_u32_e32 v49, v13, v6
	v_min_u32_e32 v50, v0, v1
	v_max3_u32 v28, v28, v36, v50
	v_max3_u32 v0, v39, v0, v1
	v_max3_u32 v1, v34, v30, v49
	v_max3_u32 v6, v40, v13, v6
	v_max3_u32 v13, v37, v32, v48
	v_max3_u32 v9, v41, v9, v10
	v_max3_u32 v10, v19, v14, v47
	v_max3_u32 v14, v42, v20, v18
	v_max3_u32 v18, v31, v35, v27
	v_max3_u32 v7, v43, v7, v11
	v_max3_u32 v11, v33, v23, v26
	v_max3_u32 v8, v44, v22, v8
	v_max3_u32 v19, v29, v38, v25
	v_max3_u32 v12, v45, v21, v12
	v_max3_u32 v3, v3, v15, v5
	v_max3_u32 v4, v46, v4, v24
	v_max_u32_e32 v5, v28, v18
	v_min_u32_e32 v15, v28, v18
	v_max_u32_e32 v18, v0, v7
	v_min_u32_e32 v0, v0, v7
	v_max_u32_e32 v7, v1, v11
	v_min_u32_e32 v1, v1, v11
	v_max_u32_e32 v11, v6, v8
	v_min_u32_e32 v6, v6, v8
	v_max_u32_e32 v8, v13, v19
	v_min_u32_e32 v13, v13, v19
	v_max_u32_e32 v19, v9, v12
	v_min_u32_e32 v9, v9, v12
	v_max_u32_e32 v12, v10, v3
	v_min_u32_e32 v3, v10, v3
	v_max_u32_e32 v10, v14, v4
	v_min_u32_e32 v4, v14, v4
	v_max_u32_e32 v14, v5, v8
	v_min_u32_e32 v5, v5, v8
	v_max_u32_e32 v8, v18, v19
	v_min_u32_e32 v18, v18, v19
	v_max_u32_e32 v19, v7, v12
	v_min_u32_e32 v7, v7, v12
	v_max_u32_e32 v12, v11, v10
	v_min_u32_e32 v10, v11, v10
	v_max_u32_e32 v11, v15, v13
	v_min_u32_e32 v13, v15, v13
	v_max_u32_e32 v15, v0, v9
	v_min_u32_e32 v0, v0, v9
	v_max_u32_e32 v9, v1, v3
	v_min_u32_e32 v1, v1, v3
	v_max_u32_e32 v3, v6, v4
	v_min_u32_e32 v4, v6, v4
	v_max_u32_e32 v6, v14, v19
	v_min_u32_e32 v14, v14, v19
	v_max_u32_e32 v19, v8, v12
	v_min_u32_e32 v8, v8, v12
	v_max_u32_e32 v12, v5, v7
	v_min_u32_e32 v5, v5, v7
	v_max_u32_e32 v7, v18, v10
	v_min_u32_e32 v10, v18, v10
	v_max_u32_e32 v18, v11, v9
	v_min_u32_e32 v9, v11, v9
	v_max_u32_e32 v11, v15, v3
	v_min_u32_e32 v3, v15, v3
	v_max_u32_e32 v15, v13, v1
	v_min_u32_e32 v13, v13, v1
	v_max_u32_e32 v1, v0, v4
	v_max_u32_e32 v20, v6, v19
	v_min_u32_e32 v6, v6, v19
	v_max_u32_e32 v19, v14, v8
	v_min_u32_e32 v8, v14, v8
	v_max_u32_e32 v14, v12, v7
	v_min_u32_e32 v7, v12, v7
	v_max_u32_e32 v12, v5, v10
	v_min_u32_e32 v5, v5, v10
	v_max_u32_e32 v10, v18, v11
	v_min_u32_e32 v11, v18, v11
	v_max_u32_e32 v18, v9, v3
	v_min_u32_e32 v9, v9, v3
	v_mov_b32_e32 v3, v16
	v_min_u32_e32 v4, v0, v4
	v_max_u32_e32 v21, v15, v1
	v_min_u32_e32 v15, v15, v1
	v_pk_add_f32 v[0:1], v[2:3], v[16:17] op_sel:[0,1]
	v_min_u32_e32 v22, v13, v4
	v_cmp_lt_i32_e32 vcc, -1, v1
	v_and_b32_e32 v1, 0xffffff00, v1
	v_min_u32_e32 v3, v20, v10
	v_cndmask_b32_e32 v2, v132, v129, vcc
	v_cmp_lt_i32_e32 vcc, -1, v0
	v_bitop3_b32 v1, v2, 31, v1 bitop3:0xde
	v_and_b32_e32 v0, 0xffffff00, v0
	v_cndmask_b32_e32 v2, v132, v129, vcc
	v_bitop3_b32 v0, v2, 15, v0 bitop3:0xde
	v_min_u32_e32 v2, v1, v0
	v_max3_u32 v2, v13, v4, v2
	v_max3_u32 v0, v22, v1, v0
	v_max_u32_e32 v1, v20, v10
	v_max_u32_e32 v4, v6, v11
	v_max_u32_e32 v10, v19, v18
	v_max_u32_e32 v13, v8, v9
	v_min_u32_e32 v8, v8, v9
	v_max_u32_e32 v9, v14, v21
	v_max_u32_e32 v16, v7, v15
	v_min_u32_e32 v7, v7, v15
	v_max_u32_e32 v15, v12, v2
	v_min_u32_e32 v2, v12, v2
	v_max_u32_e32 v12, v5, v0
	v_min_u32_e32 v6, v6, v11
	v_min_u32_e32 v11, v19, v18
	v_min_u32_e32 v14, v14, v21
	v_min_u32_e32 v0, v5, v0
	v_max_u32_e32 v5, v1, v9
	v_min_u32_e32 v1, v1, v9
	v_max_u32_e32 v9, v4, v16
	v_min_u32_e32 v4, v4, v16
	v_max_u32_e32 v16, v10, v15
	v_min_u32_e32 v10, v10, v15
	v_max_u32_e32 v15, v13, v12
	v_min_u32_e32 v12, v13, v12
	v_max_u32_e32 v13, v3, v14
	v_min_u32_e32 v3, v3, v14
	v_max_u32_e32 v14, v6, v7
	v_min_u32_e32 v6, v6, v7
	v_max_u32_e32 v7, v11, v2
	v_min_u32_e32 v2, v11, v2
	v_max_u32_e32 v11, v8, v0
	v_min_u32_e32 v0, v8, v0
	v_max_u32_e32 v8, v5, v16
	v_min_u32_e32 v5, v5, v16
	v_max_u32_e32 v16, v9, v15
	v_min_u32_e32 v9, v9, v15
	v_max_u32_e32 v15, v1, v10
	v_min_u32_e32 v1, v1, v10
	v_max_u32_e32 v10, v4, v12
	v_min_u32_e32 v4, v4, v12
	v_max_u32_e32 v12, v13, v7
	v_min_u32_e32 v7, v13, v7
	v_max_u32_e32 v13, v14, v11
	v_min_u32_e32 v11, v14, v11
	v_max_u32_e32 v14, v3, v2
	v_min_u32_e32 v2, v3, v2
	v_max_u32_e32 v3, v6, v0
	v_min_u32_e32 v0, v6, v0
	v_max_u32_e32 v6, v8, v16
	v_min_u32_e32 v8, v8, v16
	v_max_u32_e32 v34, v5, v9
	v_cmp_lt_i32_e32 vcc, -1, v8
	v_min_u32_e32 v5, v5, v9
	v_max_u32_e32 v48, v2, v0
	v_min_u32_e32 v50, v2, v0
	v_cndmask_b32_e64 v0, v129, -1, vcc
	v_cmp_lt_i32_e32 vcc, -1, v34
	v_max_u32_e32 v36, v15, v10
	v_max_u32_e32 v38, v1, v4
	v_min_u32_e32 v4, v1, v4
	v_cndmask_b32_e64 v1, v129, -1, vcc
	v_cmp_lt_i32_e32 vcc, -1, v5
	v_min_u32_e32 v10, v15, v10
	v_max_u32_e32 v45, v14, v3
	v_cndmask_b32_e64 v2, v129, -1, vcc
	v_cmp_lt_i32_e32 vcc, -1, v36
	v_min_u32_e32 v14, v14, v3
	v_max_u32_e32 v41, v12, v13
	v_cndmask_b32_e64 v3, v129, -1, vcc
	v_cmp_lt_i32_e32 vcc, -1, v10
	v_min_u32_e32 v12, v12, v13
	v_max_u32_e32 v43, v7, v11
	v_cndmask_b32_e64 v16, v129, -1, vcc
	v_cmp_lt_i32_e32 vcc, -1, v38
	v_bitop3_b32 v21, v16, v10, s25 bitop3:0x78
	v_min_u32_e32 v7, v7, v11
	v_cndmask_b32_e64 v16, v129, -1, vcc
	v_cmp_lt_i32_e32 vcc, -1, v4
	v_bitop3_b32 v22, v16, v38, s25 bitop3:0x78
	v_bitop3_b32 v0, v0, v8, s25 bitop3:0x78
	v_cndmask_b32_e64 v16, v129, -1, vcc
; __device__ __forceinline__ float unord_key(unsigned k) { unsigned u = (k & 0x80000000u) ? (k ^ 0x80000000u) : ~k; return __uint_as_float(u); }
; __device__ __forceinline__ void peer_stage2_batch(const Params& P, int tbase, int tstride, int lane, unsigned char* res, unsigned char* scr) {
;     ...
;     const float smax = unord_key(top[0] & ~255u);
;     float e[16]; float den = 0.f;
; #pragma unroll
;     for (int r = 0; r < 16; ++r) { e[r] = __expf(unord_key(top[r] & ~255u) - smax); den += e[r]; }
;     const float inv = 1.f / den;
;     __builtin_amdgcn_s_waitcnt(0xc07f);
;     __builtin_amdgcn_wave_barrier();
;     int ids[16];
; #pragma unroll
;     for (int r = 0; r < 16; ++r) {
;         const int pos = 255 - (int)(top[r] & 255u), i = pos >> 4, j = pos & 15;
;         ids[r] = (int)scr[lane * 32 + i] * 128 + (int)scr[lane * 32 + 16 + j];
	v_cmp_lt_i32_e32 vcc, -1, v41
	v_bitop3_b32 v23, v16, v4, s25 bitop3:0x78
	v_bitop3_b32 v1, v1, v34, s25 bitop3:0x78
	v_cndmask_b32_e64 v16, v129, -1, vcc
	v_cmp_lt_i32_e32 vcc, -1, v12
	v_bitop3_b32 v24, v16, v41, s25 bitop3:0x78
	v_bitop3_b32 v2, v2, v5, s25 bitop3:0x78
	v_cndmask_b32_e64 v16, v129, -1, vcc
	v_cmp_lt_i32_e32 vcc, -1, v43
	v_bitop3_b32 v25, v16, v12, s25 bitop3:0x78
	v_bitop3_b32 v3, v3, v36, s25 bitop3:0x78
	v_cndmask_b32_e64 v16, v129, -1, vcc
	v_cmp_lt_i32_e32 vcc, -1, v7
	v_bitop3_b32 v26, v16, v43, s25 bitop3:0x78
	v_and_b32_e32 v19, 0xffffff00, v50
	v_cndmask_b32_e64 v16, v129, -1, vcc
	v_cmp_lt_i32_e32 vcc, -1, v45
	v_bitop3_b32 v27, v16, v7, s25 bitop3:0x78
	v_not_b32_e32 v32, v6
	v_cndmask_b32_e64 v16, v129, -1, vcc
	v_cmp_lt_i32_e32 vcc, -1, v14
	v_bitop3_b32 v28, v16, v45, s25 bitop3:0x78
	v_not_b32_e32 v33, v8
	v_cndmask_b32_e64 v16, v129, -1, vcc
	v_cmp_lt_i32_e32 vcc, -1, v48
	v_bitop3_b32 v29, v16, v14, s25 bitop3:0x78
	v_not_b32_e32 v35, v34
	v_cndmask_b32_e64 v16, v129, -1, vcc
	v_cmp_lt_i32_e32 vcc, -1, v6
	v_bitop3_b32 v30, v16, v48, s25 bitop3:0x78
	v_and_b32_e32 v16, 0xffffff00, v6
	v_cndmask_b32_e64 v17, v129, -1, vcc
	v_xor_b32_e32 v31, v17, v16
	v_sub_f32_e32 v0, v0, v31
	v_mul_f32_e32 v0, 0x3fb8aa3b, v0
	v_cmp_lt_i32_e32 vcc, -1, v50
	v_exp_f32_e32 v17, v0
	v_sub_f32_e32 v0, v1, v31
	v_sub_f32_e32 v2, v2, v31
	v_cndmask_b32_e64 v20, v129, -1, vcc
	v_mul_f32_e32 v0, 0x3fb8aa3b, v0
	v_mul_f32_e32 v2, 0x3fb8aa3b, v2
	v_exp_f32_e32 v18, v0
	v_xor_b32_e32 v0, v20, v19
	v_exp_f32_e32 v19, v2
	v_sub_f32_e32 v2, v3, v31
	v_mul_f32_e32 v2, 0x3fb8aa3b, v2
	v_exp_f32_e32 v20, v2
	v_sub_f32_e32 v2, v21, v31
	v_mul_f32_e32 v2, 0x3fb8aa3b, v2
	v_exp_f32_e32 v21, v2
	v_sub_f32_e32 v2, v22, v31
	v_mul_f32_e32 v2, 0x3fb8aa3b, v2
	v_exp_f32_e32 v22, v2
	v_sub_f32_e32 v2, v23, v31
	v_mul_f32_e32 v2, 0x3fb8aa3b, v2
	v_sub_f32_e32 v16, v31, v31
	v_exp_f32_e32 v23, v2
	v_sub_f32_e32 v2, v24, v31
	v_mul_f32_e32 v16, 0x3fb8aa3b, v16
	v_mul_f32_e32 v2, 0x3fb8aa3b, v2
	v_exp_f32_e32 v16, v16
	v_exp_f32_e32 v24, v2
	v_sub_f32_e32 v2, v25, v31
	v_mul_f32_e32 v2, 0x3fb8aa3b, v2
	v_exp_f32_e32 v25, v2
	v_sub_f32_e32 v2, v26, v31
	v_mul_f32_e32 v2, 0x3fb8aa3b, v2
	v_add_f32_e32 v1, 0, v16
	v_exp_f32_e32 v26, v2
	v_sub_f32_e32 v2, v27, v31
	v_add_f32_e32 v1, v17, v1
	v_mul_f32_e32 v2, 0x3fb8aa3b, v2
	v_add_f32_e32 v1, v18, v1
	v_exp_f32_e32 v27, v2
	v_sub_f32_e32 v2, v28, v31
	v_add_f32_e32 v1, v19, v1
	v_mul_f32_e32 v2, 0x3fb8aa3b, v2
	v_add_f32_e32 v1, v20, v1
	v_exp_f32_e32 v28, v2
	v_sub_f32_e32 v2, v29, v31
	v_add_f32_e32 v1, v21, v1
	v_mul_f32_e32 v2, 0x3fb8aa3b, v2
	v_add_f32_e32 v1, v22, v1
	v_exp_f32_e32 v29, v2
	v_sub_f32_e32 v2, v30, v31
	v_sub_f32_e32 v0, v0, v31
	v_not_b32_e32 v9, v5
	v_add_f32_e32 v1, v23, v1
	v_mul_f32_e32 v2, 0x3fb8aa3b, v2
	v_mul_f32_e32 v0, 0x3fb8aa3b, v0
	v_add_f32_e32 v1, v24, v1
	v_exp_f32_e32 v30, v2
	v_exp_f32_e32 v31, v0
	v_bfe_u32 v0, v32, 4, 4
	v_bitop3_b32 v2, v6, 15, v6 bitop3:0xc
	v_bfe_u32 v3, v33, 4, 4
	v_bitop3_b32 v6, v8, 15, v8 bitop3:0xc
	v_bfe_u32 v8, v35, 4, 4
	v_bitop3_b32 v32, v34, 15, v34 bitop3:0xc
	v_bfe_u32 v9, v9, 4, 4
	v_bitop3_b32 v5, v5, 15, v5 bitop3:0xc
	v_add_f32_e32 v1, v25, v1
	v_add_u32_e32 v0, v117, v0
	v_add_u32_e32 v2, v117, v2
	v_add_u32_e32 v3, v117, v3
	v_add_u32_e32 v6, v117, v6
	v_add_u32_e32 v8, v117, v8
	v_add_u32_e32 v32, v117, v32
	v_add_u32_e32 v9, v117, v9
	v_add_u32_e32 v5, v117, v5
	v_add_f32_e32 v1, v26, v1
	ds_read_u8 v0, v0 offset:8192
	ds_read_u8 v2, v2 offset:8208
	ds_read_u8 v3, v3 offset:8192
	ds_read_u8 v6, v6 offset:8208
	ds_read_u8 v8, v8 offset:8192
	ds_read_u8 v32, v32 offset:8208
	ds_read_u8 v9, v9 offset:8192
	ds_read_u8 v5, v5 offset:8208
	v_add_f32_e32 v1, v27, v1
	v_add_f32_e32 v1, v28, v1
	v_add_f32_e32 v1, v29, v1
	v_not_b32_e32 v37, v36
	v_not_b32_e32 v15, v10
	v_not_b32_e32 v39, v38
	v_not_b32_e32 v40, v4
	v_add_f32_e32 v1, v30, v1
	v_add_f32_e32 v33, v31, v1
	s_waitcnt lgkmcnt(6)
	v_lshl_add_u32 v0, v0, 7, v2
	s_waitcnt lgkmcnt(4)
	v_lshl_add_u32 v1, v3, 7, v6
	s_waitcnt lgkmcnt(2)
	v_lshl_add_u32 v2, v8, 7, v32
	s_waitcnt lgkmcnt(0)
	v_lshl_add_u32 v3, v9, 7, v5
	v_bfe_u32 v5, v37, 4, 4
	v_bitop3_b32 v6, v36, 15, v36 bitop3:0xc
	v_bfe_u32 v8, v15, 4, 4
	v_bitop3_b32 v9, v10, 15, v10 bitop3:0xc
	v_bfe_u32 v10, v39, 4, 4
	v_bitop3_b32 v15, v38, 15, v38 bitop3:0xc
	v_bfe_u32 v32, v40, 4, 4
	v_add_u32_e32 v5, v117, v5
	v_add_u32_e32 v6, v117, v6
	v_add_u32_e32 v8, v117, v8
	v_add_u32_e32 v9, v117, v9
	v_add_u32_e32 v10, v117, v10
	v_add_u32_e32 v15, v117, v15
	v_bitop3_b32 v4, v4, 15, v4 bitop3:0xc
	v_add_u32_e32 v32, v117, v32
	v_add_u32_e32 v4, v117, v4
	ds_read_u8 v5, v5 offset:8192
	ds_read_u8 v6, v6 offset:8208
	ds_read_u8 v8, v8 offset:8192
	ds_read_u8 v9, v9 offset:8208
	ds_read_u8 v10, v10 offset:8192
	ds_read_u8 v15, v15 offset:8208
	ds_read_u8 v32, v32 offset:8192
	ds_read_u8 v34, v4 offset:8208
	v_not_b32_e32 v42, v41
	v_not_b32_e32 v13, v12
	v_not_b32_e32 v44, v43
	v_not_b32_e32 v11, v7
	s_waitcnt lgkmcnt(6)
	v_lshl_add_u32 v4, v5, 7, v6
	s_waitcnt lgkmcnt(4)
	v_lshl_add_u32 v5, v8, 7, v9
	s_waitcnt lgkmcnt(2)
; __device__ __forceinline__ void peer_stage2_batch(const Params& P, int tbase, int tstride, int lane, unsigned char* res, unsigned char* scr) {
;     ...
;     const float inv = 1.f / den;
;     __builtin_amdgcn_s_waitcnt(0xc07f);
;     __builtin_amdgcn_wave_barrier();
;     int ids[16];
; #pragma unroll
;     for (int r = 0; r < 16; ++r) {
;         const int pos = 255 - (int)(top[r] & 255u), i = pos >> 4, j = pos & 15;
;         ids[r] = (int)scr[lane * 32 + i] * 128 + (int)scr[lane * 32 + 16 + j];
;     }
;     int* sid = (int*)(res + tau * 1024) + hd * 16; float* sgate = (float*)(res + tau * 1024 + 512) + hd * 16;
; #pragma unroll
;     for (int q = 0; q < 4; ++q) {
;         *(int4*)(sid + 4 * q) = make_int4(ids[4 * q], ids[4 * q + 1], ids[4 * q + 2], ids[4 * q + 3]);
;         *(float4*)(sgate + 4 * q) = make_float4(e[4 * q] * inv, e[4 * q + 1] * inv, e[4 * q + 2] * inv, e[4 * q + 3] * inv);
;     }
	v_lshl_add_u32 v6, v10, 7, v15
	v_bfe_u32 v8, v42, 4, 4
	v_bitop3_b32 v9, v41, 15, v41 bitop3:0xc
	v_bfe_u32 v10, v13, 4, 4
	v_bitop3_b32 v12, v12, 15, v12 bitop3:0xc
	v_bfe_u32 v13, v44, 4, 4
	v_bitop3_b32 v15, v43, 15, v43 bitop3:0xc
	v_bfe_u32 v11, v11, 4, 4
	v_add_u32_e32 v8, v117, v8
	v_add_u32_e32 v9, v117, v9
	v_add_u32_e32 v10, v117, v10
	v_add_u32_e32 v12, v117, v12
	v_add_u32_e32 v13, v117, v13
	v_add_u32_e32 v15, v117, v15
	v_bitop3_b32 v7, v7, 15, v7 bitop3:0xc
	v_add_u32_e32 v11, v117, v11
	v_add_u32_e32 v7, v117, v7
	ds_read_u8 v8, v8 offset:8192
	ds_read_u8 v9, v9 offset:8208
	ds_read_u8 v10, v10 offset:8192
	ds_read_u8 v12, v12 offset:8208
	ds_read_u8 v13, v13 offset:8192
	ds_read_u8 v15, v15 offset:8208
	ds_read_u8 v11, v11 offset:8192
	ds_read_u8 v35, v7 offset:8208
	v_not_b32_e32 v46, v45
	v_not_b32_e32 v47, v14
	v_not_b32_e32 v49, v48
	v_not_b32_e32 v51, v50
	s_waitcnt lgkmcnt(8)
	v_lshl_add_u32 v7, v32, 7, v34
	s_waitcnt lgkmcnt(6)
	v_lshl_add_u32 v8, v8, 7, v9
	s_waitcnt lgkmcnt(4)
	v_lshl_add_u32 v9, v10, 7, v12
	s_waitcnt lgkmcnt(2)
	v_lshl_add_u32 v10, v13, 7, v15
	s_waitcnt lgkmcnt(0)
	v_lshl_add_u32 v11, v11, 7, v35
	v_bfe_u32 v12, v46, 4, 4
	v_bitop3_b32 v13, v45, 15, v45 bitop3:0xc
	v_bfe_u32 v15, v47, 4, 4
	v_bitop3_b32 v14, v14, 15, v14 bitop3:0xc
	v_bfe_u32 v32, v49, 4, 4
	v_bitop3_b32 v34, v48, 15, v48 bitop3:0xc
	v_bfe_u32 v35, v51, 4, 4
	v_bitop3_b32 v36, v50, 15, v50 bitop3:0xc
	v_div_scale_f32 v37, s[16:17], v33, v33, 1.0
	v_add_u32_e32 v12, v117, v12
	v_add_u32_e32 v13, v117, v13
	v_add_u32_e32 v15, v117, v15
	v_add_u32_e32 v14, v117, v14
	v_add_u32_e32 v32, v117, v32
	v_add_u32_e32 v34, v117, v34
	v_add_u32_e32 v35, v117, v35
	v_add_u32_e32 v36, v117, v36
	v_rcp_f32_e32 v38, v37
	ds_read_u8 v12, v12 offset:8192
	ds_read_u8 v13, v13 offset:8208
	ds_read_u8 v15, v15 offset:8192
	ds_read_u8 v14, v14 offset:8208
	ds_read_u8 v32, v32 offset:8192
	ds_read_u8 v34, v34 offset:8208
	ds_read_u8 v35, v35 offset:8192
	ds_read_u8 v36, v36 offset:8208
	s_waitcnt lgkmcnt(6)
	v_lshl_add_u32 v12, v12, 7, v13
	s_waitcnt lgkmcnt(4)
	v_lshl_add_u32 v13, v15, 7, v14
	s_waitcnt lgkmcnt(2)
	v_lshl_add_u32 v14, v32, 7, v34
	v_fma_f32 v32, -v37, v38, 1.0
	v_fmac_f32_e32 v38, v32, v38
	v_div_scale_f32 v32, vcc, 1.0, v33, 1.0
	v_mul_f32_e32 v34, v32, v38
	s_waitcnt lgkmcnt(0)
	v_lshl_add_u32 v15, v35, 7, v36
	v_fma_f32 v35, -v37, v34, v32
	v_fmac_f32_e32 v34, v35, v38
	v_fma_f32 v32, -v37, v34, v32
	v_div_fmas_f32 v32, v32, v38, v34
	v_div_fixup_f32 v32, v32, v33, 1.0
	ds_write_b128 v118, v[0:3]
	v_pk_mul_f32 v[0:1], v[16:17], v[32:33] op_sel_hi:[1,0]
	v_pk_mul_f32 v[2:3], v[18:19], v[32:33] op_sel_hi:[1,0]
	ds_write_b128 v118, v[0:3] offset:512
	ds_write_b128 v118, v[4:7] offset:16
	v_pk_mul_f32 v[0:1], v[20:21], v[32:33] op_sel_hi:[1,0]
	v_pk_mul_f32 v[2:3], v[22:23], v[32:33] op_sel_hi:[1,0]
	ds_write_b128 v118, v[0:3] offset:528
	ds_write_b128 v118, v[8:11] offset:32
	v_pk_mul_f32 v[0:1], v[24:25], v[32:33] op_sel_hi:[1,0]
	v_pk_mul_f32 v[2:3], v[26:27], v[32:33] op_sel_hi:[1,0]
	ds_write_b128 v118, v[0:3] offset:544
	ds_write_b128 v118, v[12:15] offset:48
	v_pk_mul_f32 v[0:1], v[28:29], v[32:33] op_sel_hi:[1,0]
	v_pk_mul_f32 v[2:3], v[30:31], v[32:33] op_sel_hi:[1,0]
	ds_write_b128 v118, v[0:3] offset:560
	s_waitcnt lgkmcnt(0)
	s_mov_b32 s88, 0
.Lbk_loop:
	v_lshl_add_u32 v10, s88, 10, v114
	v_lshl_add_u32 v11, v131, 2, v10
	ds_read2st64_b32 v[0:1], v11 offset1:1
	ds_read2st64_b32 v[2:3], v11 offset0:2 offset1:3
	s_waitcnt lgkmcnt(0)
	v_lshrrev_b32_e32 v4, 12, v0
	v_lshrrev_b32_e32 v5, 12, v1
	s_mov_b32 s89, 0
	v_cmp_eq_u32_e32 vcc, 0, v4
	s_nop 1
	v_mbcnt_lo_u32_b32 v6, vcc_lo, 0
	v_mbcnt_hi_u32_b32 v6, vcc_hi, v6
	s_bcnt1_i32_b64 s90, vcc
	v_add_u32_e32 v6, s89, v6
	v_cndmask_b32_e32 v8, v8, v6, vcc
	s_add_i32 s89, s89, s90
	v_cmp_eq_u32_e32 vcc, 0, v5
	s_nop 1
	v_mbcnt_lo_u32_b32 v7, vcc_lo, 0
	v_mbcnt_hi_u32_b32 v7, vcc_hi, v7
	s_bcnt1_i32_b64 s90, vcc
	v_add_u32_e32 v7, s89, v7
	v_cndmask_b32_e32 v9, v9, v7, vcc
	s_add_i32 s89, s89, s90
	v_cmp_eq_u32_e32 vcc, 1, v4
	s_nop 1
	v_mbcnt_lo_u32_b32 v6, vcc_lo, 0
	v_mbcnt_hi_u32_b32 v6, vcc_hi, v6
	s_bcnt1_i32_b64 s90, vcc
	v_add_u32_e32 v6, s89, v6
	v_cndmask_b32_e32 v8, v8, v6, vcc
	s_add_i32 s89, s89, s90
	v_cmp_eq_u32_e32 vcc, 1, v5
	s_nop 1
	v_mbcnt_lo_u32_b32 v7, vcc_lo, 0
	v_mbcnt_hi_u32_b32 v7, vcc_hi, v7
	s_bcnt1_i32_b64 s90, vcc
	v_add_u32_e32 v7, s89, v7
	v_cndmask_b32_e32 v9, v9, v7, vcc
	s_add_i32 s89, s89, s90
	v_cmp_eq_u32_e32 vcc, 2, v4
	s_nop 1
	v_mbcnt_lo_u32_b32 v6, vcc_lo, 0
	v_mbcnt_hi_u32_b32 v6, vcc_hi, v6
	s_bcnt1_i32_b64 s90, vcc
	v_add_u32_e32 v6, s89, v6
	v_cndmask_b32_e32 v8, v8, v6, vcc
	s_add_i32 s89, s89, s90
	v_cmp_eq_u32_e32 vcc, 2, v5
	s_nop 1
	v_mbcnt_lo_u32_b32 v7, vcc_lo, 0
	v_mbcnt_hi_u32_b32 v7, vcc_hi, v7
	s_bcnt1_i32_b64 s90, vcc
	v_add_u32_e32 v7, s89, v7
	v_cndmask_b32_e32 v9, v9, v7, vcc
	s_add_i32 s89, s89, s90
	v_cmp_eq_u32_e32 vcc, 3, v4
	s_nop 1
	v_mbcnt_lo_u32_b32 v6, vcc_lo, 0
	v_mbcnt_hi_u32_b32 v6, vcc_hi, v6
	s_bcnt1_i32_b64 s90, vcc
	v_add_u32_e32 v6, s89, v6
	v_cndmask_b32_e32 v8, v8, v6, vcc
	s_add_i32 s89, s89, s90
	v_cmp_eq_u32_e32 vcc, 3, v5
	s_nop 1
	v_mbcnt_lo_u32_b32 v7, vcc_lo, 0
	v_mbcnt_hi_u32_b32 v7, vcc_hi, v7
	s_bcnt1_i32_b64 s90, vcc
	v_add_u32_e32 v7, s89, v7
	v_cndmask_b32_e32 v9, v9, v7, vcc
	s_add_i32 s89, s89, s90
	v_lshl_add_u32 v8, v8, 2, v10
	v_lshl_add_u32 v9, v9, 2, v10
	ds_write_b32 v8, v0
	ds_write_b32 v8, v2 offset:512
	ds_write_b32 v9, v1
	ds_write_b32 v9, v3 offset:512
	s_waitcnt lgkmcnt(0)
	s_add_i32 s88, s88, 1
	s_cmp_lt_u32 s88, 8
	s_cbranch_scc1 .Lbk_loop
	s_branch .LBB0_1382

; __device__ __forceinline__ void peer_token(const Params& P, int t, int lane, int* sidx, float* sval, const int* sid, const float* sgate, const unsigned* szero) {
;     const bf16_t* xn = (const bf16_t*)(P.ws + WS_XN) + (size_t)t * DM;
;     const uint4 xa_pre = *(const uint4*)(xn + lane * 16), xb_pre = *(const uint4*)(xn + lane * 16 + 8);
;     const float rstd = ((const float*)(P.ws + WS_RSTD))[t];
;     const unsigned char* V = P.ws + WS_V + lane * 8;
;     const float* usc = (const float*)(P.ws + WS_USC);
;     const float* vsc = (const float*)(P.ws + WS_VSC);
;     const int g = lane >> 4, lr = lane & 15;
;     unsigned char* shi = (unsigned char*)sval;
;     unsigned char* slo = (unsigned char*)sidx;
;     {
;         const uint4 xa = xa_pre, xb = xb_pre;
;         const unsigned xw[8] = {xa.x, xa.y, xa.z, xa.w, xb.x, xb.y, xb.z, xb.w};
;         unsigned hi[4], lo[4];
; #pragma unroll
;         for (int i = 0; i < 4; ++i) {
;             const float x0 = bflo(xw[2 * i]), x1 = bfhi(xw[2 * i]), x2 = bflo(xw[2 * i + 1]), x3 = bfhi(xw[2 * i + 1]);
;             int wd = 0;
;             wd = __builtin_amdgcn_cvt_pk_fp8_f32(x0, x1, wd, false);
;             wd = __builtin_amdgcn_cvt_pk_fp8_f32(x2, x3, wd, true);
;             const f32x2 h01 = __builtin_amdgcn_cvt_pk_f32_fp8(wd, false), h23 = __builtin_amdgcn_cvt_pk_f32_fp8(wd, true);
;             int wl = 0;
;             wl = __builtin_amdgcn_cvt_pk_fp8_f32(x0 - h01.x, x1 - h01.y, wl, false);
;             wl = __builtin_amdgcn_cvt_pk_fp8_f32(x2 - h23.x, x3 - h23.y, wl, true);
;             hi[i] = (unsigned)wd; lo[i] = (unsigned)wl;
;         }
;         *(uint4*)(shi + lane * 16) = make_uint4(hi[0], hi[1], hi[2], hi[3]);
;         *(uint4*)(slo + lane * 16) = make_uint4(lo[0], lo[1], lo[2], lo[3]);
;     }
;     __builtin_amdgcn_s_waitcnt(0xc07f);
;     __builtin_amdgcn_wave_barrier();
;     {
;         typedef int v8i __attribute__((ext_vector_type(8)));
;         const unsigned char* Ub = P.ws + WS_U;
;         const unsigned lofs = 64u * (unsigned)(lr >> 3) + 16u * (unsigned)g;
;         const unsigned char* bsrc = (lr < 4) ? (((lr & 2) ? slo : shi) + 128 * (lr & 1) + 16 * g) : (const unsigned char*)szero;
;         const int bstep = (lr < 4) ? 256 : 0, bhalf = (lr < 4) ? 64 : 16;
;         v8i Bv[4];
; #pragma unroll
;         for (int st = 0; st < 4; ++st) {
.LBB0_1382:
	s_mul_i32 s16, s85, s22
	v_add_u32_e32 v112, s16, v130
	v_cmp_gt_i32_e32 vcc, s20, v112
	s_and_saveexec_b64 s[16:17], vcc
	s_cbranch_execz .LBB0_1381
	v_ashrrev_i32_e32 v113, 31, v112
	v_lshlrev_b64 v[0:1], 11, v[112:113]
	v_lshl_add_u64 v[110:111], s[36:37], 0, v[0:1]
	v_lshl_add_u64 v[4:5], v[102:103], 1, v[110:111]
	global_load_dwordx4 v[0:3], v[4:5], off
	s_nop 0
	global_load_dwordx4 v[4:7], v[4:5], off offset:16
	v_mov_b32_e32 v8, 0
	v_mov_b32_e32 v9, 0
	v_mov_b32_e32 v10, 0
	v_mov_b32_e32 v11, 0
	v_mov_b32_e32 v12, 0
	v_mov_b32_e32 v13, 0
	v_mov_b32_e32 v14, 0
	v_mov_b32_e32 v15, 0
	v_lshl_add_u32 v139, s85, 10, v114
	v_add_u32_e32 v26, v123, v121
	v_add_u32_e32 v27, v124, v121
	v_add_u32_e32 v28, v125, v121
	v_add_u32_e32 v32, v126, v121
	v_lshl_add_u64 v[16:17], v[112:113], 2, s[4:5]
	v_lshl_add_u32 v141, v115, 2, v139
	global_load_dword v140, v[16:17], off
	s_waitcnt vmcnt(2)
	v_lshlrev_b32_e32 v29, 16, v0
	v_and_b32_e32 v30, 0xffff0000, v0
	v_lshlrev_b32_e32 v34, 16, v2
	v_and_b32_e32 v35, 0xffff0000, v2
	s_waitcnt vmcnt(1)
	v_lshlrev_b32_e32 v38, 16, v4
	v_and_b32_e32 v39, 0xffff0000, v4
	v_lshlrev_b32_e32 v42, 16, v6
	v_and_b32_e32 v43, 0xffff0000, v6
	v_cvt_pk_fp8_f32 v8, v29, v30
	v_cvt_pk_fp8_f32 v9, v34, v35
	v_cvt_pk_fp8_f32 v10, v38, v39
	v_cvt_pk_fp8_f32 v11, v42, v43
	v_lshlrev_b32_e32 v31, 16, v1
	v_and_b32_e32 v33, 0xffff0000, v1
	v_lshlrev_b32_e32 v36, 16, v3
	v_and_b32_e32 v37, 0xffff0000, v3
	v_lshlrev_b32_e32 v40, 16, v5
	v_and_b32_e32 v41, 0xffff0000, v5
	v_lshlrev_b32_e32 v44, 16, v7
	v_and_b32_e32 v45, 0xffff0000, v7
	v_cvt_pk_fp8_f32 v8, v31, v33 op_sel:[0,0,1]
	v_cvt_pk_fp8_f32 v9, v36, v37 op_sel:[0,0,1]
	v_cvt_pk_fp8_f32 v10, v40, v41 op_sel:[0,0,1]
	v_cvt_pk_fp8_f32 v11, v44, v45 op_sel:[0,0,1]
	v_cvt_pk_f32_fp8_e32 v[0:1], v8
	v_cvt_pk_f32_fp8_e32 v[4:5], v9
	v_cvt_pk_f32_fp8_e32 v[18:19], v10
	v_cvt_pk_f32_fp8_e32 v[22:23], v11
	v_cvt_pk_f32_fp8_sdwa v[2:3], v8 src0_sel:WORD_1
	v_cvt_pk_f32_fp8_sdwa v[6:7], v9 src0_sel:WORD_1
	v_cvt_pk_f32_fp8_sdwa v[20:21], v10 src0_sel:WORD_1
	v_cvt_pk_f32_fp8_sdwa v[24:25], v11 src0_sel:WORD_1
	v_sub_f32_e32 v0, v29, v0
	v_sub_f32_e32 v1, v30, v1
	v_sub_f32_e32 v4, v34, v4
	v_sub_f32_e32 v5, v35, v5
	v_sub_f32_e32 v18, v38, v18
	v_sub_f32_e32 v19, v39, v19
	v_sub_f32_e32 v22, v42, v22
	v_sub_f32_e32 v23, v43, v23
	v_cvt_pk_fp8_f32 v12, v0, v1
	v_cvt_pk_fp8_f32 v13, v4, v5
	v_cvt_pk_fp8_f32 v14, v18, v19
	v_cvt_pk_fp8_f32 v15, v22, v23
	v_sub_f32_e32 v2, v31, v2
	v_sub_f32_e32 v3, v33, v3
	v_sub_f32_e32 v6, v36, v6
	v_sub_f32_e32 v7, v37, v7
	v_sub_f32_e32 v20, v40, v20
	v_sub_f32_e32 v21, v41, v21
	v_sub_f32_e32 v24, v44, v24
	v_sub_f32_e32 v25, v45, v25
	v_cvt_pk_fp8_f32 v12, v2, v3 op_sel:[0,0,1]
	v_cvt_pk_fp8_f32 v13, v6, v7 op_sel:[0,0,1]
	v_cvt_pk_fp8_f32 v14, v20, v21 op_sel:[0,0,1]
	v_cvt_pk_fp8_f32 v15, v24, v25 op_sel:[0,0,1]
	ds_write_b128 v119, v[8:11] offset:9216
	ds_write_b128 v119, v[12:15] offset:8192
	s_waitcnt lgkmcnt(0)
	s_and_b32 s90, s85, 3
	s_cmp_eq_u32 s90, 1
	s_cbranch_scc1 .Lbs1
	s_cmp_eq_u32 s90, 2
	s_cbranch_scc1 .Lbs2
	s_cmp_eq_u32 s90, 3
	s_cbranch_scc1 .Lbs3
	ds_read_b128 v[162:165], v150
	ds_read_b128 v[166:169], v151
	ds_read_b128 v[170:173], v152
	ds_read_b128 v[174:177], v153
	s_branch .Lbs_join
.Lbs1:
	ds_read_b128 v[178:181], v150
	ds_read_b128 v[182:185], v151
	ds_read_b128 v[186:189], v152
	ds_read_b128 v[190:193], v153
	s_branch .Lbs_join
.Lbs2:
	ds_read_b128 v[194:197], v150
	ds_read_b128 v[198:201], v151
	ds_read_b128 v[202:205], v152
	ds_read_b128 v[206:209], v153
	s_branch .Lbs_join
.Lbs3:
	ds_read_b128 v[210:213], v150
	ds_read_b128 v[214:217], v151
	ds_read_b128 v[218:221], v152
	ds_read_b128 v[222:225], v153
.Lbs_join:
	s_waitcnt lgkmcnt(0)
	s_or_b64 exec, exec, s[16:17]
	s_add_i32 s85, s85, 1
	s_and_b32 s90, s85, 3
	s_cmp_lg_u32 s90, 0
	s_cbranch_scc1 .LBB0_1382
	s_sub_i32 s90, s85, 4
	v_lshl_add_u32 v234, s90, 10, v114
	v_add_u32_e32 v234, v234, v145
	v_add_u32_e32 v235, 0x400, v234
	v_add_u32_e32 v236, 0x800, v234
	v_add_u32_e32 v237, 0xc00, v234
	s_lshl_b32 s91, s90, 9
	v_add_u32_e32 v238, s91, v155
	ds_read2_b32 v[96:97], v234 offset1:4
	ds_read2_b32 v[98:99], v234 offset0:8 offset1:12
	s_waitcnt lgkmcnt(0)
	v_lshl_add_u32 v96, v96, 9, v144
	v_lshl_add_u32 v97, v97, 9, v144
	v_lshl_add_u32 v98, v98, 9, v144
	v_lshl_add_u32 v99, v99, 9, v144
	global_load_dwordx4 v[0:3], v96, s[10:11]
	global_load_dwordx4 v[4:7], v96, s[10:11] offset:256
	global_load_dwordx4 v[8:11], v97, s[10:11]
	global_load_dwordx4 v[12:15], v97, s[10:11] offset:256
	global_load_dwordx4 v[16:19], v98, s[10:11]
	global_load_dwordx4 v[20:23], v98, s[10:11] offset:256
	global_load_dwordx4 v[24:27], v99, s[10:11]
	global_load_dwordx4 v[28:31], v99, s[10:11] offset:256
	ds_read2_b32 v[226:227], v235 offset1:4
	ds_read2_b32 v[228:229], v235 offset0:8 offset1:12
	s_waitcnt lgkmcnt(0)
	v_lshl_add_u32 v226, v226, 9, v144
	v_lshl_add_u32 v227, v227, 9, v144
	v_lshl_add_u32 v228, v228, 9, v144
	v_lshl_add_u32 v229, v229, 9, v144
	global_load_dwordx4 v[32:35], v226, s[10:11]
	global_load_dwordx4 v[36:39], v226, s[10:11] offset:256
	global_load_dwordx4 v[40:43], v227, s[10:11]
	global_load_dwordx4 v[44:47], v227, s[10:11] offset:256
	global_load_dwordx4 v[48:51], v228, s[10:11]
	global_load_dwordx4 v[52:55], v228, s[10:11] offset:256
	global_load_dwordx4 v[56:59], v229, s[10:11]
	global_load_dwordx4 v[60:63], v229, s[10:11] offset:256
	s_waitcnt vmcnt(8)
; __device__ __forceinline__ void peer_token(const Params& P, int t, int lane, int* sidx, float* sval, const int* sid, const float* sgate, const unsigned* szero) {
;     ...
;         for (int hh = 0; hh < 2; ++hh) off2[hh] = (unsigned)sid[8 * hh + (lr & 7)] * 512u + lofs;
; #pragma unroll
;         for (int hh = 0; hh < 2; ++hh)
; #pragma unroll
;             for (int st = 0; st < 4; ++st) abuf[0][hh][st] = *(const uint4*)(Ub + (off2[hh] + 128 * st));
; #pragma unroll
;         for (int T = 0; T < 8; ++T) {
;             if (T + 1 < 8) {
; #pragma unroll
;                 for (int hh = 0; hh < 2; ++hh) off2[hh] = (unsigned)sid[16 * (T + 1) + 8 * hh + (lr & 7)] * 512u + lofs;
; #pragma unroll
;                 for (int hh = 0; hh < 2; ++hh)
; #pragma unroll
;                     for (int st = 0; st < 4; ++st) abuf[(T + 1) & 1][hh][st] = *(const uint4*)(Ub + (off2[hh] + 128 * st));
;             }
; #pragma unroll
;             for (int hh = 0; hh < 2; ++hh) {
;                 f32x4 au = (f32x4){0.f, 0.f, 0.f, 0.f};
; #pragma unroll
;                 for (int st = 0; st < 4; ++st) {
;                     const uint4 a4 = abuf[T & 1][hh][st];
;                     const v8i Av = {(int)a4.x, (int)a4.y, (int)a4.z, (int)a4.w, 0, 0, 0, 0};
;                     au = __builtin_amdgcn_mfma_scale_f32_16x16x128_f8f6f4(Av, Bv[st], au, 4, 0, 0, 0x7f7f7f7f, 0, 0x7f7f7f7f);
;                 }
;                 if (owner) *(f32x4*)(sact + 16 * T + 8 * hh) = au;
;             }
	v_mfma_scale_f32_16x16x128_f8f6f4 v[64:67], v[0:3], v[162:169], 0, v133, v133 op_sel_hi:[0,0,0] cbsz:4
	v_mfma_scale_f32_16x16x128_f8f6f4 v[64:67], v[4:7], v[170:177], v[64:67], v133, v133 op_sel_hi:[0,0,0] cbsz:4
	v_mfma_scale_f32_16x16x128_f8f6f4 v[68:71], v[8:11], v[162:169], 0, v133, v133 op_sel_hi:[0,0,0] cbsz:4
	v_mfma_scale_f32_16x16x128_f8f6f4 v[68:71], v[12:15], v[170:177], v[68:71], v133, v133 op_sel_hi:[0,0,0] cbsz:4
	v_mfma_scale_f32_16x16x128_f8f6f4 v[72:75], v[16:19], v[162:169], 0, v133, v133 op_sel_hi:[0,0,0] cbsz:4
	v_mfma_scale_f32_16x16x128_f8f6f4 v[72:75], v[20:23], v[170:177], v[72:75], v133, v133 op_sel_hi:[0,0,0] cbsz:4
	v_mfma_scale_f32_16x16x128_f8f6f4 v[76:79], v[24:27], v[162:169], 0, v133, v133 op_sel_hi:[0,0,0] cbsz:4
	v_mfma_scale_f32_16x16x128_f8f6f4 v[76:79], v[28:31], v[170:177], v[76:79], v133, v133 op_sel_hi:[0,0,0] cbsz:4
	ds_read2_b32 v[96:97], v236 offset1:4
	ds_read2_b32 v[98:99], v236 offset0:8 offset1:12
	s_waitcnt lgkmcnt(0)
	v_lshl_add_u32 v96, v96, 9, v144
	v_lshl_add_u32 v97, v97, 9, v144
	v_lshl_add_u32 v98, v98, 9, v144
	v_lshl_add_u32 v99, v99, 9, v144
	global_load_dwordx4 v[0:3], v96, s[10:11]
	global_load_dwordx4 v[4:7], v96, s[10:11] offset:256
	global_load_dwordx4 v[8:11], v97, s[10:11]
	global_load_dwordx4 v[12:15], v97, s[10:11] offset:256
	global_load_dwordx4 v[16:19], v98, s[10:11]
	global_load_dwordx4 v[20:23], v98, s[10:11] offset:256
	global_load_dwordx4 v[24:27], v99, s[10:11]
	global_load_dwordx4 v[28:31], v99, s[10:11] offset:256
	s_waitcnt vmcnt(8)
	v_mfma_scale_f32_16x16x128_f8f6f4 v[80:83], v[32:35], v[178:185], 0, v133, v133 op_sel_hi:[0,0,0] cbsz:4
	v_mfma_scale_f32_16x16x128_f8f6f4 v[80:83], v[36:39], v[186:193], v[80:83], v133, v133 op_sel_hi:[0,0,0] cbsz:4
	v_mfma_scale_f32_16x16x128_f8f6f4 v[84:87], v[40:43], v[178:185], 0, v133, v133 op_sel_hi:[0,0,0] cbsz:4
	v_mfma_scale_f32_16x16x128_f8f6f4 v[84:87], v[44:47], v[186:193], v[84:87], v133, v133 op_sel_hi:[0,0,0] cbsz:4
	v_mfma_scale_f32_16x16x128_f8f6f4 v[88:91], v[48:51], v[178:185], 0, v133, v133 op_sel_hi:[0,0,0] cbsz:4
	v_mfma_scale_f32_16x16x128_f8f6f4 v[88:91], v[52:55], v[186:193], v[88:91], v133, v133 op_sel_hi:[0,0,0] cbsz:4
	v_mfma_scale_f32_16x16x128_f8f6f4 v[92:95], v[56:59], v[178:185], 0, v133, v133 op_sel_hi:[0,0,0] cbsz:4
	v_mfma_scale_f32_16x16x128_f8f6f4 v[92:95], v[60:63], v[186:193], v[92:95], v133, v133 op_sel_hi:[0,0,0] cbsz:4
	s_nop 3
	v_mul_f32_e32 v230, v158, v64
	v_mul_f32_e32 v231, v158, v68
	v_mul_f32_e32 v232, v158, v72
	v_mul_f32_e32 v233, v158, v76
	v_fmac_f32_e32 v230, v159, v65
	v_fmac_f32_e32 v231, v159, v69
	v_fmac_f32_e32 v232, v159, v73
	v_fmac_f32_e32 v233, v159, v77
	v_fmac_f32_e32 v230, v160, v66
	v_fmac_f32_e32 v231, v160, v70
	v_fmac_f32_e32 v232, v160, v74
	v_fmac_f32_e32 v233, v160, v78
	v_fmac_f32_e32 v230, v161, v67
	v_fmac_f32_e32 v231, v161, v71
	v_fmac_f32_e32 v232, v161, v75
	v_fmac_f32_e32 v233, v161, v79
	v_add_f32_dpp v230, v230, v230 quad_perm:[1,0,3,2] row_mask:0xf bank_mask:0xf
	v_add_f32_dpp v231, v231, v231 quad_perm:[1,0,3,2] row_mask:0xf bank_mask:0xf
	v_add_f32_dpp v232, v232, v232 quad_perm:[1,0,3,2] row_mask:0xf bank_mask:0xf
	v_add_f32_dpp v233, v233, v233 quad_perm:[1,0,3,2] row_mask:0xf bank_mask:0xf
	v_add_f32_dpp v230, v230, v230 quad_perm:[2,3,0,1] row_mask:0xf bank_mask:0xf
	v_add_f32_dpp v231, v231, v231 quad_perm:[2,3,0,1] row_mask:0xf bank_mask:0xf
	v_add_f32_dpp v232, v232, v232 quad_perm:[2,3,0,1] row_mask:0xf bank_mask:0xf
	v_add_f32_dpp v233, v233, v233 quad_perm:[2,3,0,1] row_mask:0xf bank_mask:0xf
	v_add_f32_dpp v230, v230, v230 row_half_mirror row_mask:0xf bank_mask:0xf
	v_add_f32_dpp v231, v231, v231 row_half_mirror row_mask:0xf bank_mask:0xf
	v_add_f32_dpp v232, v232, v232 row_half_mirror row_mask:0xf bank_mask:0xf
	v_add_f32_dpp v233, v233, v233 row_half_mirror row_mask:0xf bank_mask:0xf
	s_mov_b32 exec_lo, 0x10001
	s_mov_b32 exec_hi, 0x10001
	ds_write_b32 v238, v230
	ds_write_b32 v238, v231 offset:16
	ds_write_b32 v238, v232 offset:32
	ds_write_b32 v238, v233 offset:48
	s_mov_b64 exec, -1
	ds_read2_b32 v[226:227], v237 offset1:4
	ds_read2_b32 v[228:229], v237 offset0:8 offset1:12
	s_waitcnt lgkmcnt(0)
	v_lshl_add_u32 v226, v226, 9, v144
	v_lshl_add_u32 v227, v227, 9, v144
	v_lshl_add_u32 v228, v228, 9, v144
	v_lshl_add_u32 v229, v229, 9, v144
	global_load_dwordx4 v[32:35], v226, s[10:11]
	global_load_dwordx4 v[36:39], v226, s[10:11] offset:256
	global_load_dwordx4 v[40:43], v227, s[10:11]
	global_load_dwordx4 v[44:47], v227, s[10:11] offset:256
	global_load_dwordx4 v[48:51], v228, s[10:11]
	global_load_dwordx4 v[52:55], v228, s[10:11] offset:256
	global_load_dwordx4 v[56:59], v229, s[10:11]
	global_load_dwordx4 v[60:63], v229, s[10:11] offset:256
	s_waitcnt vmcnt(8)
; __device__ __forceinline__ void peer_token(const Params& P, int t, int lane, int* sidx, float* sval, const int* sid, const float* sgate, const unsigned* szero) {
;     ...
;         for (int T = 0; T < 8; ++T) {
;             if (T + 1 < 8) {
; #pragma unroll
;                 for (int hh = 0; hh < 2; ++hh) off2[hh] = (unsigned)sid[16 * (T + 1) + 8 * hh + (lr & 7)] * 512u + lofs;
; #pragma unroll
;                 for (int hh = 0; hh < 2; ++hh)
; #pragma unroll
;                     for (int st = 0; st < 4; ++st) abuf[(T + 1) & 1][hh][st] = *(const uint4*)(Ub + (off2[hh] + 128 * st));
;             }
; #pragma unroll
;             for (int hh = 0; hh < 2; ++hh) {
;                 f32x4 au = (f32x4){0.f, 0.f, 0.f, 0.f};
; #pragma unroll
;                 for (int st = 0; st < 4; ++st) {
;                     const uint4 a4 = abuf[T & 1][hh][st];
;                     const v8i Av = {(int)a4.x, (int)a4.y, (int)a4.z, (int)a4.w, 0, 0, 0, 0};
;                     au = __builtin_amdgcn_mfma_scale_f32_16x16x128_f8f6f4(Av, Bv[st], au, 4, 0, 0, 0x7f7f7f7f, 0, 0x7f7f7f7f);
;                 }
;                 if (owner) *(f32x4*)(sact + 16 * T + 8 * hh) = au;
;             }
	v_mfma_scale_f32_16x16x128_f8f6f4 v[64:67], v[0:3], v[194:201], 0, v133, v133 op_sel_hi:[0,0,0] cbsz:4
	v_mfma_scale_f32_16x16x128_f8f6f4 v[64:67], v[4:7], v[202:209], v[64:67], v133, v133 op_sel_hi:[0,0,0] cbsz:4
	v_mfma_scale_f32_16x16x128_f8f6f4 v[68:71], v[8:11], v[194:201], 0, v133, v133 op_sel_hi:[0,0,0] cbsz:4
	v_mfma_scale_f32_16x16x128_f8f6f4 v[68:71], v[12:15], v[202:209], v[68:71], v133, v133 op_sel_hi:[0,0,0] cbsz:4
	v_mfma_scale_f32_16x16x128_f8f6f4 v[72:75], v[16:19], v[194:201], 0, v133, v133 op_sel_hi:[0,0,0] cbsz:4
	v_mfma_scale_f32_16x16x128_f8f6f4 v[72:75], v[20:23], v[202:209], v[72:75], v133, v133 op_sel_hi:[0,0,0] cbsz:4
	v_mfma_scale_f32_16x16x128_f8f6f4 v[76:79], v[24:27], v[194:201], 0, v133, v133 op_sel_hi:[0,0,0] cbsz:4
	v_mfma_scale_f32_16x16x128_f8f6f4 v[76:79], v[28:31], v[202:209], v[76:79], v133, v133 op_sel_hi:[0,0,0] cbsz:4
	s_nop 3
	v_mul_f32_e32 v230, v158, v80
	v_mul_f32_e32 v231, v158, v84
	v_mul_f32_e32 v232, v158, v88
	v_mul_f32_e32 v233, v158, v92
	v_fmac_f32_e32 v230, v159, v81
	v_fmac_f32_e32 v231, v159, v85
	v_fmac_f32_e32 v232, v159, v89
	v_fmac_f32_e32 v233, v159, v93
	v_fmac_f32_e32 v230, v160, v82
	v_fmac_f32_e32 v231, v160, v86
	v_fmac_f32_e32 v232, v160, v90
	v_fmac_f32_e32 v233, v160, v94
	v_fmac_f32_e32 v230, v161, v83
	v_fmac_f32_e32 v231, v161, v87
	v_fmac_f32_e32 v232, v161, v91
	v_fmac_f32_e32 v233, v161, v95
	v_add_f32_dpp v230, v230, v230 quad_perm:[1,0,3,2] row_mask:0xf bank_mask:0xf
	v_add_f32_dpp v231, v231, v231 quad_perm:[1,0,3,2] row_mask:0xf bank_mask:0xf
	v_add_f32_dpp v232, v232, v232 quad_perm:[1,0,3,2] row_mask:0xf bank_mask:0xf
	v_add_f32_dpp v233, v233, v233 quad_perm:[1,0,3,2] row_mask:0xf bank_mask:0xf
	v_add_f32_dpp v230, v230, v230 quad_perm:[2,3,0,1] row_mask:0xf bank_mask:0xf
	v_add_f32_dpp v231, v231, v231 quad_perm:[2,3,0,1] row_mask:0xf bank_mask:0xf
	v_add_f32_dpp v232, v232, v232 quad_perm:[2,3,0,1] row_mask:0xf bank_mask:0xf
	v_add_f32_dpp v233, v233, v233 quad_perm:[2,3,0,1] row_mask:0xf bank_mask:0xf
	v_add_f32_dpp v230, v230, v230 row_half_mirror row_mask:0xf bank_mask:0xf
	v_add_f32_dpp v231, v231, v231 row_half_mirror row_mask:0xf bank_mask:0xf
	v_add_f32_dpp v232, v232, v232 row_half_mirror row_mask:0xf bank_mask:0xf
	v_add_f32_dpp v233, v233, v233 row_half_mirror row_mask:0xf bank_mask:0xf
	s_mov_b32 exec_lo, 0x10001
	s_mov_b32 exec_hi, 0x10001
	ds_write_b32 v238, v230 offset:512
	ds_write_b32 v238, v231 offset:528
	ds_write_b32 v238, v232 offset:544
	ds_write_b32 v238, v233 offset:560
	s_mov_b64 exec, -1
	ds_read2_b32 v[96:97], v234 offset0:16 offset1:20
	ds_read2_b32 v[98:99], v234 offset0:24 offset1:28
	s_waitcnt lgkmcnt(0)
	v_lshl_add_u32 v96, v96, 9, v144
	v_lshl_add_u32 v97, v97, 9, v144
	v_lshl_add_u32 v98, v98, 9, v144
	v_lshl_add_u32 v99, v99, 9, v144
	global_load_dwordx4 v[0:3], v96, s[10:11]
	global_load_dwordx4 v[4:7], v96, s[10:11] offset:256
	global_load_dwordx4 v[8:11], v97, s[10:11]
	global_load_dwordx4 v[12:15], v97, s[10:11] offset:256
	global_load_dwordx4 v[16:19], v98, s[10:11]
	global_load_dwordx4 v[20:23], v98, s[10:11] offset:256
	global_load_dwordx4 v[24:27], v99, s[10:11]
	global_load_dwordx4 v[28:31], v99, s[10:11] offset:256
	s_waitcnt vmcnt(8)
	v_mfma_scale_f32_16x16x128_f8f6f4 v[80:83], v[32:35], v[210:217], 0, v133, v133 op_sel_hi:[0,0,0] cbsz:4
	v_mfma_scale_f32_16x16x128_f8f6f4 v[80:83], v[36:39], v[218:225], v[80:83], v133, v133 op_sel_hi:[0,0,0] cbsz:4
	v_mfma_scale_f32_16x16x128_f8f6f4 v[84:87], v[40:43], v[210:217], 0, v133, v133 op_sel_hi:[0,0,0] cbsz:4
	v_mfma_scale_f32_16x16x128_f8f6f4 v[84:87], v[44:47], v[218:225], v[84:87], v133, v133 op_sel_hi:[0,0,0] cbsz:4
	v_mfma_scale_f32_16x16x128_f8f6f4 v[88:91], v[48:51], v[210:217], 0, v133, v133 op_sel_hi:[0,0,0] cbsz:4
	v_mfma_scale_f32_16x16x128_f8f6f4 v[88:91], v[52:55], v[218:225], v[88:91], v133, v133 op_sel_hi:[0,0,0] cbsz:4
	v_mfma_scale_f32_16x16x128_f8f6f4 v[92:95], v[56:59], v[210:217], 0, v133, v133 op_sel_hi:[0,0,0] cbsz:4
	v_mfma_scale_f32_16x16x128_f8f6f4 v[92:95], v[60:63], v[218:225], v[92:95], v133, v133 op_sel_hi:[0,0,0] cbsz:4
	s_nop 3
	v_mul_f32_e32 v230, v158, v64
	v_mul_f32_e32 v231, v158, v68
	v_mul_f32_e32 v232, v158, v72
	v_mul_f32_e32 v233, v158, v76
	v_fmac_f32_e32 v230, v159, v65
	v_fmac_f32_e32 v231, v159, v69
	v_fmac_f32_e32 v232, v159, v73
	v_fmac_f32_e32 v233, v159, v77
	v_fmac_f32_e32 v230, v160, v66
	v_fmac_f32_e32 v231, v160, v70
	v_fmac_f32_e32 v232, v160, v74
	v_fmac_f32_e32 v233, v160, v78
	v_fmac_f32_e32 v230, v161, v67
	v_fmac_f32_e32 v231, v161, v71
	v_fmac_f32_e32 v232, v161, v75
	v_fmac_f32_e32 v233, v161, v79
	v_add_f32_dpp v230, v230, v230 quad_perm:[1,0,3,2] row_mask:0xf bank_mask:0xf
	v_add_f32_dpp v231, v231, v231 quad_perm:[1,0,3,2] row_mask:0xf bank_mask:0xf
	v_add_f32_dpp v232, v232, v232 quad_perm:[1,0,3,2] row_mask:0xf bank_mask:0xf
	v_add_f32_dpp v233, v233, v233 quad_perm:[1,0,3,2] row_mask:0xf bank_mask:0xf
	v_add_f32_dpp v230, v230, v230 quad_perm:[2,3,0,1] row_mask:0xf bank_mask:0xf
	v_add_f32_dpp v231, v231, v231 quad_perm:[2,3,0,1] row_mask:0xf bank_mask:0xf
	v_add_f32_dpp v232, v232, v232 quad_perm:[2,3,0,1] row_mask:0xf bank_mask:0xf
	v_add_f32_dpp v233, v233, v233 quad_perm:[2,3,0,1] row_mask:0xf bank_mask:0xf
	v_add_f32_dpp v230, v230, v230 row_half_mirror row_mask:0xf bank_mask:0xf
	v_add_f32_dpp v231, v231, v231 row_half_mirror row_mask:0xf bank_mask:0xf
	v_add_f32_dpp v232, v232, v232 row_half_mirror row_mask:0xf bank_mask:0xf
	v_add_f32_dpp v233, v233, v233 row_half_mirror row_mask:0xf bank_mask:0xf
	s_mov_b32 exec_lo, 0x10001
	s_mov_b32 exec_hi, 0x10001
	ds_write_b32 v238, v230 offset:1024
	ds_write_b32 v238, v231 offset:1040
	ds_write_b32 v238, v232 offset:1056
	ds_write_b32 v238, v233 offset:1072
	s_mov_b64 exec, -1
	ds_read2_b32 v[226:227], v235 offset0:16 offset1:20
	ds_read2_b32 v[228:229], v235 offset0:24 offset1:28
	s_waitcnt lgkmcnt(0)
; __device__ __forceinline__ void peer_token(const Params& P, int t, int lane, int* sidx, float* sval, const int* sid, const float* sgate, const unsigned* szero) {
;     ...
;         for (int T = 0; T < 8; ++T) {
;             if (T + 1 < 8) {
; #pragma unroll
;                 for (int hh = 0; hh < 2; ++hh) off2[hh] = (unsigned)sid[16 * (T + 1) + 8 * hh + (lr & 7)] * 512u + lofs;
; #pragma unroll
;                 for (int hh = 0; hh < 2; ++hh)
; #pragma unroll
;                     for (int st = 0; st < 4; ++st) abuf[(T + 1) & 1][hh][st] = *(const uint4*)(Ub + (off2[hh] + 128 * st));
;             }
; #pragma unroll
;             for (int hh = 0; hh < 2; ++hh) {
;                 f32x4 au = (f32x4){0.f, 0.f, 0.f, 0.f};
; #pragma unroll
;                 for (int st = 0; st < 4; ++st) {
;                     const uint4 a4 = abuf[T & 1][hh][st];
;                     const v8i Av = {(int)a4.x, (int)a4.y, (int)a4.z, (int)a4.w, 0, 0, 0, 0};
;                     au = __builtin_amdgcn_mfma_scale_f32_16x16x128_f8f6f4(Av, Bv[st], au, 4, 0, 0, 0x7f7f7f7f, 0, 0x7f7f7f7f);
;                 }
;                 if (owner) *(f32x4*)(sact + 16 * T + 8 * hh) = au;
;             }
	v_lshl_add_u32 v226, v226, 9, v144
	v_lshl_add_u32 v227, v227, 9, v144
	v_lshl_add_u32 v228, v228, 9, v144
	v_lshl_add_u32 v229, v229, 9, v144
	global_load_dwordx4 v[32:35], v226, s[10:11]
	global_load_dwordx4 v[36:39], v226, s[10:11] offset:256
	global_load_dwordx4 v[40:43], v227, s[10:11]
	global_load_dwordx4 v[44:47], v227, s[10:11] offset:256
	global_load_dwordx4 v[48:51], v228, s[10:11]
	global_load_dwordx4 v[52:55], v228, s[10:11] offset:256
	global_load_dwordx4 v[56:59], v229, s[10:11]
	global_load_dwordx4 v[60:63], v229, s[10:11] offset:256
	s_waitcnt vmcnt(8)
	v_mfma_scale_f32_16x16x128_f8f6f4 v[64:67], v[0:3], v[162:169], 0, v133, v133 op_sel_hi:[0,0,0] cbsz:4
	v_mfma_scale_f32_16x16x128_f8f6f4 v[64:67], v[4:7], v[170:177], v[64:67], v133, v133 op_sel_hi:[0,0,0] cbsz:4
	v_mfma_scale_f32_16x16x128_f8f6f4 v[68:71], v[8:11], v[162:169], 0, v133, v133 op_sel_hi:[0,0,0] cbsz:4
	v_mfma_scale_f32_16x16x128_f8f6f4 v[68:71], v[12:15], v[170:177], v[68:71], v133, v133 op_sel_hi:[0,0,0] cbsz:4
	v_mfma_scale_f32_16x16x128_f8f6f4 v[72:75], v[16:19], v[162:169], 0, v133, v133 op_sel_hi:[0,0,0] cbsz:4
	v_mfma_scale_f32_16x16x128_f8f6f4 v[72:75], v[20:23], v[170:177], v[72:75], v133, v133 op_sel_hi:[0,0,0] cbsz:4
	v_mfma_scale_f32_16x16x128_f8f6f4 v[76:79], v[24:27], v[162:169], 0, v133, v133 op_sel_hi:[0,0,0] cbsz:4
	v_mfma_scale_f32_16x16x128_f8f6f4 v[76:79], v[28:31], v[170:177], v[76:79], v133, v133 op_sel_hi:[0,0,0] cbsz:4
	s_nop 3
	v_mul_f32_e32 v230, v158, v80
	v_mul_f32_e32 v231, v158, v84
	v_mul_f32_e32 v232, v158, v88
	v_mul_f32_e32 v233, v158, v92
	v_fmac_f32_e32 v230, v159, v81
	v_fmac_f32_e32 v231, v159, v85
	v_fmac_f32_e32 v232, v159, v89
	v_fmac_f32_e32 v233, v159, v93
	v_fmac_f32_e32 v230, v160, v82
	v_fmac_f32_e32 v231, v160, v86
	v_fmac_f32_e32 v232, v160, v90
	v_fmac_f32_e32 v233, v160, v94
	v_fmac_f32_e32 v230, v161, v83
	v_fmac_f32_e32 v231, v161, v87
	v_fmac_f32_e32 v232, v161, v91
	v_fmac_f32_e32 v233, v161, v95
	v_add_f32_dpp v230, v230, v230 quad_perm:[1,0,3,2] row_mask:0xf bank_mask:0xf
	v_add_f32_dpp v231, v231, v231 quad_perm:[1,0,3,2] row_mask:0xf bank_mask:0xf
	v_add_f32_dpp v232, v232, v232 quad_perm:[1,0,3,2] row_mask:0xf bank_mask:0xf
	v_add_f32_dpp v233, v233, v233 quad_perm:[1,0,3,2] row_mask:0xf bank_mask:0xf
	v_add_f32_dpp v230, v230, v230 quad_perm:[2,3,0,1] row_mask:0xf bank_mask:0xf
	v_add_f32_dpp v231, v231, v231 quad_perm:[2,3,0,1] row_mask:0xf bank_mask:0xf
	v_add_f32_dpp v232, v232, v232 quad_perm:[2,3,0,1] row_mask:0xf bank_mask:0xf
	v_add_f32_dpp v233, v233, v233 quad_perm:[2,3,0,1] row_mask:0xf bank_mask:0xf
	v_add_f32_dpp v230, v230, v230 row_half_mirror row_mask:0xf bank_mask:0xf
	v_add_f32_dpp v231, v231, v231 row_half_mirror row_mask:0xf bank_mask:0xf
	v_add_f32_dpp v232, v232, v232 row_half_mirror row_mask:0xf bank_mask:0xf
	v_add_f32_dpp v233, v233, v233 row_half_mirror row_mask:0xf bank_mask:0xf
	s_mov_b32 exec_lo, 0x10001
	s_mov_b32 exec_hi, 0x10001
	ds_write_b32 v238, v230 offset:1536
	ds_write_b32 v238, v231 offset:1552
	ds_write_b32 v238, v232 offset:1568
	ds_write_b32 v238, v233 offset:1584
	s_mov_b64 exec, -1
	ds_read2_b32 v[96:97], v236 offset0:16 offset1:20
	ds_read2_b32 v[98:99], v236 offset0:24 offset1:28
	s_waitcnt lgkmcnt(0)
	v_lshl_add_u32 v96, v96, 9, v144
	v_lshl_add_u32 v97, v97, 9, v144
	v_lshl_add_u32 v98, v98, 9, v144
	v_lshl_add_u32 v99, v99, 9, v144
	global_load_dwordx4 v[0:3], v96, s[10:11]
	global_load_dwordx4 v[4:7], v96, s[10:11] offset:256
	global_load_dwordx4 v[8:11], v97, s[10:11]
	global_load_dwordx4 v[12:15], v97, s[10:11] offset:256
	global_load_dwordx4 v[16:19], v98, s[10:11]
	global_load_dwordx4 v[20:23], v98, s[10:11] offset:256
	global_load_dwordx4 v[24:27], v99, s[10:11]
	global_load_dwordx4 v[28:31], v99, s[10:11] offset:256
	s_waitcnt vmcnt(8)
	v_mfma_scale_f32_16x16x128_f8f6f4 v[80:83], v[32:35], v[178:185], 0, v133, v133 op_sel_hi:[0,0,0] cbsz:4
	v_mfma_scale_f32_16x16x128_f8f6f4 v[80:83], v[36:39], v[186:193], v[80:83], v133, v133 op_sel_hi:[0,0,0] cbsz:4
	v_mfma_scale_f32_16x16x128_f8f6f4 v[84:87], v[40:43], v[178:185], 0, v133, v133 op_sel_hi:[0,0,0] cbsz:4
	v_mfma_scale_f32_16x16x128_f8f6f4 v[84:87], v[44:47], v[186:193], v[84:87], v133, v133 op_sel_hi:[0,0,0] cbsz:4
	v_mfma_scale_f32_16x16x128_f8f6f4 v[88:91], v[48:51], v[178:185], 0, v133, v133 op_sel_hi:[0,0,0] cbsz:4
	v_mfma_scale_f32_16x16x128_f8f6f4 v[88:91], v[52:55], v[186:193], v[88:91], v133, v133 op_sel_hi:[0,0,0] cbsz:4
	v_mfma_scale_f32_16x16x128_f8f6f4 v[92:95], v[56:59], v[178:185], 0, v133, v133 op_sel_hi:[0,0,0] cbsz:4
	v_mfma_scale_f32_16x16x128_f8f6f4 v[92:95], v[60:63], v[186:193], v[92:95], v133, v133 op_sel_hi:[0,0,0] cbsz:4
	s_nop 3
	v_mul_f32_e32 v230, v158, v64
	v_mul_f32_e32 v231, v158, v68
	v_mul_f32_e32 v232, v158, v72
	v_mul_f32_e32 v233, v158, v76
	v_fmac_f32_e32 v230, v159, v65
	v_fmac_f32_e32 v231, v159, v69
	v_fmac_f32_e32 v232, v159, v73
	v_fmac_f32_e32 v233, v159, v77
	v_fmac_f32_e32 v230, v160, v66
	v_fmac_f32_e32 v231, v160, v70
	v_fmac_f32_e32 v232, v160, v74
	v_fmac_f32_e32 v233, v160, v78
	v_fmac_f32_e32 v230, v161, v67
	v_fmac_f32_e32 v231, v161, v71
	v_fmac_f32_e32 v232, v161, v75
	v_fmac_f32_e32 v233, v161, v79
	v_add_f32_dpp v230, v230, v230 quad_perm:[1,0,3,2] row_mask:0xf bank_mask:0xf
	v_add_f32_dpp v231, v231, v231 quad_perm:[1,0,3,2] row_mask:0xf bank_mask:0xf
	v_add_f32_dpp v232, v232, v232 quad_perm:[1,0,3,2] row_mask:0xf bank_mask:0xf
	v_add_f32_dpp v233, v233, v233 quad_perm:[1,0,3,2] row_mask:0xf bank_mask:0xf
	v_add_f32_dpp v230, v230, v230 quad_perm:[2,3,0,1] row_mask:0xf bank_mask:0xf
	v_add_f32_dpp v231, v231, v231 quad_perm:[2,3,0,1] row_mask:0xf bank_mask:0xf
	v_add_f32_dpp v232, v232, v232 quad_perm:[2,3,0,1] row_mask:0xf bank_mask:0xf
	v_add_f32_dpp v233, v233, v233 quad_perm:[2,3,0,1] row_mask:0xf bank_mask:0xf
	v_add_f32_dpp v230, v230, v230 row_half_mirror row_mask:0xf bank_mask:0xf
	v_add_f32_dpp v231, v231, v231 row_half_mirror row_mask:0xf bank_mask:0xf
	v_add_f32_dpp v232, v232, v232 row_half_mirror row_mask:0xf bank_mask:0xf
	v_add_f32_dpp v233, v233, v233 row_half_mirror row_mask:0xf bank_mask:0xf
	s_mov_b32 exec_lo, 0x10001
	s_mov_b32 exec_hi, 0x10001
	ds_write_b32 v238, v230 offset:64
	ds_write_b32 v238, v231 offset:80
	ds_write_b32 v238, v232 offset:96
	ds_write_b32 v238, v233 offset:112
	s_mov_b64 exec, -1
	ds_read2_b32 v[226:227], v237 offset0:16 offset1:20
	ds_read2_b32 v[228:229], v237 offset0:24 offset1:28
	s_waitcnt lgkmcnt(0)
; __device__ __forceinline__ void peer_token(const Params& P, int t, int lane, int* sidx, float* sval, const int* sid, const float* sgate, const unsigned* szero) {
;     ...
;         for (int T = 0; T < 8; ++T) {
;             if (T + 1 < 8) {
; #pragma unroll
;                 for (int hh = 0; hh < 2; ++hh) off2[hh] = (unsigned)sid[16 * (T + 1) + 8 * hh + (lr & 7)] * 512u + lofs;
; #pragma unroll
;                 for (int hh = 0; hh < 2; ++hh)
; #pragma unroll
;                     for (int st = 0; st < 4; ++st) abuf[(T + 1) & 1][hh][st] = *(const uint4*)(Ub + (off2[hh] + 128 * st));
;             }
; #pragma unroll
;             for (int hh = 0; hh < 2; ++hh) {
;                 f32x4 au = (f32x4){0.f, 0.f, 0.f, 0.f};
; #pragma unroll
;                 for (int st = 0; st < 4; ++st) {
;                     const uint4 a4 = abuf[T & 1][hh][st];
;                     const v8i Av = {(int)a4.x, (int)a4.y, (int)a4.z, (int)a4.w, 0, 0, 0, 0};
;                     au = __builtin_amdgcn_mfma_scale_f32_16x16x128_f8f6f4(Av, Bv[st], au, 4, 0, 0, 0x7f7f7f7f, 0, 0x7f7f7f7f);
;                 }
;                 if (owner) *(f32x4*)(sact + 16 * T + 8 * hh) = au;
;             }
	v_lshl_add_u32 v226, v226, 9, v144
	v_lshl_add_u32 v227, v227, 9, v144
	v_lshl_add_u32 v228, v228, 9, v144
	v_lshl_add_u32 v229, v229, 9, v144
	global_load_dwordx4 v[32:35], v226, s[10:11]
	global_load_dwordx4 v[36:39], v226, s[10:11] offset:256
	global_load_dwordx4 v[40:43], v227, s[10:11]
	global_load_dwordx4 v[44:47], v227, s[10:11] offset:256
	global_load_dwordx4 v[48:51], v228, s[10:11]
	global_load_dwordx4 v[52:55], v228, s[10:11] offset:256
	global_load_dwordx4 v[56:59], v229, s[10:11]
	global_load_dwordx4 v[60:63], v229, s[10:11] offset:256
	s_waitcnt vmcnt(8)
	v_mfma_scale_f32_16x16x128_f8f6f4 v[64:67], v[0:3], v[194:201], 0, v133, v133 op_sel_hi:[0,0,0] cbsz:4
	v_mfma_scale_f32_16x16x128_f8f6f4 v[64:67], v[4:7], v[202:209], v[64:67], v133, v133 op_sel_hi:[0,0,0] cbsz:4
	v_mfma_scale_f32_16x16x128_f8f6f4 v[68:71], v[8:11], v[194:201], 0, v133, v133 op_sel_hi:[0,0,0] cbsz:4
	v_mfma_scale_f32_16x16x128_f8f6f4 v[68:71], v[12:15], v[202:209], v[68:71], v133, v133 op_sel_hi:[0,0,0] cbsz:4
	v_mfma_scale_f32_16x16x128_f8f6f4 v[72:75], v[16:19], v[194:201], 0, v133, v133 op_sel_hi:[0,0,0] cbsz:4
	v_mfma_scale_f32_16x16x128_f8f6f4 v[72:75], v[20:23], v[202:209], v[72:75], v133, v133 op_sel_hi:[0,0,0] cbsz:4
	v_mfma_scale_f32_16x16x128_f8f6f4 v[76:79], v[24:27], v[194:201], 0, v133, v133 op_sel_hi:[0,0,0] cbsz:4
	v_mfma_scale_f32_16x16x128_f8f6f4 v[76:79], v[28:31], v[202:209], v[76:79], v133, v133 op_sel_hi:[0,0,0] cbsz:4
	s_nop 3
	v_mul_f32_e32 v230, v158, v80
	v_mul_f32_e32 v231, v158, v84
	v_mul_f32_e32 v232, v158, v88
	v_mul_f32_e32 v233, v158, v92
	v_fmac_f32_e32 v230, v159, v81
	v_fmac_f32_e32 v231, v159, v85
	v_fmac_f32_e32 v232, v159, v89
	v_fmac_f32_e32 v233, v159, v93
	v_fmac_f32_e32 v230, v160, v82
	v_fmac_f32_e32 v231, v160, v86
	v_fmac_f32_e32 v232, v160, v90
	v_fmac_f32_e32 v233, v160, v94
	v_fmac_f32_e32 v230, v161, v83
	v_fmac_f32_e32 v231, v161, v87
	v_fmac_f32_e32 v232, v161, v91
	v_fmac_f32_e32 v233, v161, v95
	v_add_f32_dpp v230, v230, v230 quad_perm:[1,0,3,2] row_mask:0xf bank_mask:0xf
	v_add_f32_dpp v231, v231, v231 quad_perm:[1,0,3,2] row_mask:0xf bank_mask:0xf
	v_add_f32_dpp v232, v232, v232 quad_perm:[1,0,3,2] row_mask:0xf bank_mask:0xf
	v_add_f32_dpp v233, v233, v233 quad_perm:[1,0,3,2] row_mask:0xf bank_mask:0xf
	v_add_f32_dpp v230, v230, v230 quad_perm:[2,3,0,1] row_mask:0xf bank_mask:0xf
	v_add_f32_dpp v231, v231, v231 quad_perm:[2,3,0,1] row_mask:0xf bank_mask:0xf
	v_add_f32_dpp v232, v232, v232 quad_perm:[2,3,0,1] row_mask:0xf bank_mask:0xf
	v_add_f32_dpp v233, v233, v233 quad_perm:[2,3,0,1] row_mask:0xf bank_mask:0xf
	v_add_f32_dpp v230, v230, v230 row_half_mirror row_mask:0xf bank_mask:0xf
	v_add_f32_dpp v231, v231, v231 row_half_mirror row_mask:0xf bank_mask:0xf
	v_add_f32_dpp v232, v232, v232 row_half_mirror row_mask:0xf bank_mask:0xf
	v_add_f32_dpp v233, v233, v233 row_half_mirror row_mask:0xf bank_mask:0xf
	s_mov_b32 exec_lo, 0x10001
	s_mov_b32 exec_hi, 0x10001
	ds_write_b32 v238, v230 offset:576
	ds_write_b32 v238, v231 offset:592
	ds_write_b32 v238, v232 offset:608
	ds_write_b32 v238, v233 offset:624
	s_mov_b64 exec, -1
	ds_read2_b32 v[96:97], v234 offset0:32 offset1:36
	ds_read2_b32 v[98:99], v234 offset0:40 offset1:44
	s_waitcnt lgkmcnt(0)
	v_lshl_add_u32 v96, v96, 9, v144
	v_lshl_add_u32 v97, v97, 9, v144
	v_lshl_add_u32 v98, v98, 9, v144
	v_lshl_add_u32 v99, v99, 9, v144
	global_load_dwordx4 v[0:3], v96, s[10:11]
	global_load_dwordx4 v[4:7], v96, s[10:11] offset:256
	global_load_dwordx4 v[8:11], v97, s[10:11]
	global_load_dwordx4 v[12:15], v97, s[10:11] offset:256
	global_load_dwordx4 v[16:19], v98, s[10:11]
	global_load_dwordx4 v[20:23], v98, s[10:11] offset:256
	global_load_dwordx4 v[24:27], v99, s[10:11]
	global_load_dwordx4 v[28:31], v99, s[10:11] offset:256
	s_waitcnt vmcnt(8)
	v_mfma_scale_f32_16x16x128_f8f6f4 v[80:83], v[32:35], v[210:217], 0, v133, v133 op_sel_hi:[0,0,0] cbsz:4
	v_mfma_scale_f32_16x16x128_f8f6f4 v[80:83], v[36:39], v[218:225], v[80:83], v133, v133 op_sel_hi:[0,0,0] cbsz:4
	v_mfma_scale_f32_16x16x128_f8f6f4 v[84:87], v[40:43], v[210:217], 0, v133, v133 op_sel_hi:[0,0,0] cbsz:4
	v_mfma_scale_f32_16x16x128_f8f6f4 v[84:87], v[44:47], v[218:225], v[84:87], v133, v133 op_sel_hi:[0,0,0] cbsz:4
	v_mfma_scale_f32_16x16x128_f8f6f4 v[88:91], v[48:51], v[210:217], 0, v133, v133 op_sel_hi:[0,0,0] cbsz:4
	v_mfma_scale_f32_16x16x128_f8f6f4 v[88:91], v[52:55], v[218:225], v[88:91], v133, v133 op_sel_hi:[0,0,0] cbsz:4
	v_mfma_scale_f32_16x16x128_f8f6f4 v[92:95], v[56:59], v[210:217], 0, v133, v133 op_sel_hi:[0,0,0] cbsz:4
	v_mfma_scale_f32_16x16x128_f8f6f4 v[92:95], v[60:63], v[218:225], v[92:95], v133, v133 op_sel_hi:[0,0,0] cbsz:4
	s_nop 3
	v_mul_f32_e32 v230, v158, v64
	v_mul_f32_e32 v231, v158, v68
	v_mul_f32_e32 v232, v158, v72
	v_mul_f32_e32 v233, v158, v76
	v_fmac_f32_e32 v230, v159, v65
	v_fmac_f32_e32 v231, v159, v69
	v_fmac_f32_e32 v232, v159, v73
	v_fmac_f32_e32 v233, v159, v77
	v_fmac_f32_e32 v230, v160, v66
	v_fmac_f32_e32 v231, v160, v70
	v_fmac_f32_e32 v232, v160, v74
	v_fmac_f32_e32 v233, v160, v78
	v_fmac_f32_e32 v230, v161, v67
	v_fmac_f32_e32 v231, v161, v71
	v_fmac_f32_e32 v232, v161, v75
	v_fmac_f32_e32 v233, v161, v79
	v_add_f32_dpp v230, v230, v230 quad_perm:[1,0,3,2] row_mask:0xf bank_mask:0xf
	v_add_f32_dpp v231, v231, v231 quad_perm:[1,0,3,2] row_mask:0xf bank_mask:0xf
	v_add_f32_dpp v232, v232, v232 quad_perm:[1,0,3,2] row_mask:0xf bank_mask:0xf
	v_add_f32_dpp v233, v233, v233 quad_perm:[1,0,3,2] row_mask:0xf bank_mask:0xf
	v_add_f32_dpp v230, v230, v230 quad_perm:[2,3,0,1] row_mask:0xf bank_mask:0xf
	v_add_f32_dpp v231, v231, v231 quad_perm:[2,3,0,1] row_mask:0xf bank_mask:0xf
	v_add_f32_dpp v232, v232, v232 quad_perm:[2,3,0,1] row_mask:0xf bank_mask:0xf
	v_add_f32_dpp v233, v233, v233 quad_perm:[2,3,0,1] row_mask:0xf bank_mask:0xf
	v_add_f32_dpp v230, v230, v230 row_half_mirror row_mask:0xf bank_mask:0xf
	v_add_f32_dpp v231, v231, v231 row_half_mirror row_mask:0xf bank_mask:0xf
	v_add_f32_dpp v232, v232, v232 row_half_mirror row_mask:0xf bank_mask:0xf
	v_add_f32_dpp v233, v233, v233 row_half_mirror row_mask:0xf bank_mask:0xf
	s_mov_b32 exec_lo, 0x10001
	s_mov_b32 exec_hi, 0x10001
	ds_write_b32 v238, v230 offset:1088
	ds_write_b32 v238, v231 offset:1104
	ds_write_b32 v238, v232 offset:1120
	ds_write_b32 v238, v233 offset:1136
	s_mov_b64 exec, -1
	ds_read2_b32 v[226:227], v235 offset0:32 offset1:36
	ds_read2_b32 v[228:229], v235 offset0:40 offset1:44
	s_waitcnt lgkmcnt(0)
; __device__ __forceinline__ void peer_token(const Params& P, int t, int lane, int* sidx, float* sval, const int* sid, const float* sgate, const unsigned* szero) {
;     ...
;         for (int T = 0; T < 8; ++T) {
;             if (T + 1 < 8) {
; #pragma unroll
;                 for (int hh = 0; hh < 2; ++hh) off2[hh] = (unsigned)sid[16 * (T + 1) + 8 * hh + (lr & 7)] * 512u + lofs;
; #pragma unroll
;                 for (int hh = 0; hh < 2; ++hh)
; #pragma unroll
;                     for (int st = 0; st < 4; ++st) abuf[(T + 1) & 1][hh][st] = *(const uint4*)(Ub + (off2[hh] + 128 * st));
;             }
; #pragma unroll
;             for (int hh = 0; hh < 2; ++hh) {
;                 f32x4 au = (f32x4){0.f, 0.f, 0.f, 0.f};
; #pragma unroll
;                 for (int st = 0; st < 4; ++st) {
;                     const uint4 a4 = abuf[T & 1][hh][st];
;                     const v8i Av = {(int)a4.x, (int)a4.y, (int)a4.z, (int)a4.w, 0, 0, 0, 0};
;                     au = __builtin_amdgcn_mfma_scale_f32_16x16x128_f8f6f4(Av, Bv[st], au, 4, 0, 0, 0x7f7f7f7f, 0, 0x7f7f7f7f);
;                 }
;                 if (owner) *(f32x4*)(sact + 16 * T + 8 * hh) = au;
;             }
	v_lshl_add_u32 v226, v226, 9, v144
	v_lshl_add_u32 v227, v227, 9, v144
	v_lshl_add_u32 v228, v228, 9, v144
	v_lshl_add_u32 v229, v229, 9, v144
	global_load_dwordx4 v[32:35], v226, s[10:11]
	global_load_dwordx4 v[36:39], v226, s[10:11] offset:256
	global_load_dwordx4 v[40:43], v227, s[10:11]
	global_load_dwordx4 v[44:47], v227, s[10:11] offset:256
	global_load_dwordx4 v[48:51], v228, s[10:11]
	global_load_dwordx4 v[52:55], v228, s[10:11] offset:256
	global_load_dwordx4 v[56:59], v229, s[10:11]
	global_load_dwordx4 v[60:63], v229, s[10:11] offset:256
	s_waitcnt vmcnt(8)
	v_mfma_scale_f32_16x16x128_f8f6f4 v[64:67], v[0:3], v[162:169], 0, v133, v133 op_sel_hi:[0,0,0] cbsz:4
	v_mfma_scale_f32_16x16x128_f8f6f4 v[64:67], v[4:7], v[170:177], v[64:67], v133, v133 op_sel_hi:[0,0,0] cbsz:4
	v_mfma_scale_f32_16x16x128_f8f6f4 v[68:71], v[8:11], v[162:169], 0, v133, v133 op_sel_hi:[0,0,0] cbsz:4
	v_mfma_scale_f32_16x16x128_f8f6f4 v[68:71], v[12:15], v[170:177], v[68:71], v133, v133 op_sel_hi:[0,0,0] cbsz:4
	v_mfma_scale_f32_16x16x128_f8f6f4 v[72:75], v[16:19], v[162:169], 0, v133, v133 op_sel_hi:[0,0,0] cbsz:4
	v_mfma_scale_f32_16x16x128_f8f6f4 v[72:75], v[20:23], v[170:177], v[72:75], v133, v133 op_sel_hi:[0,0,0] cbsz:4
	v_mfma_scale_f32_16x16x128_f8f6f4 v[76:79], v[24:27], v[162:169], 0, v133, v133 op_sel_hi:[0,0,0] cbsz:4
	v_mfma_scale_f32_16x16x128_f8f6f4 v[76:79], v[28:31], v[170:177], v[76:79], v133, v133 op_sel_hi:[0,0,0] cbsz:4
	s_nop 3
	v_mul_f32_e32 v230, v158, v80
	v_mul_f32_e32 v231, v158, v84
	v_mul_f32_e32 v232, v158, v88
	v_mul_f32_e32 v233, v158, v92
	v_fmac_f32_e32 v230, v159, v81
	v_fmac_f32_e32 v231, v159, v85
	v_fmac_f32_e32 v232, v159, v89
	v_fmac_f32_e32 v233, v159, v93
	v_fmac_f32_e32 v230, v160, v82
	v_fmac_f32_e32 v231, v160, v86
	v_fmac_f32_e32 v232, v160, v90
	v_fmac_f32_e32 v233, v160, v94
	v_fmac_f32_e32 v230, v161, v83
	v_fmac_f32_e32 v231, v161, v87
	v_fmac_f32_e32 v232, v161, v91
	v_fmac_f32_e32 v233, v161, v95
	v_add_f32_dpp v230, v230, v230 quad_perm:[1,0,3,2] row_mask:0xf bank_mask:0xf
	v_add_f32_dpp v231, v231, v231 quad_perm:[1,0,3,2] row_mask:0xf bank_mask:0xf
	v_add_f32_dpp v232, v232, v232 quad_perm:[1,0,3,2] row_mask:0xf bank_mask:0xf
	v_add_f32_dpp v233, v233, v233 quad_perm:[1,0,3,2] row_mask:0xf bank_mask:0xf
	v_add_f32_dpp v230, v230, v230 quad_perm:[2,3,0,1] row_mask:0xf bank_mask:0xf
	v_add_f32_dpp v231, v231, v231 quad_perm:[2,3,0,1] row_mask:0xf bank_mask:0xf
	v_add_f32_dpp v232, v232, v232 quad_perm:[2,3,0,1] row_mask:0xf bank_mask:0xf
	v_add_f32_dpp v233, v233, v233 quad_perm:[2,3,0,1] row_mask:0xf bank_mask:0xf
	v_add_f32_dpp v230, v230, v230 row_half_mirror row_mask:0xf bank_mask:0xf
	v_add_f32_dpp v231, v231, v231 row_half_mirror row_mask:0xf bank_mask:0xf
	v_add_f32_dpp v232, v232, v232 row_half_mirror row_mask:0xf bank_mask:0xf
	v_add_f32_dpp v233, v233, v233 row_half_mirror row_mask:0xf bank_mask:0xf
	s_mov_b32 exec_lo, 0x10001
	s_mov_b32 exec_hi, 0x10001
	ds_write_b32 v238, v230 offset:1600
	ds_write_b32 v238, v231 offset:1616
	ds_write_b32 v238, v232 offset:1632
	ds_write_b32 v238, v233 offset:1648
	s_mov_b64 exec, -1
	ds_read2_b32 v[96:97], v236 offset0:32 offset1:36
	ds_read2_b32 v[98:99], v236 offset0:40 offset1:44
	s_waitcnt lgkmcnt(0)
	v_lshl_add_u32 v96, v96, 9, v144
	v_lshl_add_u32 v97, v97, 9, v144
	v_lshl_add_u32 v98, v98, 9, v144
	v_lshl_add_u32 v99, v99, 9, v144
	global_load_dwordx4 v[0:3], v96, s[10:11]
	global_load_dwordx4 v[4:7], v96, s[10:11] offset:256
	global_load_dwordx4 v[8:11], v97, s[10:11]
	global_load_dwordx4 v[12:15], v97, s[10:11] offset:256
	global_load_dwordx4 v[16:19], v98, s[10:11]
	global_load_dwordx4 v[20:23], v98, s[10:11] offset:256
	global_load_dwordx4 v[24:27], v99, s[10:11]
	global_load_dwordx4 v[28:31], v99, s[10:11] offset:256
	s_waitcnt vmcnt(8)
	v_mfma_scale_f32_16x16x128_f8f6f4 v[80:83], v[32:35], v[178:185], 0, v133, v133 op_sel_hi:[0,0,0] cbsz:4
	v_mfma_scale_f32_16x16x128_f8f6f4 v[80:83], v[36:39], v[186:193], v[80:83], v133, v133 op_sel_hi:[0,0,0] cbsz:4
	v_mfma_scale_f32_16x16x128_f8f6f4 v[84:87], v[40:43], v[178:185], 0, v133, v133 op_sel_hi:[0,0,0] cbsz:4
	v_mfma_scale_f32_16x16x128_f8f6f4 v[84:87], v[44:47], v[186:193], v[84:87], v133, v133 op_sel_hi:[0,0,0] cbsz:4
	v_mfma_scale_f32_16x16x128_f8f6f4 v[88:91], v[48:51], v[178:185], 0, v133, v133 op_sel_hi:[0,0,0] cbsz:4
	v_mfma_scale_f32_16x16x128_f8f6f4 v[88:91], v[52:55], v[186:193], v[88:91], v133, v133 op_sel_hi:[0,0,0] cbsz:4
	v_mfma_scale_f32_16x16x128_f8f6f4 v[92:95], v[56:59], v[178:185], 0, v133, v133 op_sel_hi:[0,0,0] cbsz:4
	v_mfma_scale_f32_16x16x128_f8f6f4 v[92:95], v[60:63], v[186:193], v[92:95], v133, v133 op_sel_hi:[0,0,0] cbsz:4
	s_nop 3
	v_mul_f32_e32 v230, v158, v64
	v_mul_f32_e32 v231, v158, v68
	v_mul_f32_e32 v232, v158, v72
	v_mul_f32_e32 v233, v158, v76
	v_fmac_f32_e32 v230, v159, v65
	v_fmac_f32_e32 v231, v159, v69
	v_fmac_f32_e32 v232, v159, v73
	v_fmac_f32_e32 v233, v159, v77
	v_fmac_f32_e32 v230, v160, v66
	v_fmac_f32_e32 v231, v160, v70
	v_fmac_f32_e32 v232, v160, v74
	v_fmac_f32_e32 v233, v160, v78
	v_fmac_f32_e32 v230, v161, v67
	v_fmac_f32_e32 v231, v161, v71
	v_fmac_f32_e32 v232, v161, v75
	v_fmac_f32_e32 v233, v161, v79
	v_add_f32_dpp v230, v230, v230 quad_perm:[1,0,3,2] row_mask:0xf bank_mask:0xf
	v_add_f32_dpp v231, v231, v231 quad_perm:[1,0,3,2] row_mask:0xf bank_mask:0xf
	v_add_f32_dpp v232, v232, v232 quad_perm:[1,0,3,2] row_mask:0xf bank_mask:0xf
	v_add_f32_dpp v233, v233, v233 quad_perm:[1,0,3,2] row_mask:0xf bank_mask:0xf
	v_add_f32_dpp v230, v230, v230 quad_perm:[2,3,0,1] row_mask:0xf bank_mask:0xf
	v_add_f32_dpp v231, v231, v231 quad_perm:[2,3,0,1] row_mask:0xf bank_mask:0xf
	v_add_f32_dpp v232, v232, v232 quad_perm:[2,3,0,1] row_mask:0xf bank_mask:0xf
	v_add_f32_dpp v233, v233, v233 quad_perm:[2,3,0,1] row_mask:0xf bank_mask:0xf
	v_add_f32_dpp v230, v230, v230 row_half_mirror row_mask:0xf bank_mask:0xf
	v_add_f32_dpp v231, v231, v231 row_half_mirror row_mask:0xf bank_mask:0xf
	v_add_f32_dpp v232, v232, v232 row_half_mirror row_mask:0xf bank_mask:0xf
	v_add_f32_dpp v233, v233, v233 row_half_mirror row_mask:0xf bank_mask:0xf
	s_mov_b32 exec_lo, 0x10001
	s_mov_b32 exec_hi, 0x10001
	ds_write_b32 v238, v230 offset:128
	ds_write_b32 v238, v231 offset:144
	ds_write_b32 v238, v232 offset:160
	ds_write_b32 v238, v233 offset:176
	s_mov_b64 exec, -1
	ds_read2_b32 v[226:227], v237 offset0:32 offset1:36
	ds_read2_b32 v[228:229], v237 offset0:40 offset1:44
	s_waitcnt lgkmcnt(0)
; __device__ __forceinline__ void peer_token(const Params& P, int t, int lane, int* sidx, float* sval, const int* sid, const float* sgate, const unsigned* szero) {
;     ...
;         for (int T = 0; T < 8; ++T) {
;             if (T + 1 < 8) {
; #pragma unroll
;                 for (int hh = 0; hh < 2; ++hh) off2[hh] = (unsigned)sid[16 * (T + 1) + 8 * hh + (lr & 7)] * 512u + lofs;
; #pragma unroll
;                 for (int hh = 0; hh < 2; ++hh)
; #pragma unroll
;                     for (int st = 0; st < 4; ++st) abuf[(T + 1) & 1][hh][st] = *(const uint4*)(Ub + (off2[hh] + 128 * st));
;             }
; #pragma unroll
;             for (int hh = 0; hh < 2; ++hh) {
;                 f32x4 au = (f32x4){0.f, 0.f, 0.f, 0.f};
; #pragma unroll
;                 for (int st = 0; st < 4; ++st) {
;                     const uint4 a4 = abuf[T & 1][hh][st];
;                     const v8i Av = {(int)a4.x, (int)a4.y, (int)a4.z, (int)a4.w, 0, 0, 0, 0};
;                     au = __builtin_amdgcn_mfma_scale_f32_16x16x128_f8f6f4(Av, Bv[st], au, 4, 0, 0, 0x7f7f7f7f, 0, 0x7f7f7f7f);
;                 }
;                 if (owner) *(f32x4*)(sact + 16 * T + 8 * hh) = au;
;             }
	v_lshl_add_u32 v226, v226, 9, v144
	v_lshl_add_u32 v227, v227, 9, v144
	v_lshl_add_u32 v228, v228, 9, v144
	v_lshl_add_u32 v229, v229, 9, v144
	global_load_dwordx4 v[32:35], v226, s[10:11]
	global_load_dwordx4 v[36:39], v226, s[10:11] offset:256
	global_load_dwordx4 v[40:43], v227, s[10:11]
	global_load_dwordx4 v[44:47], v227, s[10:11] offset:256
	global_load_dwordx4 v[48:51], v228, s[10:11]
	global_load_dwordx4 v[52:55], v228, s[10:11] offset:256
	global_load_dwordx4 v[56:59], v229, s[10:11]
	global_load_dwordx4 v[60:63], v229, s[10:11] offset:256
	s_waitcnt vmcnt(8)
	v_mfma_scale_f32_16x16x128_f8f6f4 v[64:67], v[0:3], v[194:201], 0, v133, v133 op_sel_hi:[0,0,0] cbsz:4
	v_mfma_scale_f32_16x16x128_f8f6f4 v[64:67], v[4:7], v[202:209], v[64:67], v133, v133 op_sel_hi:[0,0,0] cbsz:4
	v_mfma_scale_f32_16x16x128_f8f6f4 v[68:71], v[8:11], v[194:201], 0, v133, v133 op_sel_hi:[0,0,0] cbsz:4
	v_mfma_scale_f32_16x16x128_f8f6f4 v[68:71], v[12:15], v[202:209], v[68:71], v133, v133 op_sel_hi:[0,0,0] cbsz:4
	v_mfma_scale_f32_16x16x128_f8f6f4 v[72:75], v[16:19], v[194:201], 0, v133, v133 op_sel_hi:[0,0,0] cbsz:4
	v_mfma_scale_f32_16x16x128_f8f6f4 v[72:75], v[20:23], v[202:209], v[72:75], v133, v133 op_sel_hi:[0,0,0] cbsz:4
	v_mfma_scale_f32_16x16x128_f8f6f4 v[76:79], v[24:27], v[194:201], 0, v133, v133 op_sel_hi:[0,0,0] cbsz:4
	v_mfma_scale_f32_16x16x128_f8f6f4 v[76:79], v[28:31], v[202:209], v[76:79], v133, v133 op_sel_hi:[0,0,0] cbsz:4
	s_nop 3
	v_mul_f32_e32 v230, v158, v80
	v_mul_f32_e32 v231, v158, v84
	v_mul_f32_e32 v232, v158, v88
	v_mul_f32_e32 v233, v158, v92
	v_fmac_f32_e32 v230, v159, v81
	v_fmac_f32_e32 v231, v159, v85
	v_fmac_f32_e32 v232, v159, v89
	v_fmac_f32_e32 v233, v159, v93
	v_fmac_f32_e32 v230, v160, v82
	v_fmac_f32_e32 v231, v160, v86
	v_fmac_f32_e32 v232, v160, v90
	v_fmac_f32_e32 v233, v160, v94
	v_fmac_f32_e32 v230, v161, v83
	v_fmac_f32_e32 v231, v161, v87
	v_fmac_f32_e32 v232, v161, v91
	v_fmac_f32_e32 v233, v161, v95
	v_add_f32_dpp v230, v230, v230 quad_perm:[1,0,3,2] row_mask:0xf bank_mask:0xf
	v_add_f32_dpp v231, v231, v231 quad_perm:[1,0,3,2] row_mask:0xf bank_mask:0xf
	v_add_f32_dpp v232, v232, v232 quad_perm:[1,0,3,2] row_mask:0xf bank_mask:0xf
	v_add_f32_dpp v233, v233, v233 quad_perm:[1,0,3,2] row_mask:0xf bank_mask:0xf
	v_add_f32_dpp v230, v230, v230 quad_perm:[2,3,0,1] row_mask:0xf bank_mask:0xf
	v_add_f32_dpp v231, v231, v231 quad_perm:[2,3,0,1] row_mask:0xf bank_mask:0xf
	v_add_f32_dpp v232, v232, v232 quad_perm:[2,3,0,1] row_mask:0xf bank_mask:0xf
	v_add_f32_dpp v233, v233, v233 quad_perm:[2,3,0,1] row_mask:0xf bank_mask:0xf
	v_add_f32_dpp v230, v230, v230 row_half_mirror row_mask:0xf bank_mask:0xf
	v_add_f32_dpp v231, v231, v231 row_half_mirror row_mask:0xf bank_mask:0xf
	v_add_f32_dpp v232, v232, v232 row_half_mirror row_mask:0xf bank_mask:0xf
	v_add_f32_dpp v233, v233, v233 row_half_mirror row_mask:0xf bank_mask:0xf
	s_mov_b32 exec_lo, 0x10001
	s_mov_b32 exec_hi, 0x10001
	ds_write_b32 v238, v230 offset:640
	ds_write_b32 v238, v231 offset:656
	ds_write_b32 v238, v232 offset:672
	ds_write_b32 v238, v233 offset:688
	s_mov_b64 exec, -1
	ds_read2_b32 v[96:97], v234 offset0:48 offset1:52
	ds_read2_b32 v[98:99], v234 offset0:56 offset1:60
	s_waitcnt lgkmcnt(0)
	v_lshl_add_u32 v96, v96, 9, v144
	v_lshl_add_u32 v97, v97, 9, v144
	v_lshl_add_u32 v98, v98, 9, v144
	v_lshl_add_u32 v99, v99, 9, v144
	global_load_dwordx4 v[0:3], v96, s[10:11]
	global_load_dwordx4 v[4:7], v96, s[10:11] offset:256
	global_load_dwordx4 v[8:11], v97, s[10:11]
	global_load_dwordx4 v[12:15], v97, s[10:11] offset:256
	global_load_dwordx4 v[16:19], v98, s[10:11]
	global_load_dwordx4 v[20:23], v98, s[10:11] offset:256
	global_load_dwordx4 v[24:27], v99, s[10:11]
	global_load_dwordx4 v[28:31], v99, s[10:11] offset:256
	s_waitcnt vmcnt(8)
	v_mfma_scale_f32_16x16x128_f8f6f4 v[80:83], v[32:35], v[210:217], 0, v133, v133 op_sel_hi:[0,0,0] cbsz:4
	v_mfma_scale_f32_16x16x128_f8f6f4 v[80:83], v[36:39], v[218:225], v[80:83], v133, v133 op_sel_hi:[0,0,0] cbsz:4
	v_mfma_scale_f32_16x16x128_f8f6f4 v[84:87], v[40:43], v[210:217], 0, v133, v133 op_sel_hi:[0,0,0] cbsz:4
	v_mfma_scale_f32_16x16x128_f8f6f4 v[84:87], v[44:47], v[218:225], v[84:87], v133, v133 op_sel_hi:[0,0,0] cbsz:4
	v_mfma_scale_f32_16x16x128_f8f6f4 v[88:91], v[48:51], v[210:217], 0, v133, v133 op_sel_hi:[0,0,0] cbsz:4
	v_mfma_scale_f32_16x16x128_f8f6f4 v[88:91], v[52:55], v[218:225], v[88:91], v133, v133 op_sel_hi:[0,0,0] cbsz:4
	v_mfma_scale_f32_16x16x128_f8f6f4 v[92:95], v[56:59], v[210:217], 0, v133, v133 op_sel_hi:[0,0,0] cbsz:4
	v_mfma_scale_f32_16x16x128_f8f6f4 v[92:95], v[60:63], v[218:225], v[92:95], v133, v133 op_sel_hi:[0,0,0] cbsz:4
	s_nop 3
	v_mul_f32_e32 v230, v158, v64
	v_mul_f32_e32 v231, v158, v68
	v_mul_f32_e32 v232, v158, v72
	v_mul_f32_e32 v233, v158, v76
	v_fmac_f32_e32 v230, v159, v65
	v_fmac_f32_e32 v231, v159, v69
	v_fmac_f32_e32 v232, v159, v73
	v_fmac_f32_e32 v233, v159, v77
	v_fmac_f32_e32 v230, v160, v66
	v_fmac_f32_e32 v231, v160, v70
	v_fmac_f32_e32 v232, v160, v74
	v_fmac_f32_e32 v233, v160, v78
	v_fmac_f32_e32 v230, v161, v67
	v_fmac_f32_e32 v231, v161, v71
	v_fmac_f32_e32 v232, v161, v75
	v_fmac_f32_e32 v233, v161, v79
	v_add_f32_dpp v230, v230, v230 quad_perm:[1,0,3,2] row_mask:0xf bank_mask:0xf
	v_add_f32_dpp v231, v231, v231 quad_perm:[1,0,3,2] row_mask:0xf bank_mask:0xf
	v_add_f32_dpp v232, v232, v232 quad_perm:[1,0,3,2] row_mask:0xf bank_mask:0xf
	v_add_f32_dpp v233, v233, v233 quad_perm:[1,0,3,2] row_mask:0xf bank_mask:0xf
	v_add_f32_dpp v230, v230, v230 quad_perm:[2,3,0,1] row_mask:0xf bank_mask:0xf
	v_add_f32_dpp v231, v231, v231 quad_perm:[2,3,0,1] row_mask:0xf bank_mask:0xf
	v_add_f32_dpp v232, v232, v232 quad_perm:[2,3,0,1] row_mask:0xf bank_mask:0xf
	v_add_f32_dpp v233, v233, v233 quad_perm:[2,3,0,1] row_mask:0xf bank_mask:0xf
	v_add_f32_dpp v230, v230, v230 row_half_mirror row_mask:0xf bank_mask:0xf
	v_add_f32_dpp v231, v231, v231 row_half_mirror row_mask:0xf bank_mask:0xf
	v_add_f32_dpp v232, v232, v232 row_half_mirror row_mask:0xf bank_mask:0xf
	v_add_f32_dpp v233, v233, v233 row_half_mirror row_mask:0xf bank_mask:0xf
	s_mov_b32 exec_lo, 0x10001
	s_mov_b32 exec_hi, 0x10001
	ds_write_b32 v238, v230 offset:1152
	ds_write_b32 v238, v231 offset:1168
	ds_write_b32 v238, v232 offset:1184
	ds_write_b32 v238, v233 offset:1200
	s_mov_b64 exec, -1
	ds_read2_b32 v[226:227], v235 offset0:48 offset1:52
	ds_read2_b32 v[228:229], v235 offset0:56 offset1:60
	s_waitcnt lgkmcnt(0)
; __device__ __forceinline__ void peer_token(const Params& P, int t, int lane, int* sidx, float* sval, const int* sid, const float* sgate, const unsigned* szero) {
;     ...
;         for (int T = 0; T < 8; ++T) {
;             if (T + 1 < 8) {
; #pragma unroll
;                 for (int hh = 0; hh < 2; ++hh) off2[hh] = (unsigned)sid[16 * (T + 1) + 8 * hh + (lr & 7)] * 512u + lofs;
; #pragma unroll
;                 for (int hh = 0; hh < 2; ++hh)
; #pragma unroll
;                     for (int st = 0; st < 4; ++st) abuf[(T + 1) & 1][hh][st] = *(const uint4*)(Ub + (off2[hh] + 128 * st));
;             }
; #pragma unroll
;             for (int hh = 0; hh < 2; ++hh) {
;                 f32x4 au = (f32x4){0.f, 0.f, 0.f, 0.f};
; #pragma unroll
;                 for (int st = 0; st < 4; ++st) {
;                     const uint4 a4 = abuf[T & 1][hh][st];
;                     const v8i Av = {(int)a4.x, (int)a4.y, (int)a4.z, (int)a4.w, 0, 0, 0, 0};
;                     au = __builtin_amdgcn_mfma_scale_f32_16x16x128_f8f6f4(Av, Bv[st], au, 4, 0, 0, 0x7f7f7f7f, 0, 0x7f7f7f7f);
;                 }
;                 if (owner) *(f32x4*)(sact + 16 * T + 8 * hh) = au;
;             }
	v_lshl_add_u32 v226, v226, 9, v144
	v_lshl_add_u32 v227, v227, 9, v144
	v_lshl_add_u32 v228, v228, 9, v144
	v_lshl_add_u32 v229, v229, 9, v144
	global_load_dwordx4 v[32:35], v226, s[10:11]
	global_load_dwordx4 v[36:39], v226, s[10:11] offset:256
	global_load_dwordx4 v[40:43], v227, s[10:11]
	global_load_dwordx4 v[44:47], v227, s[10:11] offset:256
	global_load_dwordx4 v[48:51], v228, s[10:11]
	global_load_dwordx4 v[52:55], v228, s[10:11] offset:256
	global_load_dwordx4 v[56:59], v229, s[10:11]
	global_load_dwordx4 v[60:63], v229, s[10:11] offset:256
	s_waitcnt vmcnt(8)
	v_mfma_scale_f32_16x16x128_f8f6f4 v[64:67], v[0:3], v[162:169], 0, v133, v133 op_sel_hi:[0,0,0] cbsz:4
	v_mfma_scale_f32_16x16x128_f8f6f4 v[64:67], v[4:7], v[170:177], v[64:67], v133, v133 op_sel_hi:[0,0,0] cbsz:4
	v_mfma_scale_f32_16x16x128_f8f6f4 v[68:71], v[8:11], v[162:169], 0, v133, v133 op_sel_hi:[0,0,0] cbsz:4
	v_mfma_scale_f32_16x16x128_f8f6f4 v[68:71], v[12:15], v[170:177], v[68:71], v133, v133 op_sel_hi:[0,0,0] cbsz:4
	v_mfma_scale_f32_16x16x128_f8f6f4 v[72:75], v[16:19], v[162:169], 0, v133, v133 op_sel_hi:[0,0,0] cbsz:4
	v_mfma_scale_f32_16x16x128_f8f6f4 v[72:75], v[20:23], v[170:177], v[72:75], v133, v133 op_sel_hi:[0,0,0] cbsz:4
	v_mfma_scale_f32_16x16x128_f8f6f4 v[76:79], v[24:27], v[162:169], 0, v133, v133 op_sel_hi:[0,0,0] cbsz:4
	v_mfma_scale_f32_16x16x128_f8f6f4 v[76:79], v[28:31], v[170:177], v[76:79], v133, v133 op_sel_hi:[0,0,0] cbsz:4
	s_nop 3
	v_mul_f32_e32 v230, v158, v80
	v_mul_f32_e32 v231, v158, v84
	v_mul_f32_e32 v232, v158, v88
	v_mul_f32_e32 v233, v158, v92
	v_fmac_f32_e32 v230, v159, v81
	v_fmac_f32_e32 v231, v159, v85
	v_fmac_f32_e32 v232, v159, v89
	v_fmac_f32_e32 v233, v159, v93
	v_fmac_f32_e32 v230, v160, v82
	v_fmac_f32_e32 v231, v160, v86
	v_fmac_f32_e32 v232, v160, v90
	v_fmac_f32_e32 v233, v160, v94
	v_fmac_f32_e32 v230, v161, v83
	v_fmac_f32_e32 v231, v161, v87
	v_fmac_f32_e32 v232, v161, v91
	v_fmac_f32_e32 v233, v161, v95
	v_add_f32_dpp v230, v230, v230 quad_perm:[1,0,3,2] row_mask:0xf bank_mask:0xf
	v_add_f32_dpp v231, v231, v231 quad_perm:[1,0,3,2] row_mask:0xf bank_mask:0xf
	v_add_f32_dpp v232, v232, v232 quad_perm:[1,0,3,2] row_mask:0xf bank_mask:0xf
	v_add_f32_dpp v233, v233, v233 quad_perm:[1,0,3,2] row_mask:0xf bank_mask:0xf
	v_add_f32_dpp v230, v230, v230 quad_perm:[2,3,0,1] row_mask:0xf bank_mask:0xf
	v_add_f32_dpp v231, v231, v231 quad_perm:[2,3,0,1] row_mask:0xf bank_mask:0xf
	v_add_f32_dpp v232, v232, v232 quad_perm:[2,3,0,1] row_mask:0xf bank_mask:0xf
	v_add_f32_dpp v233, v233, v233 quad_perm:[2,3,0,1] row_mask:0xf bank_mask:0xf
	v_add_f32_dpp v230, v230, v230 row_half_mirror row_mask:0xf bank_mask:0xf
	v_add_f32_dpp v231, v231, v231 row_half_mirror row_mask:0xf bank_mask:0xf
	v_add_f32_dpp v232, v232, v232 row_half_mirror row_mask:0xf bank_mask:0xf
	v_add_f32_dpp v233, v233, v233 row_half_mirror row_mask:0xf bank_mask:0xf
	s_mov_b32 exec_lo, 0x10001
	s_mov_b32 exec_hi, 0x10001
	ds_write_b32 v238, v230 offset:1664
	ds_write_b32 v238, v231 offset:1680
	ds_write_b32 v238, v232 offset:1696
	ds_write_b32 v238, v233 offset:1712
	s_mov_b64 exec, -1
	ds_read2_b32 v[96:97], v236 offset0:48 offset1:52
	ds_read2_b32 v[98:99], v236 offset0:56 offset1:60
	s_waitcnt lgkmcnt(0)
	v_lshl_add_u32 v96, v96, 9, v144
	v_lshl_add_u32 v97, v97, 9, v144
	v_lshl_add_u32 v98, v98, 9, v144
	v_lshl_add_u32 v99, v99, 9, v144
	global_load_dwordx4 v[0:3], v96, s[10:11]
	global_load_dwordx4 v[4:7], v96, s[10:11] offset:256
	global_load_dwordx4 v[8:11], v97, s[10:11]
	global_load_dwordx4 v[12:15], v97, s[10:11] offset:256
	global_load_dwordx4 v[16:19], v98, s[10:11]
	global_load_dwordx4 v[20:23], v98, s[10:11] offset:256
	global_load_dwordx4 v[24:27], v99, s[10:11]
	global_load_dwordx4 v[28:31], v99, s[10:11] offset:256
	s_waitcnt vmcnt(8)
	v_mfma_scale_f32_16x16x128_f8f6f4 v[80:83], v[32:35], v[178:185], 0, v133, v133 op_sel_hi:[0,0,0] cbsz:4
	v_mfma_scale_f32_16x16x128_f8f6f4 v[80:83], v[36:39], v[186:193], v[80:83], v133, v133 op_sel_hi:[0,0,0] cbsz:4
	v_mfma_scale_f32_16x16x128_f8f6f4 v[84:87], v[40:43], v[178:185], 0, v133, v133 op_sel_hi:[0,0,0] cbsz:4
	v_mfma_scale_f32_16x16x128_f8f6f4 v[84:87], v[44:47], v[186:193], v[84:87], v133, v133 op_sel_hi:[0,0,0] cbsz:4
	v_mfma_scale_f32_16x16x128_f8f6f4 v[88:91], v[48:51], v[178:185], 0, v133, v133 op_sel_hi:[0,0,0] cbsz:4
	v_mfma_scale_f32_16x16x128_f8f6f4 v[88:91], v[52:55], v[186:193], v[88:91], v133, v133 op_sel_hi:[0,0,0] cbsz:4
	v_mfma_scale_f32_16x16x128_f8f6f4 v[92:95], v[56:59], v[178:185], 0, v133, v133 op_sel_hi:[0,0,0] cbsz:4
	v_mfma_scale_f32_16x16x128_f8f6f4 v[92:95], v[60:63], v[186:193], v[92:95], v133, v133 op_sel_hi:[0,0,0] cbsz:4
	s_nop 3
	v_mul_f32_e32 v230, v158, v64
	v_mul_f32_e32 v231, v158, v68
	v_mul_f32_e32 v232, v158, v72
	v_mul_f32_e32 v233, v158, v76
	v_fmac_f32_e32 v230, v159, v65
	v_fmac_f32_e32 v231, v159, v69
	v_fmac_f32_e32 v232, v159, v73
	v_fmac_f32_e32 v233, v159, v77
	v_fmac_f32_e32 v230, v160, v66
	v_fmac_f32_e32 v231, v160, v70
	v_fmac_f32_e32 v232, v160, v74
	v_fmac_f32_e32 v233, v160, v78
	v_fmac_f32_e32 v230, v161, v67
	v_fmac_f32_e32 v231, v161, v71
	v_fmac_f32_e32 v232, v161, v75
	v_fmac_f32_e32 v233, v161, v79
	v_add_f32_dpp v230, v230, v230 quad_perm:[1,0,3,2] row_mask:0xf bank_mask:0xf
	v_add_f32_dpp v231, v231, v231 quad_perm:[1,0,3,2] row_mask:0xf bank_mask:0xf
	v_add_f32_dpp v232, v232, v232 quad_perm:[1,0,3,2] row_mask:0xf bank_mask:0xf
	v_add_f32_dpp v233, v233, v233 quad_perm:[1,0,3,2] row_mask:0xf bank_mask:0xf
	v_add_f32_dpp v230, v230, v230 quad_perm:[2,3,0,1] row_mask:0xf bank_mask:0xf
	v_add_f32_dpp v231, v231, v231 quad_perm:[2,3,0,1] row_mask:0xf bank_mask:0xf
	v_add_f32_dpp v232, v232, v232 quad_perm:[2,3,0,1] row_mask:0xf bank_mask:0xf
	v_add_f32_dpp v233, v233, v233 quad_perm:[2,3,0,1] row_mask:0xf bank_mask:0xf
	v_add_f32_dpp v230, v230, v230 row_half_mirror row_mask:0xf bank_mask:0xf
	v_add_f32_dpp v231, v231, v231 row_half_mirror row_mask:0xf bank_mask:0xf
	v_add_f32_dpp v232, v232, v232 row_half_mirror row_mask:0xf bank_mask:0xf
	v_add_f32_dpp v233, v233, v233 row_half_mirror row_mask:0xf bank_mask:0xf
	s_mov_b32 exec_lo, 0x10001
	s_mov_b32 exec_hi, 0x10001
	ds_write_b32 v238, v230 offset:192
	ds_write_b32 v238, v231 offset:208
	ds_write_b32 v238, v232 offset:224
	ds_write_b32 v238, v233 offset:240
	s_mov_b64 exec, -1
	ds_read2_b32 v[226:227], v237 offset0:48 offset1:52
	ds_read2_b32 v[228:229], v237 offset0:56 offset1:60
	s_waitcnt lgkmcnt(0)
; __device__ __forceinline__ void peer_token(const Params& P, int t, int lane, int* sidx, float* sval, const int* sid, const float* sgate, const unsigned* szero) {
;     ...
;         for (int T = 0; T < 8; ++T) {
;             if (T + 1 < 8) {
; #pragma unroll
;                 for (int hh = 0; hh < 2; ++hh) off2[hh] = (unsigned)sid[16 * (T + 1) + 8 * hh + (lr & 7)] * 512u + lofs;
; #pragma unroll
;                 for (int hh = 0; hh < 2; ++hh)
; #pragma unroll
;                     for (int st = 0; st < 4; ++st) abuf[(T + 1) & 1][hh][st] = *(const uint4*)(Ub + (off2[hh] + 128 * st));
;             }
; #pragma unroll
;             for (int hh = 0; hh < 2; ++hh) {
;                 f32x4 au = (f32x4){0.f, 0.f, 0.f, 0.f};
; #pragma unroll
;                 for (int st = 0; st < 4; ++st) {
;                     const uint4 a4 = abuf[T & 1][hh][st];
;                     const v8i Av = {(int)a4.x, (int)a4.y, (int)a4.z, (int)a4.w, 0, 0, 0, 0};
;                     au = __builtin_amdgcn_mfma_scale_f32_16x16x128_f8f6f4(Av, Bv[st], au, 4, 0, 0, 0x7f7f7f7f, 0, 0x7f7f7f7f);
;                 }
;                 if (owner) *(f32x4*)(sact + 16 * T + 8 * hh) = au;
;             }
	v_lshl_add_u32 v226, v226, 9, v144
	v_lshl_add_u32 v227, v227, 9, v144
	v_lshl_add_u32 v228, v228, 9, v144
	v_lshl_add_u32 v229, v229, 9, v144
	global_load_dwordx4 v[32:35], v226, s[10:11]
	global_load_dwordx4 v[36:39], v226, s[10:11] offset:256
	global_load_dwordx4 v[40:43], v227, s[10:11]
	global_load_dwordx4 v[44:47], v227, s[10:11] offset:256
	global_load_dwordx4 v[48:51], v228, s[10:11]
	global_load_dwordx4 v[52:55], v228, s[10:11] offset:256
	global_load_dwordx4 v[56:59], v229, s[10:11]
	global_load_dwordx4 v[60:63], v229, s[10:11] offset:256
	s_waitcnt vmcnt(8)
	v_mfma_scale_f32_16x16x128_f8f6f4 v[64:67], v[0:3], v[194:201], 0, v133, v133 op_sel_hi:[0,0,0] cbsz:4
	v_mfma_scale_f32_16x16x128_f8f6f4 v[64:67], v[4:7], v[202:209], v[64:67], v133, v133 op_sel_hi:[0,0,0] cbsz:4
	v_mfma_scale_f32_16x16x128_f8f6f4 v[68:71], v[8:11], v[194:201], 0, v133, v133 op_sel_hi:[0,0,0] cbsz:4
	v_mfma_scale_f32_16x16x128_f8f6f4 v[68:71], v[12:15], v[202:209], v[68:71], v133, v133 op_sel_hi:[0,0,0] cbsz:4
	v_mfma_scale_f32_16x16x128_f8f6f4 v[72:75], v[16:19], v[194:201], 0, v133, v133 op_sel_hi:[0,0,0] cbsz:4
	v_mfma_scale_f32_16x16x128_f8f6f4 v[72:75], v[20:23], v[202:209], v[72:75], v133, v133 op_sel_hi:[0,0,0] cbsz:4
	v_mfma_scale_f32_16x16x128_f8f6f4 v[76:79], v[24:27], v[194:201], 0, v133, v133 op_sel_hi:[0,0,0] cbsz:4
	v_mfma_scale_f32_16x16x128_f8f6f4 v[76:79], v[28:31], v[202:209], v[76:79], v133, v133 op_sel_hi:[0,0,0] cbsz:4
	s_nop 3
	v_mul_f32_e32 v230, v158, v80
	v_mul_f32_e32 v231, v158, v84
	v_mul_f32_e32 v232, v158, v88
	v_mul_f32_e32 v233, v158, v92
	v_fmac_f32_e32 v230, v159, v81
	v_fmac_f32_e32 v231, v159, v85
	v_fmac_f32_e32 v232, v159, v89
	v_fmac_f32_e32 v233, v159, v93
	v_fmac_f32_e32 v230, v160, v82
	v_fmac_f32_e32 v231, v160, v86
	v_fmac_f32_e32 v232, v160, v90
	v_fmac_f32_e32 v233, v160, v94
	v_fmac_f32_e32 v230, v161, v83
	v_fmac_f32_e32 v231, v161, v87
	v_fmac_f32_e32 v232, v161, v91
	v_fmac_f32_e32 v233, v161, v95
	v_add_f32_dpp v230, v230, v230 quad_perm:[1,0,3,2] row_mask:0xf bank_mask:0xf
	v_add_f32_dpp v231, v231, v231 quad_perm:[1,0,3,2] row_mask:0xf bank_mask:0xf
	v_add_f32_dpp v232, v232, v232 quad_perm:[1,0,3,2] row_mask:0xf bank_mask:0xf
	v_add_f32_dpp v233, v233, v233 quad_perm:[1,0,3,2] row_mask:0xf bank_mask:0xf
	v_add_f32_dpp v230, v230, v230 quad_perm:[2,3,0,1] row_mask:0xf bank_mask:0xf
	v_add_f32_dpp v231, v231, v231 quad_perm:[2,3,0,1] row_mask:0xf bank_mask:0xf
	v_add_f32_dpp v232, v232, v232 quad_perm:[2,3,0,1] row_mask:0xf bank_mask:0xf
	v_add_f32_dpp v233, v233, v233 quad_perm:[2,3,0,1] row_mask:0xf bank_mask:0xf
	v_add_f32_dpp v230, v230, v230 row_half_mirror row_mask:0xf bank_mask:0xf
	v_add_f32_dpp v231, v231, v231 row_half_mirror row_mask:0xf bank_mask:0xf
	v_add_f32_dpp v232, v232, v232 row_half_mirror row_mask:0xf bank_mask:0xf
	v_add_f32_dpp v233, v233, v233 row_half_mirror row_mask:0xf bank_mask:0xf
	s_mov_b32 exec_lo, 0x10001
	s_mov_b32 exec_hi, 0x10001
	ds_write_b32 v238, v230 offset:704
	ds_write_b32 v238, v231 offset:720
	ds_write_b32 v238, v232 offset:736
	ds_write_b32 v238, v233 offset:752
	s_mov_b64 exec, -1
	ds_read2_b32 v[96:97], v234 offset0:64 offset1:68
	ds_read2_b32 v[98:99], v234 offset0:72 offset1:76
	s_waitcnt lgkmcnt(0)
	v_lshl_add_u32 v96, v96, 9, v144
	v_lshl_add_u32 v97, v97, 9, v144
	v_lshl_add_u32 v98, v98, 9, v144
	v_lshl_add_u32 v99, v99, 9, v144
	global_load_dwordx4 v[0:3], v96, s[10:11]
	global_load_dwordx4 v[4:7], v96, s[10:11] offset:256
	global_load_dwordx4 v[8:11], v97, s[10:11]
	global_load_dwordx4 v[12:15], v97, s[10:11] offset:256
	global_load_dwordx4 v[16:19], v98, s[10:11]
	global_load_dwordx4 v[20:23], v98, s[10:11] offset:256
	global_load_dwordx4 v[24:27], v99, s[10:11]
	global_load_dwordx4 v[28:31], v99, s[10:11] offset:256
	s_waitcnt vmcnt(8)
	v_mfma_scale_f32_16x16x128_f8f6f4 v[80:83], v[32:35], v[210:217], 0, v133, v133 op_sel_hi:[0,0,0] cbsz:4
	v_mfma_scale_f32_16x16x128_f8f6f4 v[80:83], v[36:39], v[218:225], v[80:83], v133, v133 op_sel_hi:[0,0,0] cbsz:4
	v_mfma_scale_f32_16x16x128_f8f6f4 v[84:87], v[40:43], v[210:217], 0, v133, v133 op_sel_hi:[0,0,0] cbsz:4
	v_mfma_scale_f32_16x16x128_f8f6f4 v[84:87], v[44:47], v[218:225], v[84:87], v133, v133 op_sel_hi:[0,0,0] cbsz:4
	v_mfma_scale_f32_16x16x128_f8f6f4 v[88:91], v[48:51], v[210:217], 0, v133, v133 op_sel_hi:[0,0,0] cbsz:4
	v_mfma_scale_f32_16x16x128_f8f6f4 v[88:91], v[52:55], v[218:225], v[88:91], v133, v133 op_sel_hi:[0,0,0] cbsz:4
	v_mfma_scale_f32_16x16x128_f8f6f4 v[92:95], v[56:59], v[210:217], 0, v133, v133 op_sel_hi:[0,0,0] cbsz:4
	v_mfma_scale_f32_16x16x128_f8f6f4 v[92:95], v[60:63], v[218:225], v[92:95], v133, v133 op_sel_hi:[0,0,0] cbsz:4
	s_nop 3
	v_mul_f32_e32 v230, v158, v64
	v_mul_f32_e32 v231, v158, v68
	v_mul_f32_e32 v232, v158, v72
	v_mul_f32_e32 v233, v158, v76
	v_fmac_f32_e32 v230, v159, v65
	v_fmac_f32_e32 v231, v159, v69
	v_fmac_f32_e32 v232, v159, v73
	v_fmac_f32_e32 v233, v159, v77
	v_fmac_f32_e32 v230, v160, v66
	v_fmac_f32_e32 v231, v160, v70
	v_fmac_f32_e32 v232, v160, v74
	v_fmac_f32_e32 v233, v160, v78
	v_fmac_f32_e32 v230, v161, v67
	v_fmac_f32_e32 v231, v161, v71
	v_fmac_f32_e32 v232, v161, v75
	v_fmac_f32_e32 v233, v161, v79
	v_add_f32_dpp v230, v230, v230 quad_perm:[1,0,3,2] row_mask:0xf bank_mask:0xf
	v_add_f32_dpp v231, v231, v231 quad_perm:[1,0,3,2] row_mask:0xf bank_mask:0xf
	v_add_f32_dpp v232, v232, v232 quad_perm:[1,0,3,2] row_mask:0xf bank_mask:0xf
	v_add_f32_dpp v233, v233, v233 quad_perm:[1,0,3,2] row_mask:0xf bank_mask:0xf
	v_add_f32_dpp v230, v230, v230 quad_perm:[2,3,0,1] row_mask:0xf bank_mask:0xf
	v_add_f32_dpp v231, v231, v231 quad_perm:[2,3,0,1] row_mask:0xf bank_mask:0xf
	v_add_f32_dpp v232, v232, v232 quad_perm:[2,3,0,1] row_mask:0xf bank_mask:0xf
	v_add_f32_dpp v233, v233, v233 quad_perm:[2,3,0,1] row_mask:0xf bank_mask:0xf
	v_add_f32_dpp v230, v230, v230 row_half_mirror row_mask:0xf bank_mask:0xf
	v_add_f32_dpp v231, v231, v231 row_half_mirror row_mask:0xf bank_mask:0xf
	v_add_f32_dpp v232, v232, v232 row_half_mirror row_mask:0xf bank_mask:0xf
	v_add_f32_dpp v233, v233, v233 row_half_mirror row_mask:0xf bank_mask:0xf
	s_mov_b32 exec_lo, 0x10001
	s_mov_b32 exec_hi, 0x10001
	ds_write_b32 v238, v230 offset:1216
	ds_write_b32 v238, v231 offset:1232
	ds_write_b32 v238, v232 offset:1248
	ds_write_b32 v238, v233 offset:1264
	s_mov_b64 exec, -1
	ds_read2_b32 v[226:227], v235 offset0:64 offset1:68
	ds_read2_b32 v[228:229], v235 offset0:72 offset1:76
	s_waitcnt lgkmcnt(0)
; __device__ __forceinline__ void peer_token(const Params& P, int t, int lane, int* sidx, float* sval, const int* sid, const float* sgate, const unsigned* szero) {
;     ...
;         for (int T = 0; T < 8; ++T) {
;             if (T + 1 < 8) {
; #pragma unroll
;                 for (int hh = 0; hh < 2; ++hh) off2[hh] = (unsigned)sid[16 * (T + 1) + 8 * hh + (lr & 7)] * 512u + lofs;
; #pragma unroll
;                 for (int hh = 0; hh < 2; ++hh)
; #pragma unroll
;                     for (int st = 0; st < 4; ++st) abuf[(T + 1) & 1][hh][st] = *(const uint4*)(Ub + (off2[hh] + 128 * st));
;             }
; #pragma unroll
;             for (int hh = 0; hh < 2; ++hh) {
;                 f32x4 au = (f32x4){0.f, 0.f, 0.f, 0.f};
; #pragma unroll
;                 for (int st = 0; st < 4; ++st) {
;                     const uint4 a4 = abuf[T & 1][hh][st];
;                     const v8i Av = {(int)a4.x, (int)a4.y, (int)a4.z, (int)a4.w, 0, 0, 0, 0};
;                     au = __builtin_amdgcn_mfma_scale_f32_16x16x128_f8f6f4(Av, Bv[st], au, 4, 0, 0, 0x7f7f7f7f, 0, 0x7f7f7f7f);
;                 }
;                 if (owner) *(f32x4*)(sact + 16 * T + 8 * hh) = au;
;             }
	v_lshl_add_u32 v226, v226, 9, v144
	v_lshl_add_u32 v227, v227, 9, v144
	v_lshl_add_u32 v228, v228, 9, v144
	v_lshl_add_u32 v229, v229, 9, v144
	global_load_dwordx4 v[32:35], v226, s[10:11]
	global_load_dwordx4 v[36:39], v226, s[10:11] offset:256
	global_load_dwordx4 v[40:43], v227, s[10:11]
	global_load_dwordx4 v[44:47], v227, s[10:11] offset:256
	global_load_dwordx4 v[48:51], v228, s[10:11]
	global_load_dwordx4 v[52:55], v228, s[10:11] offset:256
	global_load_dwordx4 v[56:59], v229, s[10:11]
	global_load_dwordx4 v[60:63], v229, s[10:11] offset:256
	s_waitcnt vmcnt(8)
	v_mfma_scale_f32_16x16x128_f8f6f4 v[64:67], v[0:3], v[162:169], 0, v133, v133 op_sel_hi:[0,0,0] cbsz:4
	v_mfma_scale_f32_16x16x128_f8f6f4 v[64:67], v[4:7], v[170:177], v[64:67], v133, v133 op_sel_hi:[0,0,0] cbsz:4
	v_mfma_scale_f32_16x16x128_f8f6f4 v[68:71], v[8:11], v[162:169], 0, v133, v133 op_sel_hi:[0,0,0] cbsz:4
	v_mfma_scale_f32_16x16x128_f8f6f4 v[68:71], v[12:15], v[170:177], v[68:71], v133, v133 op_sel_hi:[0,0,0] cbsz:4
	v_mfma_scale_f32_16x16x128_f8f6f4 v[72:75], v[16:19], v[162:169], 0, v133, v133 op_sel_hi:[0,0,0] cbsz:4
	v_mfma_scale_f32_16x16x128_f8f6f4 v[72:75], v[20:23], v[170:177], v[72:75], v133, v133 op_sel_hi:[0,0,0] cbsz:4
	v_mfma_scale_f32_16x16x128_f8f6f4 v[76:79], v[24:27], v[162:169], 0, v133, v133 op_sel_hi:[0,0,0] cbsz:4
	v_mfma_scale_f32_16x16x128_f8f6f4 v[76:79], v[28:31], v[170:177], v[76:79], v133, v133 op_sel_hi:[0,0,0] cbsz:4
	s_nop 3
	v_mul_f32_e32 v230, v158, v80
	v_mul_f32_e32 v231, v158, v84
	v_mul_f32_e32 v232, v158, v88
	v_mul_f32_e32 v233, v158, v92
	v_fmac_f32_e32 v230, v159, v81
	v_fmac_f32_e32 v231, v159, v85
	v_fmac_f32_e32 v232, v159, v89
	v_fmac_f32_e32 v233, v159, v93
	v_fmac_f32_e32 v230, v160, v82
	v_fmac_f32_e32 v231, v160, v86
	v_fmac_f32_e32 v232, v160, v90
	v_fmac_f32_e32 v233, v160, v94
	v_fmac_f32_e32 v230, v161, v83
	v_fmac_f32_e32 v231, v161, v87
	v_fmac_f32_e32 v232, v161, v91
	v_fmac_f32_e32 v233, v161, v95
	v_add_f32_dpp v230, v230, v230 quad_perm:[1,0,3,2] row_mask:0xf bank_mask:0xf
	v_add_f32_dpp v231, v231, v231 quad_perm:[1,0,3,2] row_mask:0xf bank_mask:0xf
	v_add_f32_dpp v232, v232, v232 quad_perm:[1,0,3,2] row_mask:0xf bank_mask:0xf
	v_add_f32_dpp v233, v233, v233 quad_perm:[1,0,3,2] row_mask:0xf bank_mask:0xf
	v_add_f32_dpp v230, v230, v230 quad_perm:[2,3,0,1] row_mask:0xf bank_mask:0xf
	v_add_f32_dpp v231, v231, v231 quad_perm:[2,3,0,1] row_mask:0xf bank_mask:0xf
	v_add_f32_dpp v232, v232, v232 quad_perm:[2,3,0,1] row_mask:0xf bank_mask:0xf
	v_add_f32_dpp v233, v233, v233 quad_perm:[2,3,0,1] row_mask:0xf bank_mask:0xf
	v_add_f32_dpp v230, v230, v230 row_half_mirror row_mask:0xf bank_mask:0xf
	v_add_f32_dpp v231, v231, v231 row_half_mirror row_mask:0xf bank_mask:0xf
	v_add_f32_dpp v232, v232, v232 row_half_mirror row_mask:0xf bank_mask:0xf
	v_add_f32_dpp v233, v233, v233 row_half_mirror row_mask:0xf bank_mask:0xf
	s_mov_b32 exec_lo, 0x10001
	s_mov_b32 exec_hi, 0x10001
	ds_write_b32 v238, v230 offset:1728
	ds_write_b32 v238, v231 offset:1744
	ds_write_b32 v238, v232 offset:1760
	ds_write_b32 v238, v233 offset:1776
	s_mov_b64 exec, -1
	ds_read2_b32 v[96:97], v236 offset0:64 offset1:68
	ds_read2_b32 v[98:99], v236 offset0:72 offset1:76
	s_waitcnt lgkmcnt(0)
	v_lshl_add_u32 v96, v96, 9, v144
	v_lshl_add_u32 v97, v97, 9, v144
	v_lshl_add_u32 v98, v98, 9, v144
	v_lshl_add_u32 v99, v99, 9, v144
	global_load_dwordx4 v[0:3], v96, s[10:11]
	global_load_dwordx4 v[4:7], v96, s[10:11] offset:256
	global_load_dwordx4 v[8:11], v97, s[10:11]
	global_load_dwordx4 v[12:15], v97, s[10:11] offset:256
	global_load_dwordx4 v[16:19], v98, s[10:11]
	global_load_dwordx4 v[20:23], v98, s[10:11] offset:256
	global_load_dwordx4 v[24:27], v99, s[10:11]
	global_load_dwordx4 v[28:31], v99, s[10:11] offset:256
	s_waitcnt vmcnt(8)
	v_mfma_scale_f32_16x16x128_f8f6f4 v[80:83], v[32:35], v[178:185], 0, v133, v133 op_sel_hi:[0,0,0] cbsz:4
	v_mfma_scale_f32_16x16x128_f8f6f4 v[80:83], v[36:39], v[186:193], v[80:83], v133, v133 op_sel_hi:[0,0,0] cbsz:4
	v_mfma_scale_f32_16x16x128_f8f6f4 v[84:87], v[40:43], v[178:185], 0, v133, v133 op_sel_hi:[0,0,0] cbsz:4
	v_mfma_scale_f32_16x16x128_f8f6f4 v[84:87], v[44:47], v[186:193], v[84:87], v133, v133 op_sel_hi:[0,0,0] cbsz:4
	v_mfma_scale_f32_16x16x128_f8f6f4 v[88:91], v[48:51], v[178:185], 0, v133, v133 op_sel_hi:[0,0,0] cbsz:4
	v_mfma_scale_f32_16x16x128_f8f6f4 v[88:91], v[52:55], v[186:193], v[88:91], v133, v133 op_sel_hi:[0,0,0] cbsz:4
	v_mfma_scale_f32_16x16x128_f8f6f4 v[92:95], v[56:59], v[178:185], 0, v133, v133 op_sel_hi:[0,0,0] cbsz:4
	v_mfma_scale_f32_16x16x128_f8f6f4 v[92:95], v[60:63], v[186:193], v[92:95], v133, v133 op_sel_hi:[0,0,0] cbsz:4
	s_nop 3
	v_mul_f32_e32 v230, v158, v64
	v_mul_f32_e32 v231, v158, v68
	v_mul_f32_e32 v232, v158, v72
	v_mul_f32_e32 v233, v158, v76
	v_fmac_f32_e32 v230, v159, v65
	v_fmac_f32_e32 v231, v159, v69
	v_fmac_f32_e32 v232, v159, v73
	v_fmac_f32_e32 v233, v159, v77
	v_fmac_f32_e32 v230, v160, v66
	v_fmac_f32_e32 v231, v160, v70
	v_fmac_f32_e32 v232, v160, v74
	v_fmac_f32_e32 v233, v160, v78
	v_fmac_f32_e32 v230, v161, v67
	v_fmac_f32_e32 v231, v161, v71
	v_fmac_f32_e32 v232, v161, v75
	v_fmac_f32_e32 v233, v161, v79
	v_add_f32_dpp v230, v230, v230 quad_perm:[1,0,3,2] row_mask:0xf bank_mask:0xf
	v_add_f32_dpp v231, v231, v231 quad_perm:[1,0,3,2] row_mask:0xf bank_mask:0xf
	v_add_f32_dpp v232, v232, v232 quad_perm:[1,0,3,2] row_mask:0xf bank_mask:0xf
	v_add_f32_dpp v233, v233, v233 quad_perm:[1,0,3,2] row_mask:0xf bank_mask:0xf
	v_add_f32_dpp v230, v230, v230 quad_perm:[2,3,0,1] row_mask:0xf bank_mask:0xf
	v_add_f32_dpp v231, v231, v231 quad_perm:[2,3,0,1] row_mask:0xf bank_mask:0xf
	v_add_f32_dpp v232, v232, v232 quad_perm:[2,3,0,1] row_mask:0xf bank_mask:0xf
	v_add_f32_dpp v233, v233, v233 quad_perm:[2,3,0,1] row_mask:0xf bank_mask:0xf
	v_add_f32_dpp v230, v230, v230 row_half_mirror row_mask:0xf bank_mask:0xf
	v_add_f32_dpp v231, v231, v231 row_half_mirror row_mask:0xf bank_mask:0xf
	v_add_f32_dpp v232, v232, v232 row_half_mirror row_mask:0xf bank_mask:0xf
	v_add_f32_dpp v233, v233, v233 row_half_mirror row_mask:0xf bank_mask:0xf
	s_mov_b32 exec_lo, 0x10001
	s_mov_b32 exec_hi, 0x10001
	ds_write_b32 v238, v230 offset:256
	ds_write_b32 v238, v231 offset:272
	ds_write_b32 v238, v232 offset:288
	ds_write_b32 v238, v233 offset:304
	s_mov_b64 exec, -1
	ds_read2_b32 v[226:227], v237 offset0:64 offset1:68
	ds_read2_b32 v[228:229], v237 offset0:72 offset1:76
	s_waitcnt lgkmcnt(0)
; __device__ __forceinline__ void peer_token(const Params& P, int t, int lane, int* sidx, float* sval, const int* sid, const float* sgate, const unsigned* szero) {
;     ...
;         for (int T = 0; T < 8; ++T) {
;             if (T + 1 < 8) {
; #pragma unroll
;                 for (int hh = 0; hh < 2; ++hh) off2[hh] = (unsigned)sid[16 * (T + 1) + 8 * hh + (lr & 7)] * 512u + lofs;
; #pragma unroll
;                 for (int hh = 0; hh < 2; ++hh)
; #pragma unroll
;                     for (int st = 0; st < 4; ++st) abuf[(T + 1) & 1][hh][st] = *(const uint4*)(Ub + (off2[hh] + 128 * st));
;             }
; #pragma unroll
;             for (int hh = 0; hh < 2; ++hh) {
;                 f32x4 au = (f32x4){0.f, 0.f, 0.f, 0.f};
; #pragma unroll
;                 for (int st = 0; st < 4; ++st) {
;                     const uint4 a4 = abuf[T & 1][hh][st];
;                     const v8i Av = {(int)a4.x, (int)a4.y, (int)a4.z, (int)a4.w, 0, 0, 0, 0};
;                     au = __builtin_amdgcn_mfma_scale_f32_16x16x128_f8f6f4(Av, Bv[st], au, 4, 0, 0, 0x7f7f7f7f, 0, 0x7f7f7f7f);
;                 }
;                 if (owner) *(f32x4*)(sact + 16 * T + 8 * hh) = au;
;             }
	v_lshl_add_u32 v226, v226, 9, v144
	v_lshl_add_u32 v227, v227, 9, v144
	v_lshl_add_u32 v228, v228, 9, v144
	v_lshl_add_u32 v229, v229, 9, v144
	global_load_dwordx4 v[32:35], v226, s[10:11]
	global_load_dwordx4 v[36:39], v226, s[10:11] offset:256
	global_load_dwordx4 v[40:43], v227, s[10:11]
	global_load_dwordx4 v[44:47], v227, s[10:11] offset:256
	global_load_dwordx4 v[48:51], v228, s[10:11]
	global_load_dwordx4 v[52:55], v228, s[10:11] offset:256
	global_load_dwordx4 v[56:59], v229, s[10:11]
	global_load_dwordx4 v[60:63], v229, s[10:11] offset:256
	s_waitcnt vmcnt(8)
	v_mfma_scale_f32_16x16x128_f8f6f4 v[64:67], v[0:3], v[194:201], 0, v133, v133 op_sel_hi:[0,0,0] cbsz:4
	v_mfma_scale_f32_16x16x128_f8f6f4 v[64:67], v[4:7], v[202:209], v[64:67], v133, v133 op_sel_hi:[0,0,0] cbsz:4
	v_mfma_scale_f32_16x16x128_f8f6f4 v[68:71], v[8:11], v[194:201], 0, v133, v133 op_sel_hi:[0,0,0] cbsz:4
	v_mfma_scale_f32_16x16x128_f8f6f4 v[68:71], v[12:15], v[202:209], v[68:71], v133, v133 op_sel_hi:[0,0,0] cbsz:4
	v_mfma_scale_f32_16x16x128_f8f6f4 v[72:75], v[16:19], v[194:201], 0, v133, v133 op_sel_hi:[0,0,0] cbsz:4
	v_mfma_scale_f32_16x16x128_f8f6f4 v[72:75], v[20:23], v[202:209], v[72:75], v133, v133 op_sel_hi:[0,0,0] cbsz:4
	v_mfma_scale_f32_16x16x128_f8f6f4 v[76:79], v[24:27], v[194:201], 0, v133, v133 op_sel_hi:[0,0,0] cbsz:4
	v_mfma_scale_f32_16x16x128_f8f6f4 v[76:79], v[28:31], v[202:209], v[76:79], v133, v133 op_sel_hi:[0,0,0] cbsz:4
	s_nop 3
	v_mul_f32_e32 v230, v158, v80
	v_mul_f32_e32 v231, v158, v84
	v_mul_f32_e32 v232, v158, v88
	v_mul_f32_e32 v233, v158, v92
	v_fmac_f32_e32 v230, v159, v81
	v_fmac_f32_e32 v231, v159, v85
	v_fmac_f32_e32 v232, v159, v89
	v_fmac_f32_e32 v233, v159, v93
	v_fmac_f32_e32 v230, v160, v82
	v_fmac_f32_e32 v231, v160, v86
	v_fmac_f32_e32 v232, v160, v90
	v_fmac_f32_e32 v233, v160, v94
	v_fmac_f32_e32 v230, v161, v83
	v_fmac_f32_e32 v231, v161, v87
	v_fmac_f32_e32 v232, v161, v91
	v_fmac_f32_e32 v233, v161, v95
	v_add_f32_dpp v230, v230, v230 quad_perm:[1,0,3,2] row_mask:0xf bank_mask:0xf
	v_add_f32_dpp v231, v231, v231 quad_perm:[1,0,3,2] row_mask:0xf bank_mask:0xf
	v_add_f32_dpp v232, v232, v232 quad_perm:[1,0,3,2] row_mask:0xf bank_mask:0xf
	v_add_f32_dpp v233, v233, v233 quad_perm:[1,0,3,2] row_mask:0xf bank_mask:0xf
	v_add_f32_dpp v230, v230, v230 quad_perm:[2,3,0,1] row_mask:0xf bank_mask:0xf
	v_add_f32_dpp v231, v231, v231 quad_perm:[2,3,0,1] row_mask:0xf bank_mask:0xf
	v_add_f32_dpp v232, v232, v232 quad_perm:[2,3,0,1] row_mask:0xf bank_mask:0xf
	v_add_f32_dpp v233, v233, v233 quad_perm:[2,3,0,1] row_mask:0xf bank_mask:0xf
	v_add_f32_dpp v230, v230, v230 row_half_mirror row_mask:0xf bank_mask:0xf
	v_add_f32_dpp v231, v231, v231 row_half_mirror row_mask:0xf bank_mask:0xf
	v_add_f32_dpp v232, v232, v232 row_half_mirror row_mask:0xf bank_mask:0xf
	v_add_f32_dpp v233, v233, v233 row_half_mirror row_mask:0xf bank_mask:0xf
	s_mov_b32 exec_lo, 0x10001
	s_mov_b32 exec_hi, 0x10001
	ds_write_b32 v238, v230 offset:768
	ds_write_b32 v238, v231 offset:784
	ds_write_b32 v238, v232 offset:800
	ds_write_b32 v238, v233 offset:816
	s_mov_b64 exec, -1
	ds_read2_b32 v[96:97], v234 offset0:80 offset1:84
	ds_read2_b32 v[98:99], v234 offset0:88 offset1:92
	s_waitcnt lgkmcnt(0)
	v_lshl_add_u32 v96, v96, 9, v144
	v_lshl_add_u32 v97, v97, 9, v144
	v_lshl_add_u32 v98, v98, 9, v144
	v_lshl_add_u32 v99, v99, 9, v144
	global_load_dwordx4 v[0:3], v96, s[10:11]
	global_load_dwordx4 v[4:7], v96, s[10:11] offset:256
	global_load_dwordx4 v[8:11], v97, s[10:11]
	global_load_dwordx4 v[12:15], v97, s[10:11] offset:256
	global_load_dwordx4 v[16:19], v98, s[10:11]
	global_load_dwordx4 v[20:23], v98, s[10:11] offset:256
	global_load_dwordx4 v[24:27], v99, s[10:11]
	global_load_dwordx4 v[28:31], v99, s[10:11] offset:256
	s_waitcnt vmcnt(8)
	v_mfma_scale_f32_16x16x128_f8f6f4 v[80:83], v[32:35], v[210:217], 0, v133, v133 op_sel_hi:[0,0,0] cbsz:4
	v_mfma_scale_f32_16x16x128_f8f6f4 v[80:83], v[36:39], v[218:225], v[80:83], v133, v133 op_sel_hi:[0,0,0] cbsz:4
	v_mfma_scale_f32_16x16x128_f8f6f4 v[84:87], v[40:43], v[210:217], 0, v133, v133 op_sel_hi:[0,0,0] cbsz:4
	v_mfma_scale_f32_16x16x128_f8f6f4 v[84:87], v[44:47], v[218:225], v[84:87], v133, v133 op_sel_hi:[0,0,0] cbsz:4
	v_mfma_scale_f32_16x16x128_f8f6f4 v[88:91], v[48:51], v[210:217], 0, v133, v133 op_sel_hi:[0,0,0] cbsz:4
	v_mfma_scale_f32_16x16x128_f8f6f4 v[88:91], v[52:55], v[218:225], v[88:91], v133, v133 op_sel_hi:[0,0,0] cbsz:4
	v_mfma_scale_f32_16x16x128_f8f6f4 v[92:95], v[56:59], v[210:217], 0, v133, v133 op_sel_hi:[0,0,0] cbsz:4
	v_mfma_scale_f32_16x16x128_f8f6f4 v[92:95], v[60:63], v[218:225], v[92:95], v133, v133 op_sel_hi:[0,0,0] cbsz:4
	s_nop 3
	v_mul_f32_e32 v230, v158, v64
	v_mul_f32_e32 v231, v158, v68
	v_mul_f32_e32 v232, v158, v72
	v_mul_f32_e32 v233, v158, v76
	v_fmac_f32_e32 v230, v159, v65
	v_fmac_f32_e32 v231, v159, v69
	v_fmac_f32_e32 v232, v159, v73
	v_fmac_f32_e32 v233, v159, v77
	v_fmac_f32_e32 v230, v160, v66
	v_fmac_f32_e32 v231, v160, v70
	v_fmac_f32_e32 v232, v160, v74
	v_fmac_f32_e32 v233, v160, v78
	v_fmac_f32_e32 v230, v161, v67
	v_fmac_f32_e32 v231, v161, v71
	v_fmac_f32_e32 v232, v161, v75
	v_fmac_f32_e32 v233, v161, v79
	v_add_f32_dpp v230, v230, v230 quad_perm:[1,0,3,2] row_mask:0xf bank_mask:0xf
	v_add_f32_dpp v231, v231, v231 quad_perm:[1,0,3,2] row_mask:0xf bank_mask:0xf
	v_add_f32_dpp v232, v232, v232 quad_perm:[1,0,3,2] row_mask:0xf bank_mask:0xf
	v_add_f32_dpp v233, v233, v233 quad_perm:[1,0,3,2] row_mask:0xf bank_mask:0xf
	v_add_f32_dpp v230, v230, v230 quad_perm:[2,3,0,1] row_mask:0xf bank_mask:0xf
	v_add_f32_dpp v231, v231, v231 quad_perm:[2,3,0,1] row_mask:0xf bank_mask:0xf
	v_add_f32_dpp v232, v232, v232 quad_perm:[2,3,0,1] row_mask:0xf bank_mask:0xf
	v_add_f32_dpp v233, v233, v233 quad_perm:[2,3,0,1] row_mask:0xf bank_mask:0xf
	v_add_f32_dpp v230, v230, v230 row_half_mirror row_mask:0xf bank_mask:0xf
	v_add_f32_dpp v231, v231, v231 row_half_mirror row_mask:0xf bank_mask:0xf
	v_add_f32_dpp v232, v232, v232 row_half_mirror row_mask:0xf bank_mask:0xf
	v_add_f32_dpp v233, v233, v233 row_half_mirror row_mask:0xf bank_mask:0xf
	s_mov_b32 exec_lo, 0x10001
	s_mov_b32 exec_hi, 0x10001
	ds_write_b32 v238, v230 offset:1280
	ds_write_b32 v238, v231 offset:1296
	ds_write_b32 v238, v232 offset:1312
	ds_write_b32 v238, v233 offset:1328
	s_mov_b64 exec, -1
	ds_read2_b32 v[226:227], v235 offset0:80 offset1:84
	ds_read2_b32 v[228:229], v235 offset0:88 offset1:92
	s_waitcnt lgkmcnt(0)
; __device__ __forceinline__ void peer_token(const Params& P, int t, int lane, int* sidx, float* sval, const int* sid, const float* sgate, const unsigned* szero) {
;     ...
;         for (int T = 0; T < 8; ++T) {
;             if (T + 1 < 8) {
; #pragma unroll
;                 for (int hh = 0; hh < 2; ++hh) off2[hh] = (unsigned)sid[16 * (T + 1) + 8 * hh + (lr & 7)] * 512u + lofs;
; #pragma unroll
;                 for (int hh = 0; hh < 2; ++hh)
; #pragma unroll
;                     for (int st = 0; st < 4; ++st) abuf[(T + 1) & 1][hh][st] = *(const uint4*)(Ub + (off2[hh] + 128 * st));
;             }
; #pragma unroll
;             for (int hh = 0; hh < 2; ++hh) {
;                 f32x4 au = (f32x4){0.f, 0.f, 0.f, 0.f};
; #pragma unroll
;                 for (int st = 0; st < 4; ++st) {
;                     const uint4 a4 = abuf[T & 1][hh][st];
;                     const v8i Av = {(int)a4.x, (int)a4.y, (int)a4.z, (int)a4.w, 0, 0, 0, 0};
;                     au = __builtin_amdgcn_mfma_scale_f32_16x16x128_f8f6f4(Av, Bv[st], au, 4, 0, 0, 0x7f7f7f7f, 0, 0x7f7f7f7f);
;                 }
;                 if (owner) *(f32x4*)(sact + 16 * T + 8 * hh) = au;
;             }
	v_lshl_add_u32 v226, v226, 9, v144
	v_lshl_add_u32 v227, v227, 9, v144
	v_lshl_add_u32 v228, v228, 9, v144
	v_lshl_add_u32 v229, v229, 9, v144
	global_load_dwordx4 v[32:35], v226, s[10:11]
	global_load_dwordx4 v[36:39], v226, s[10:11] offset:256
	global_load_dwordx4 v[40:43], v227, s[10:11]
	global_load_dwordx4 v[44:47], v227, s[10:11] offset:256
	global_load_dwordx4 v[48:51], v228, s[10:11]
	global_load_dwordx4 v[52:55], v228, s[10:11] offset:256
	global_load_dwordx4 v[56:59], v229, s[10:11]
	global_load_dwordx4 v[60:63], v229, s[10:11] offset:256
	s_waitcnt vmcnt(8)
	v_mfma_scale_f32_16x16x128_f8f6f4 v[64:67], v[0:3], v[162:169], 0, v133, v133 op_sel_hi:[0,0,0] cbsz:4
	v_mfma_scale_f32_16x16x128_f8f6f4 v[64:67], v[4:7], v[170:177], v[64:67], v133, v133 op_sel_hi:[0,0,0] cbsz:4
	v_mfma_scale_f32_16x16x128_f8f6f4 v[68:71], v[8:11], v[162:169], 0, v133, v133 op_sel_hi:[0,0,0] cbsz:4
	v_mfma_scale_f32_16x16x128_f8f6f4 v[68:71], v[12:15], v[170:177], v[68:71], v133, v133 op_sel_hi:[0,0,0] cbsz:4
	v_mfma_scale_f32_16x16x128_f8f6f4 v[72:75], v[16:19], v[162:169], 0, v133, v133 op_sel_hi:[0,0,0] cbsz:4
	v_mfma_scale_f32_16x16x128_f8f6f4 v[72:75], v[20:23], v[170:177], v[72:75], v133, v133 op_sel_hi:[0,0,0] cbsz:4
	v_mfma_scale_f32_16x16x128_f8f6f4 v[76:79], v[24:27], v[162:169], 0, v133, v133 op_sel_hi:[0,0,0] cbsz:4
	v_mfma_scale_f32_16x16x128_f8f6f4 v[76:79], v[28:31], v[170:177], v[76:79], v133, v133 op_sel_hi:[0,0,0] cbsz:4
	s_nop 3
	v_mul_f32_e32 v230, v158, v80
	v_mul_f32_e32 v231, v158, v84
	v_mul_f32_e32 v232, v158, v88
	v_mul_f32_e32 v233, v158, v92
	v_fmac_f32_e32 v230, v159, v81
	v_fmac_f32_e32 v231, v159, v85
	v_fmac_f32_e32 v232, v159, v89
	v_fmac_f32_e32 v233, v159, v93
	v_fmac_f32_e32 v230, v160, v82
	v_fmac_f32_e32 v231, v160, v86
	v_fmac_f32_e32 v232, v160, v90
	v_fmac_f32_e32 v233, v160, v94
	v_fmac_f32_e32 v230, v161, v83
	v_fmac_f32_e32 v231, v161, v87
	v_fmac_f32_e32 v232, v161, v91
	v_fmac_f32_e32 v233, v161, v95
	v_add_f32_dpp v230, v230, v230 quad_perm:[1,0,3,2] row_mask:0xf bank_mask:0xf
	v_add_f32_dpp v231, v231, v231 quad_perm:[1,0,3,2] row_mask:0xf bank_mask:0xf
	v_add_f32_dpp v232, v232, v232 quad_perm:[1,0,3,2] row_mask:0xf bank_mask:0xf
	v_add_f32_dpp v233, v233, v233 quad_perm:[1,0,3,2] row_mask:0xf bank_mask:0xf
	v_add_f32_dpp v230, v230, v230 quad_perm:[2,3,0,1] row_mask:0xf bank_mask:0xf
	v_add_f32_dpp v231, v231, v231 quad_perm:[2,3,0,1] row_mask:0xf bank_mask:0xf
	v_add_f32_dpp v232, v232, v232 quad_perm:[2,3,0,1] row_mask:0xf bank_mask:0xf
	v_add_f32_dpp v233, v233, v233 quad_perm:[2,3,0,1] row_mask:0xf bank_mask:0xf
	v_add_f32_dpp v230, v230, v230 row_half_mirror row_mask:0xf bank_mask:0xf
	v_add_f32_dpp v231, v231, v231 row_half_mirror row_mask:0xf bank_mask:0xf
	v_add_f32_dpp v232, v232, v232 row_half_mirror row_mask:0xf bank_mask:0xf
	v_add_f32_dpp v233, v233, v233 row_half_mirror row_mask:0xf bank_mask:0xf
	s_mov_b32 exec_lo, 0x10001
	s_mov_b32 exec_hi, 0x10001
	ds_write_b32 v238, v230 offset:1792
	ds_write_b32 v238, v231 offset:1808
	ds_write_b32 v238, v232 offset:1824
	ds_write_b32 v238, v233 offset:1840
	s_mov_b64 exec, -1
	ds_read2_b32 v[96:97], v236 offset0:80 offset1:84
	ds_read2_b32 v[98:99], v236 offset0:88 offset1:92
	s_waitcnt lgkmcnt(0)
	v_lshl_add_u32 v96, v96, 9, v144
	v_lshl_add_u32 v97, v97, 9, v144
	v_lshl_add_u32 v98, v98, 9, v144
	v_lshl_add_u32 v99, v99, 9, v144
	global_load_dwordx4 v[0:3], v96, s[10:11]
	global_load_dwordx4 v[4:7], v96, s[10:11] offset:256
	global_load_dwordx4 v[8:11], v97, s[10:11]
	global_load_dwordx4 v[12:15], v97, s[10:11] offset:256
	global_load_dwordx4 v[16:19], v98, s[10:11]
	global_load_dwordx4 v[20:23], v98, s[10:11] offset:256
	global_load_dwordx4 v[24:27], v99, s[10:11]
	global_load_dwordx4 v[28:31], v99, s[10:11] offset:256
	s_waitcnt vmcnt(8)
	v_mfma_scale_f32_16x16x128_f8f6f4 v[80:83], v[32:35], v[178:185], 0, v133, v133 op_sel_hi:[0,0,0] cbsz:4
	v_mfma_scale_f32_16x16x128_f8f6f4 v[80:83], v[36:39], v[186:193], v[80:83], v133, v133 op_sel_hi:[0,0,0] cbsz:4
	v_mfma_scale_f32_16x16x128_f8f6f4 v[84:87], v[40:43], v[178:185], 0, v133, v133 op_sel_hi:[0,0,0] cbsz:4
	v_mfma_scale_f32_16x16x128_f8f6f4 v[84:87], v[44:47], v[186:193], v[84:87], v133, v133 op_sel_hi:[0,0,0] cbsz:4
	v_mfma_scale_f32_16x16x128_f8f6f4 v[88:91], v[48:51], v[178:185], 0, v133, v133 op_sel_hi:[0,0,0] cbsz:4
	v_mfma_scale_f32_16x16x128_f8f6f4 v[88:91], v[52:55], v[186:193], v[88:91], v133, v133 op_sel_hi:[0,0,0] cbsz:4
	v_mfma_scale_f32_16x16x128_f8f6f4 v[92:95], v[56:59], v[178:185], 0, v133, v133 op_sel_hi:[0,0,0] cbsz:4
	v_mfma_scale_f32_16x16x128_f8f6f4 v[92:95], v[60:63], v[186:193], v[92:95], v133, v133 op_sel_hi:[0,0,0] cbsz:4
	s_nop 3
	v_mul_f32_e32 v230, v158, v64
	v_mul_f32_e32 v231, v158, v68
	v_mul_f32_e32 v232, v158, v72
	v_mul_f32_e32 v233, v158, v76
	v_fmac_f32_e32 v230, v159, v65
	v_fmac_f32_e32 v231, v159, v69
	v_fmac_f32_e32 v232, v159, v73
	v_fmac_f32_e32 v233, v159, v77
	v_fmac_f32_e32 v230, v160, v66
	v_fmac_f32_e32 v231, v160, v70
	v_fmac_f32_e32 v232, v160, v74
	v_fmac_f32_e32 v233, v160, v78
	v_fmac_f32_e32 v230, v161, v67
	v_fmac_f32_e32 v231, v161, v71
	v_fmac_f32_e32 v232, v161, v75
	v_fmac_f32_e32 v233, v161, v79
	v_add_f32_dpp v230, v230, v230 quad_perm:[1,0,3,2] row_mask:0xf bank_mask:0xf
	v_add_f32_dpp v231, v231, v231 quad_perm:[1,0,3,2] row_mask:0xf bank_mask:0xf
	v_add_f32_dpp v232, v232, v232 quad_perm:[1,0,3,2] row_mask:0xf bank_mask:0xf
	v_add_f32_dpp v233, v233, v233 quad_perm:[1,0,3,2] row_mask:0xf bank_mask:0xf
	v_add_f32_dpp v230, v230, v230 quad_perm:[2,3,0,1] row_mask:0xf bank_mask:0xf
	v_add_f32_dpp v231, v231, v231 quad_perm:[2,3,0,1] row_mask:0xf bank_mask:0xf
	v_add_f32_dpp v232, v232, v232 quad_perm:[2,3,0,1] row_mask:0xf bank_mask:0xf
	v_add_f32_dpp v233, v233, v233 quad_perm:[2,3,0,1] row_mask:0xf bank_mask:0xf
	v_add_f32_dpp v230, v230, v230 row_half_mirror row_mask:0xf bank_mask:0xf
	v_add_f32_dpp v231, v231, v231 row_half_mirror row_mask:0xf bank_mask:0xf
	v_add_f32_dpp v232, v232, v232 row_half_mirror row_mask:0xf bank_mask:0xf
	v_add_f32_dpp v233, v233, v233 row_half_mirror row_mask:0xf bank_mask:0xf
	s_mov_b32 exec_lo, 0x10001
	s_mov_b32 exec_hi, 0x10001
	ds_write_b32 v238, v230 offset:320
	ds_write_b32 v238, v231 offset:336
	ds_write_b32 v238, v232 offset:352
	ds_write_b32 v238, v233 offset:368
	s_mov_b64 exec, -1
	ds_read2_b32 v[226:227], v237 offset0:80 offset1:84
	ds_read2_b32 v[228:229], v237 offset0:88 offset1:92
	s_waitcnt lgkmcnt(0)
; __device__ __forceinline__ void peer_token(const Params& P, int t, int lane, int* sidx, float* sval, const int* sid, const float* sgate, const unsigned* szero) {
;     ...
;         for (int T = 0; T < 8; ++T) {
;             if (T + 1 < 8) {
; #pragma unroll
;                 for (int hh = 0; hh < 2; ++hh) off2[hh] = (unsigned)sid[16 * (T + 1) + 8 * hh + (lr & 7)] * 512u + lofs;
; #pragma unroll
;                 for (int hh = 0; hh < 2; ++hh)
; #pragma unroll
;                     for (int st = 0; st < 4; ++st) abuf[(T + 1) & 1][hh][st] = *(const uint4*)(Ub + (off2[hh] + 128 * st));
;             }
; #pragma unroll
;             for (int hh = 0; hh < 2; ++hh) {
;                 f32x4 au = (f32x4){0.f, 0.f, 0.f, 0.f};
; #pragma unroll
;                 for (int st = 0; st < 4; ++st) {
;                     const uint4 a4 = abuf[T & 1][hh][st];
;                     const v8i Av = {(int)a4.x, (int)a4.y, (int)a4.z, (int)a4.w, 0, 0, 0, 0};
;                     au = __builtin_amdgcn_mfma_scale_f32_16x16x128_f8f6f4(Av, Bv[st], au, 4, 0, 0, 0x7f7f7f7f, 0, 0x7f7f7f7f);
;                 }
;                 if (owner) *(f32x4*)(sact + 16 * T + 8 * hh) = au;
;             }
	v_lshl_add_u32 v226, v226, 9, v144
	v_lshl_add_u32 v227, v227, 9, v144
	v_lshl_add_u32 v228, v228, 9, v144
	v_lshl_add_u32 v229, v229, 9, v144
	global_load_dwordx4 v[32:35], v226, s[10:11]
	global_load_dwordx4 v[36:39], v226, s[10:11] offset:256
	global_load_dwordx4 v[40:43], v227, s[10:11]
	global_load_dwordx4 v[44:47], v227, s[10:11] offset:256
	global_load_dwordx4 v[48:51], v228, s[10:11]
	global_load_dwordx4 v[52:55], v228, s[10:11] offset:256
	global_load_dwordx4 v[56:59], v229, s[10:11]
	global_load_dwordx4 v[60:63], v229, s[10:11] offset:256
	s_waitcnt vmcnt(8)
	v_mfma_scale_f32_16x16x128_f8f6f4 v[64:67], v[0:3], v[194:201], 0, v133, v133 op_sel_hi:[0,0,0] cbsz:4
	v_mfma_scale_f32_16x16x128_f8f6f4 v[64:67], v[4:7], v[202:209], v[64:67], v133, v133 op_sel_hi:[0,0,0] cbsz:4
	v_mfma_scale_f32_16x16x128_f8f6f4 v[68:71], v[8:11], v[194:201], 0, v133, v133 op_sel_hi:[0,0,0] cbsz:4
	v_mfma_scale_f32_16x16x128_f8f6f4 v[68:71], v[12:15], v[202:209], v[68:71], v133, v133 op_sel_hi:[0,0,0] cbsz:4
	v_mfma_scale_f32_16x16x128_f8f6f4 v[72:75], v[16:19], v[194:201], 0, v133, v133 op_sel_hi:[0,0,0] cbsz:4
	v_mfma_scale_f32_16x16x128_f8f6f4 v[72:75], v[20:23], v[202:209], v[72:75], v133, v133 op_sel_hi:[0,0,0] cbsz:4
	v_mfma_scale_f32_16x16x128_f8f6f4 v[76:79], v[24:27], v[194:201], 0, v133, v133 op_sel_hi:[0,0,0] cbsz:4
	v_mfma_scale_f32_16x16x128_f8f6f4 v[76:79], v[28:31], v[202:209], v[76:79], v133, v133 op_sel_hi:[0,0,0] cbsz:4
	s_nop 3
	v_mul_f32_e32 v230, v158, v80
	v_mul_f32_e32 v231, v158, v84
	v_mul_f32_e32 v232, v158, v88
	v_mul_f32_e32 v233, v158, v92
	v_fmac_f32_e32 v230, v159, v81
	v_fmac_f32_e32 v231, v159, v85
	v_fmac_f32_e32 v232, v159, v89
	v_fmac_f32_e32 v233, v159, v93
	v_fmac_f32_e32 v230, v160, v82
	v_fmac_f32_e32 v231, v160, v86
	v_fmac_f32_e32 v232, v160, v90
	v_fmac_f32_e32 v233, v160, v94
	v_fmac_f32_e32 v230, v161, v83
	v_fmac_f32_e32 v231, v161, v87
	v_fmac_f32_e32 v232, v161, v91
	v_fmac_f32_e32 v233, v161, v95
	v_add_f32_dpp v230, v230, v230 quad_perm:[1,0,3,2] row_mask:0xf bank_mask:0xf
	v_add_f32_dpp v231, v231, v231 quad_perm:[1,0,3,2] row_mask:0xf bank_mask:0xf
	v_add_f32_dpp v232, v232, v232 quad_perm:[1,0,3,2] row_mask:0xf bank_mask:0xf
	v_add_f32_dpp v233, v233, v233 quad_perm:[1,0,3,2] row_mask:0xf bank_mask:0xf
	v_add_f32_dpp v230, v230, v230 quad_perm:[2,3,0,1] row_mask:0xf bank_mask:0xf
	v_add_f32_dpp v231, v231, v231 quad_perm:[2,3,0,1] row_mask:0xf bank_mask:0xf
	v_add_f32_dpp v232, v232, v232 quad_perm:[2,3,0,1] row_mask:0xf bank_mask:0xf
	v_add_f32_dpp v233, v233, v233 quad_perm:[2,3,0,1] row_mask:0xf bank_mask:0xf
	v_add_f32_dpp v230, v230, v230 row_half_mirror row_mask:0xf bank_mask:0xf
	v_add_f32_dpp v231, v231, v231 row_half_mirror row_mask:0xf bank_mask:0xf
	v_add_f32_dpp v232, v232, v232 row_half_mirror row_mask:0xf bank_mask:0xf
	v_add_f32_dpp v233, v233, v233 row_half_mirror row_mask:0xf bank_mask:0xf
	s_mov_b32 exec_lo, 0x10001
	s_mov_b32 exec_hi, 0x10001
	ds_write_b32 v238, v230 offset:832
	ds_write_b32 v238, v231 offset:848
	ds_write_b32 v238, v232 offset:864
	ds_write_b32 v238, v233 offset:880
	s_mov_b64 exec, -1
	ds_read2_b32 v[96:97], v234 offset0:96 offset1:100
	ds_read2_b32 v[98:99], v234 offset0:104 offset1:108
	s_waitcnt lgkmcnt(0)
	v_lshl_add_u32 v96, v96, 9, v144
	v_lshl_add_u32 v97, v97, 9, v144
	v_lshl_add_u32 v98, v98, 9, v144
	v_lshl_add_u32 v99, v99, 9, v144
	global_load_dwordx4 v[0:3], v96, s[10:11]
	global_load_dwordx4 v[4:7], v96, s[10:11] offset:256
	global_load_dwordx4 v[8:11], v97, s[10:11]
	global_load_dwordx4 v[12:15], v97, s[10:11] offset:256
	global_load_dwordx4 v[16:19], v98, s[10:11]
	global_load_dwordx4 v[20:23], v98, s[10:11] offset:256
	global_load_dwordx4 v[24:27], v99, s[10:11]
	global_load_dwordx4 v[28:31], v99, s[10:11] offset:256
	s_waitcnt vmcnt(8)
	v_mfma_scale_f32_16x16x128_f8f6f4 v[80:83], v[32:35], v[210:217], 0, v133, v133 op_sel_hi:[0,0,0] cbsz:4
	v_mfma_scale_f32_16x16x128_f8f6f4 v[80:83], v[36:39], v[218:225], v[80:83], v133, v133 op_sel_hi:[0,0,0] cbsz:4
	v_mfma_scale_f32_16x16x128_f8f6f4 v[84:87], v[40:43], v[210:217], 0, v133, v133 op_sel_hi:[0,0,0] cbsz:4
	v_mfma_scale_f32_16x16x128_f8f6f4 v[84:87], v[44:47], v[218:225], v[84:87], v133, v133 op_sel_hi:[0,0,0] cbsz:4
	v_mfma_scale_f32_16x16x128_f8f6f4 v[88:91], v[48:51], v[210:217], 0, v133, v133 op_sel_hi:[0,0,0] cbsz:4
	v_mfma_scale_f32_16x16x128_f8f6f4 v[88:91], v[52:55], v[218:225], v[88:91], v133, v133 op_sel_hi:[0,0,0] cbsz:4
	v_mfma_scale_f32_16x16x128_f8f6f4 v[92:95], v[56:59], v[210:217], 0, v133, v133 op_sel_hi:[0,0,0] cbsz:4
	v_mfma_scale_f32_16x16x128_f8f6f4 v[92:95], v[60:63], v[218:225], v[92:95], v133, v133 op_sel_hi:[0,0,0] cbsz:4
	s_nop 3
	v_mul_f32_e32 v230, v158, v64
	v_mul_f32_e32 v231, v158, v68
	v_mul_f32_e32 v232, v158, v72
	v_mul_f32_e32 v233, v158, v76
	v_fmac_f32_e32 v230, v159, v65
	v_fmac_f32_e32 v231, v159, v69
	v_fmac_f32_e32 v232, v159, v73
	v_fmac_f32_e32 v233, v159, v77
	v_fmac_f32_e32 v230, v160, v66
	v_fmac_f32_e32 v231, v160, v70
	v_fmac_f32_e32 v232, v160, v74
	v_fmac_f32_e32 v233, v160, v78
	v_fmac_f32_e32 v230, v161, v67
	v_fmac_f32_e32 v231, v161, v71
	v_fmac_f32_e32 v232, v161, v75
	v_fmac_f32_e32 v233, v161, v79
	v_add_f32_dpp v230, v230, v230 quad_perm:[1,0,3,2] row_mask:0xf bank_mask:0xf
	v_add_f32_dpp v231, v231, v231 quad_perm:[1,0,3,2] row_mask:0xf bank_mask:0xf
	v_add_f32_dpp v232, v232, v232 quad_perm:[1,0,3,2] row_mask:0xf bank_mask:0xf
	v_add_f32_dpp v233, v233, v233 quad_perm:[1,0,3,2] row_mask:0xf bank_mask:0xf
	v_add_f32_dpp v230, v230, v230 quad_perm:[2,3,0,1] row_mask:0xf bank_mask:0xf
	v_add_f32_dpp v231, v231, v231 quad_perm:[2,3,0,1] row_mask:0xf bank_mask:0xf
	v_add_f32_dpp v232, v232, v232 quad_perm:[2,3,0,1] row_mask:0xf bank_mask:0xf
	v_add_f32_dpp v233, v233, v233 quad_perm:[2,3,0,1] row_mask:0xf bank_mask:0xf
	v_add_f32_dpp v230, v230, v230 row_half_mirror row_mask:0xf bank_mask:0xf
	v_add_f32_dpp v231, v231, v231 row_half_mirror row_mask:0xf bank_mask:0xf
	v_add_f32_dpp v232, v232, v232 row_half_mirror row_mask:0xf bank_mask:0xf
	v_add_f32_dpp v233, v233, v233 row_half_mirror row_mask:0xf bank_mask:0xf
	s_mov_b32 exec_lo, 0x10001
	s_mov_b32 exec_hi, 0x10001
	ds_write_b32 v238, v230 offset:1344
	ds_write_b32 v238, v231 offset:1360
	ds_write_b32 v238, v232 offset:1376
	ds_write_b32 v238, v233 offset:1392
	s_mov_b64 exec, -1
	ds_read2_b32 v[226:227], v235 offset0:96 offset1:100
	ds_read2_b32 v[228:229], v235 offset0:104 offset1:108
	s_waitcnt lgkmcnt(0)
; __device__ __forceinline__ void peer_token(const Params& P, int t, int lane, int* sidx, float* sval, const int* sid, const float* sgate, const unsigned* szero) {
;     ...
;         for (int T = 0; T < 8; ++T) {
;             if (T + 1 < 8) {
; #pragma unroll
;                 for (int hh = 0; hh < 2; ++hh) off2[hh] = (unsigned)sid[16 * (T + 1) + 8 * hh + (lr & 7)] * 512u + lofs;
; #pragma unroll
;                 for (int hh = 0; hh < 2; ++hh)
; #pragma unroll
;                     for (int st = 0; st < 4; ++st) abuf[(T + 1) & 1][hh][st] = *(const uint4*)(Ub + (off2[hh] + 128 * st));
;             }
; #pragma unroll
;             for (int hh = 0; hh < 2; ++hh) {
;                 f32x4 au = (f32x4){0.f, 0.f, 0.f, 0.f};
; #pragma unroll
;                 for (int st = 0; st < 4; ++st) {
;                     const uint4 a4 = abuf[T & 1][hh][st];
;                     const v8i Av = {(int)a4.x, (int)a4.y, (int)a4.z, (int)a4.w, 0, 0, 0, 0};
;                     au = __builtin_amdgcn_mfma_scale_f32_16x16x128_f8f6f4(Av, Bv[st], au, 4, 0, 0, 0x7f7f7f7f, 0, 0x7f7f7f7f);
;                 }
;                 if (owner) *(f32x4*)(sact + 16 * T + 8 * hh) = au;
;             }
	v_lshl_add_u32 v226, v226, 9, v144
	v_lshl_add_u32 v227, v227, 9, v144
	v_lshl_add_u32 v228, v228, 9, v144
	v_lshl_add_u32 v229, v229, 9, v144
	global_load_dwordx4 v[32:35], v226, s[10:11]
	global_load_dwordx4 v[36:39], v226, s[10:11] offset:256
	global_load_dwordx4 v[40:43], v227, s[10:11]
	global_load_dwordx4 v[44:47], v227, s[10:11] offset:256
	global_load_dwordx4 v[48:51], v228, s[10:11]
	global_load_dwordx4 v[52:55], v228, s[10:11] offset:256
	global_load_dwordx4 v[56:59], v229, s[10:11]
	global_load_dwordx4 v[60:63], v229, s[10:11] offset:256
	s_waitcnt vmcnt(8)
	v_mfma_scale_f32_16x16x128_f8f6f4 v[64:67], v[0:3], v[162:169], 0, v133, v133 op_sel_hi:[0,0,0] cbsz:4
	v_mfma_scale_f32_16x16x128_f8f6f4 v[64:67], v[4:7], v[170:177], v[64:67], v133, v133 op_sel_hi:[0,0,0] cbsz:4
	v_mfma_scale_f32_16x16x128_f8f6f4 v[68:71], v[8:11], v[162:169], 0, v133, v133 op_sel_hi:[0,0,0] cbsz:4
	v_mfma_scale_f32_16x16x128_f8f6f4 v[68:71], v[12:15], v[170:177], v[68:71], v133, v133 op_sel_hi:[0,0,0] cbsz:4
	v_mfma_scale_f32_16x16x128_f8f6f4 v[72:75], v[16:19], v[162:169], 0, v133, v133 op_sel_hi:[0,0,0] cbsz:4
	v_mfma_scale_f32_16x16x128_f8f6f4 v[72:75], v[20:23], v[170:177], v[72:75], v133, v133 op_sel_hi:[0,0,0] cbsz:4
	v_mfma_scale_f32_16x16x128_f8f6f4 v[76:79], v[24:27], v[162:169], 0, v133, v133 op_sel_hi:[0,0,0] cbsz:4
	v_mfma_scale_f32_16x16x128_f8f6f4 v[76:79], v[28:31], v[170:177], v[76:79], v133, v133 op_sel_hi:[0,0,0] cbsz:4
	s_nop 3
	v_mul_f32_e32 v230, v158, v80
	v_mul_f32_e32 v231, v158, v84
	v_mul_f32_e32 v232, v158, v88
	v_mul_f32_e32 v233, v158, v92
	v_fmac_f32_e32 v230, v159, v81
	v_fmac_f32_e32 v231, v159, v85
	v_fmac_f32_e32 v232, v159, v89
	v_fmac_f32_e32 v233, v159, v93
	v_fmac_f32_e32 v230, v160, v82
	v_fmac_f32_e32 v231, v160, v86
	v_fmac_f32_e32 v232, v160, v90
	v_fmac_f32_e32 v233, v160, v94
	v_fmac_f32_e32 v230, v161, v83
	v_fmac_f32_e32 v231, v161, v87
	v_fmac_f32_e32 v232, v161, v91
	v_fmac_f32_e32 v233, v161, v95
	v_add_f32_dpp v230, v230, v230 quad_perm:[1,0,3,2] row_mask:0xf bank_mask:0xf
	v_add_f32_dpp v231, v231, v231 quad_perm:[1,0,3,2] row_mask:0xf bank_mask:0xf
	v_add_f32_dpp v232, v232, v232 quad_perm:[1,0,3,2] row_mask:0xf bank_mask:0xf
	v_add_f32_dpp v233, v233, v233 quad_perm:[1,0,3,2] row_mask:0xf bank_mask:0xf
	v_add_f32_dpp v230, v230, v230 quad_perm:[2,3,0,1] row_mask:0xf bank_mask:0xf
	v_add_f32_dpp v231, v231, v231 quad_perm:[2,3,0,1] row_mask:0xf bank_mask:0xf
	v_add_f32_dpp v232, v232, v232 quad_perm:[2,3,0,1] row_mask:0xf bank_mask:0xf
	v_add_f32_dpp v233, v233, v233 quad_perm:[2,3,0,1] row_mask:0xf bank_mask:0xf
	v_add_f32_dpp v230, v230, v230 row_half_mirror row_mask:0xf bank_mask:0xf
	v_add_f32_dpp v231, v231, v231 row_half_mirror row_mask:0xf bank_mask:0xf
	v_add_f32_dpp v232, v232, v232 row_half_mirror row_mask:0xf bank_mask:0xf
	v_add_f32_dpp v233, v233, v233 row_half_mirror row_mask:0xf bank_mask:0xf
	s_mov_b32 exec_lo, 0x10001
	s_mov_b32 exec_hi, 0x10001
	ds_write_b32 v238, v230 offset:1856
	ds_write_b32 v238, v231 offset:1872
	ds_write_b32 v238, v232 offset:1888
	ds_write_b32 v238, v233 offset:1904
	s_mov_b64 exec, -1
	ds_read2_b32 v[96:97], v236 offset0:96 offset1:100
	ds_read2_b32 v[98:99], v236 offset0:104 offset1:108
	s_waitcnt lgkmcnt(0)
	v_lshl_add_u32 v96, v96, 9, v144
	v_lshl_add_u32 v97, v97, 9, v144
	v_lshl_add_u32 v98, v98, 9, v144
	v_lshl_add_u32 v99, v99, 9, v144
	global_load_dwordx4 v[0:3], v96, s[10:11]
	global_load_dwordx4 v[4:7], v96, s[10:11] offset:256
	global_load_dwordx4 v[8:11], v97, s[10:11]
	global_load_dwordx4 v[12:15], v97, s[10:11] offset:256
	global_load_dwordx4 v[16:19], v98, s[10:11]
	global_load_dwordx4 v[20:23], v98, s[10:11] offset:256
	global_load_dwordx4 v[24:27], v99, s[10:11]
	global_load_dwordx4 v[28:31], v99, s[10:11] offset:256
	s_waitcnt vmcnt(8)
	v_mfma_scale_f32_16x16x128_f8f6f4 v[80:83], v[32:35], v[178:185], 0, v133, v133 op_sel_hi:[0,0,0] cbsz:4
	v_mfma_scale_f32_16x16x128_f8f6f4 v[80:83], v[36:39], v[186:193], v[80:83], v133, v133 op_sel_hi:[0,0,0] cbsz:4
	v_mfma_scale_f32_16x16x128_f8f6f4 v[84:87], v[40:43], v[178:185], 0, v133, v133 op_sel_hi:[0,0,0] cbsz:4
	v_mfma_scale_f32_16x16x128_f8f6f4 v[84:87], v[44:47], v[186:193], v[84:87], v133, v133 op_sel_hi:[0,0,0] cbsz:4
	v_mfma_scale_f32_16x16x128_f8f6f4 v[88:91], v[48:51], v[178:185], 0, v133, v133 op_sel_hi:[0,0,0] cbsz:4
	v_mfma_scale_f32_16x16x128_f8f6f4 v[88:91], v[52:55], v[186:193], v[88:91], v133, v133 op_sel_hi:[0,0,0] cbsz:4
	v_mfma_scale_f32_16x16x128_f8f6f4 v[92:95], v[56:59], v[178:185], 0, v133, v133 op_sel_hi:[0,0,0] cbsz:4
	v_mfma_scale_f32_16x16x128_f8f6f4 v[92:95], v[60:63], v[186:193], v[92:95], v133, v133 op_sel_hi:[0,0,0] cbsz:4
	s_nop 3
	v_mul_f32_e32 v230, v158, v64
	v_mul_f32_e32 v231, v158, v68
	v_mul_f32_e32 v232, v158, v72
	v_mul_f32_e32 v233, v158, v76
	v_fmac_f32_e32 v230, v159, v65
	v_fmac_f32_e32 v231, v159, v69
	v_fmac_f32_e32 v232, v159, v73
	v_fmac_f32_e32 v233, v159, v77
	v_fmac_f32_e32 v230, v160, v66
	v_fmac_f32_e32 v231, v160, v70
	v_fmac_f32_e32 v232, v160, v74
	v_fmac_f32_e32 v233, v160, v78
	v_fmac_f32_e32 v230, v161, v67
	v_fmac_f32_e32 v231, v161, v71
	v_fmac_f32_e32 v232, v161, v75
	v_fmac_f32_e32 v233, v161, v79
	v_add_f32_dpp v230, v230, v230 quad_perm:[1,0,3,2] row_mask:0xf bank_mask:0xf
	v_add_f32_dpp v231, v231, v231 quad_perm:[1,0,3,2] row_mask:0xf bank_mask:0xf
	v_add_f32_dpp v232, v232, v232 quad_perm:[1,0,3,2] row_mask:0xf bank_mask:0xf
	v_add_f32_dpp v233, v233, v233 quad_perm:[1,0,3,2] row_mask:0xf bank_mask:0xf
	v_add_f32_dpp v230, v230, v230 quad_perm:[2,3,0,1] row_mask:0xf bank_mask:0xf
	v_add_f32_dpp v231, v231, v231 quad_perm:[2,3,0,1] row_mask:0xf bank_mask:0xf
	v_add_f32_dpp v232, v232, v232 quad_perm:[2,3,0,1] row_mask:0xf bank_mask:0xf
	v_add_f32_dpp v233, v233, v233 quad_perm:[2,3,0,1] row_mask:0xf bank_mask:0xf
	v_add_f32_dpp v230, v230, v230 row_half_mirror row_mask:0xf bank_mask:0xf
	v_add_f32_dpp v231, v231, v231 row_half_mirror row_mask:0xf bank_mask:0xf
	v_add_f32_dpp v232, v232, v232 row_half_mirror row_mask:0xf bank_mask:0xf
	v_add_f32_dpp v233, v233, v233 row_half_mirror row_mask:0xf bank_mask:0xf
	s_mov_b32 exec_lo, 0x10001
	s_mov_b32 exec_hi, 0x10001
	ds_write_b32 v238, v230 offset:384
	ds_write_b32 v238, v231 offset:400
	ds_write_b32 v238, v232 offset:416
	ds_write_b32 v238, v233 offset:432
	s_mov_b64 exec, -1
	ds_read2_b32 v[226:227], v237 offset0:96 offset1:100
	ds_read2_b32 v[228:229], v237 offset0:104 offset1:108
	s_waitcnt lgkmcnt(0)
; __device__ __forceinline__ void peer_token(const Params& P, int t, int lane, int* sidx, float* sval, const int* sid, const float* sgate, const unsigned* szero) {
;     ...
;         for (int T = 0; T < 8; ++T) {
;             if (T + 1 < 8) {
; #pragma unroll
;                 for (int hh = 0; hh < 2; ++hh) off2[hh] = (unsigned)sid[16 * (T + 1) + 8 * hh + (lr & 7)] * 512u + lofs;
; #pragma unroll
;                 for (int hh = 0; hh < 2; ++hh)
; #pragma unroll
;                     for (int st = 0; st < 4; ++st) abuf[(T + 1) & 1][hh][st] = *(const uint4*)(Ub + (off2[hh] + 128 * st));
;             }
; #pragma unroll
;             for (int hh = 0; hh < 2; ++hh) {
;                 f32x4 au = (f32x4){0.f, 0.f, 0.f, 0.f};
; #pragma unroll
;                 for (int st = 0; st < 4; ++st) {
;                     const uint4 a4 = abuf[T & 1][hh][st];
;                     const v8i Av = {(int)a4.x, (int)a4.y, (int)a4.z, (int)a4.w, 0, 0, 0, 0};
;                     au = __builtin_amdgcn_mfma_scale_f32_16x16x128_f8f6f4(Av, Bv[st], au, 4, 0, 0, 0x7f7f7f7f, 0, 0x7f7f7f7f);
;                 }
;                 if (owner) *(f32x4*)(sact + 16 * T + 8 * hh) = au;
;             }
	v_lshl_add_u32 v226, v226, 9, v144
	v_lshl_add_u32 v227, v227, 9, v144
	v_lshl_add_u32 v228, v228, 9, v144
	v_lshl_add_u32 v229, v229, 9, v144
	global_load_dwordx4 v[32:35], v226, s[10:11]
	global_load_dwordx4 v[36:39], v226, s[10:11] offset:256
	global_load_dwordx4 v[40:43], v227, s[10:11]
	global_load_dwordx4 v[44:47], v227, s[10:11] offset:256
	global_load_dwordx4 v[48:51], v228, s[10:11]
	global_load_dwordx4 v[52:55], v228, s[10:11] offset:256
	global_load_dwordx4 v[56:59], v229, s[10:11]
	global_load_dwordx4 v[60:63], v229, s[10:11] offset:256
	s_waitcnt vmcnt(8)
	v_mfma_scale_f32_16x16x128_f8f6f4 v[64:67], v[0:3], v[194:201], 0, v133, v133 op_sel_hi:[0,0,0] cbsz:4
	v_mfma_scale_f32_16x16x128_f8f6f4 v[64:67], v[4:7], v[202:209], v[64:67], v133, v133 op_sel_hi:[0,0,0] cbsz:4
	v_mfma_scale_f32_16x16x128_f8f6f4 v[68:71], v[8:11], v[194:201], 0, v133, v133 op_sel_hi:[0,0,0] cbsz:4
	v_mfma_scale_f32_16x16x128_f8f6f4 v[68:71], v[12:15], v[202:209], v[68:71], v133, v133 op_sel_hi:[0,0,0] cbsz:4
	v_mfma_scale_f32_16x16x128_f8f6f4 v[72:75], v[16:19], v[194:201], 0, v133, v133 op_sel_hi:[0,0,0] cbsz:4
	v_mfma_scale_f32_16x16x128_f8f6f4 v[72:75], v[20:23], v[202:209], v[72:75], v133, v133 op_sel_hi:[0,0,0] cbsz:4
	v_mfma_scale_f32_16x16x128_f8f6f4 v[76:79], v[24:27], v[194:201], 0, v133, v133 op_sel_hi:[0,0,0] cbsz:4
	v_mfma_scale_f32_16x16x128_f8f6f4 v[76:79], v[28:31], v[202:209], v[76:79], v133, v133 op_sel_hi:[0,0,0] cbsz:4
	s_nop 3
	v_mul_f32_e32 v230, v158, v80
	v_mul_f32_e32 v231, v158, v84
	v_mul_f32_e32 v232, v158, v88
	v_mul_f32_e32 v233, v158, v92
	v_fmac_f32_e32 v230, v159, v81
	v_fmac_f32_e32 v231, v159, v85
	v_fmac_f32_e32 v232, v159, v89
	v_fmac_f32_e32 v233, v159, v93
	v_fmac_f32_e32 v230, v160, v82
	v_fmac_f32_e32 v231, v160, v86
	v_fmac_f32_e32 v232, v160, v90
	v_fmac_f32_e32 v233, v160, v94
	v_fmac_f32_e32 v230, v161, v83
	v_fmac_f32_e32 v231, v161, v87
	v_fmac_f32_e32 v232, v161, v91
	v_fmac_f32_e32 v233, v161, v95
	v_add_f32_dpp v230, v230, v230 quad_perm:[1,0,3,2] row_mask:0xf bank_mask:0xf
	v_add_f32_dpp v231, v231, v231 quad_perm:[1,0,3,2] row_mask:0xf bank_mask:0xf
	v_add_f32_dpp v232, v232, v232 quad_perm:[1,0,3,2] row_mask:0xf bank_mask:0xf
	v_add_f32_dpp v233, v233, v233 quad_perm:[1,0,3,2] row_mask:0xf bank_mask:0xf
	v_add_f32_dpp v230, v230, v230 quad_perm:[2,3,0,1] row_mask:0xf bank_mask:0xf
	v_add_f32_dpp v231, v231, v231 quad_perm:[2,3,0,1] row_mask:0xf bank_mask:0xf
	v_add_f32_dpp v232, v232, v232 quad_perm:[2,3,0,1] row_mask:0xf bank_mask:0xf
	v_add_f32_dpp v233, v233, v233 quad_perm:[2,3,0,1] row_mask:0xf bank_mask:0xf
	v_add_f32_dpp v230, v230, v230 row_half_mirror row_mask:0xf bank_mask:0xf
	v_add_f32_dpp v231, v231, v231 row_half_mirror row_mask:0xf bank_mask:0xf
	v_add_f32_dpp v232, v232, v232 row_half_mirror row_mask:0xf bank_mask:0xf
	v_add_f32_dpp v233, v233, v233 row_half_mirror row_mask:0xf bank_mask:0xf
	s_mov_b32 exec_lo, 0x10001
	s_mov_b32 exec_hi, 0x10001
	ds_write_b32 v238, v230 offset:896
	ds_write_b32 v238, v231 offset:912
	ds_write_b32 v238, v232 offset:928
	ds_write_b32 v238, v233 offset:944
	s_mov_b64 exec, -1
	ds_read2_b32 v[96:97], v234 offset0:112 offset1:116
	ds_read2_b32 v[98:99], v234 offset0:120 offset1:124
	s_waitcnt lgkmcnt(0)
	v_lshl_add_u32 v96, v96, 9, v144
	v_lshl_add_u32 v97, v97, 9, v144
	v_lshl_add_u32 v98, v98, 9, v144
	v_lshl_add_u32 v99, v99, 9, v144
	global_load_dwordx4 v[0:3], v96, s[10:11]
	global_load_dwordx4 v[4:7], v96, s[10:11] offset:256
	global_load_dwordx4 v[8:11], v97, s[10:11]
	global_load_dwordx4 v[12:15], v97, s[10:11] offset:256
	global_load_dwordx4 v[16:19], v98, s[10:11]
	global_load_dwordx4 v[20:23], v98, s[10:11] offset:256
	global_load_dwordx4 v[24:27], v99, s[10:11]
	global_load_dwordx4 v[28:31], v99, s[10:11] offset:256
	s_waitcnt vmcnt(8)
	v_mfma_scale_f32_16x16x128_f8f6f4 v[80:83], v[32:35], v[210:217], 0, v133, v133 op_sel_hi:[0,0,0] cbsz:4
	v_mfma_scale_f32_16x16x128_f8f6f4 v[80:83], v[36:39], v[218:225], v[80:83], v133, v133 op_sel_hi:[0,0,0] cbsz:4
	v_mfma_scale_f32_16x16x128_f8f6f4 v[84:87], v[40:43], v[210:217], 0, v133, v133 op_sel_hi:[0,0,0] cbsz:4
	v_mfma_scale_f32_16x16x128_f8f6f4 v[84:87], v[44:47], v[218:225], v[84:87], v133, v133 op_sel_hi:[0,0,0] cbsz:4
	v_mfma_scale_f32_16x16x128_f8f6f4 v[88:91], v[48:51], v[210:217], 0, v133, v133 op_sel_hi:[0,0,0] cbsz:4
	v_mfma_scale_f32_16x16x128_f8f6f4 v[88:91], v[52:55], v[218:225], v[88:91], v133, v133 op_sel_hi:[0,0,0] cbsz:4
	v_mfma_scale_f32_16x16x128_f8f6f4 v[92:95], v[56:59], v[210:217], 0, v133, v133 op_sel_hi:[0,0,0] cbsz:4
	v_mfma_scale_f32_16x16x128_f8f6f4 v[92:95], v[60:63], v[218:225], v[92:95], v133, v133 op_sel_hi:[0,0,0] cbsz:4
	s_nop 3
	v_mul_f32_e32 v230, v158, v64
	v_mul_f32_e32 v231, v158, v68
	v_mul_f32_e32 v232, v158, v72
	v_mul_f32_e32 v233, v158, v76
	v_fmac_f32_e32 v230, v159, v65
	v_fmac_f32_e32 v231, v159, v69
	v_fmac_f32_e32 v232, v159, v73
	v_fmac_f32_e32 v233, v159, v77
	v_fmac_f32_e32 v230, v160, v66
	v_fmac_f32_e32 v231, v160, v70
	v_fmac_f32_e32 v232, v160, v74
	v_fmac_f32_e32 v233, v160, v78
	v_fmac_f32_e32 v230, v161, v67
	v_fmac_f32_e32 v231, v161, v71
	v_fmac_f32_e32 v232, v161, v75
	v_fmac_f32_e32 v233, v161, v79
	v_add_f32_dpp v230, v230, v230 quad_perm:[1,0,3,2] row_mask:0xf bank_mask:0xf
	v_add_f32_dpp v231, v231, v231 quad_perm:[1,0,3,2] row_mask:0xf bank_mask:0xf
	v_add_f32_dpp v232, v232, v232 quad_perm:[1,0,3,2] row_mask:0xf bank_mask:0xf
	v_add_f32_dpp v233, v233, v233 quad_perm:[1,0,3,2] row_mask:0xf bank_mask:0xf
	v_add_f32_dpp v230, v230, v230 quad_perm:[2,3,0,1] row_mask:0xf bank_mask:0xf
	v_add_f32_dpp v231, v231, v231 quad_perm:[2,3,0,1] row_mask:0xf bank_mask:0xf
	v_add_f32_dpp v232, v232, v232 quad_perm:[2,3,0,1] row_mask:0xf bank_mask:0xf
	v_add_f32_dpp v233, v233, v233 quad_perm:[2,3,0,1] row_mask:0xf bank_mask:0xf
	v_add_f32_dpp v230, v230, v230 row_half_mirror row_mask:0xf bank_mask:0xf
	v_add_f32_dpp v231, v231, v231 row_half_mirror row_mask:0xf bank_mask:0xf
	v_add_f32_dpp v232, v232, v232 row_half_mirror row_mask:0xf bank_mask:0xf
	v_add_f32_dpp v233, v233, v233 row_half_mirror row_mask:0xf bank_mask:0xf
	s_mov_b32 exec_lo, 0x10001
	s_mov_b32 exec_hi, 0x10001
	ds_write_b32 v238, v230 offset:1408
	ds_write_b32 v238, v231 offset:1424
	ds_write_b32 v238, v232 offset:1440
	ds_write_b32 v238, v233 offset:1456
	s_mov_b64 exec, -1
	ds_read2_b32 v[226:227], v235 offset0:112 offset1:116
	ds_read2_b32 v[228:229], v235 offset0:120 offset1:124
	s_waitcnt lgkmcnt(0)
; __device__ __forceinline__ void peer_token(const Params& P, int t, int lane, int* sidx, float* sval, const int* sid, const float* sgate, const unsigned* szero) {
;     ...
;         for (int T = 0; T < 8; ++T) {
;             if (T + 1 < 8) {
; #pragma unroll
;                 for (int hh = 0; hh < 2; ++hh) off2[hh] = (unsigned)sid[16 * (T + 1) + 8 * hh + (lr & 7)] * 512u + lofs;
; #pragma unroll
;                 for (int hh = 0; hh < 2; ++hh)
; #pragma unroll
;                     for (int st = 0; st < 4; ++st) abuf[(T + 1) & 1][hh][st] = *(const uint4*)(Ub + (off2[hh] + 128 * st));
;             }
; #pragma unroll
;             for (int hh = 0; hh < 2; ++hh) {
;                 f32x4 au = (f32x4){0.f, 0.f, 0.f, 0.f};
; #pragma unroll
;                 for (int st = 0; st < 4; ++st) {
;                     const uint4 a4 = abuf[T & 1][hh][st];
;                     const v8i Av = {(int)a4.x, (int)a4.y, (int)a4.z, (int)a4.w, 0, 0, 0, 0};
;                     au = __builtin_amdgcn_mfma_scale_f32_16x16x128_f8f6f4(Av, Bv[st], au, 4, 0, 0, 0x7f7f7f7f, 0, 0x7f7f7f7f);
;                 }
;                 if (owner) *(f32x4*)(sact + 16 * T + 8 * hh) = au;
;             }
	v_lshl_add_u32 v226, v226, 9, v144
	v_lshl_add_u32 v227, v227, 9, v144
	v_lshl_add_u32 v228, v228, 9, v144
	v_lshl_add_u32 v229, v229, 9, v144
	global_load_dwordx4 v[32:35], v226, s[10:11]
	global_load_dwordx4 v[36:39], v226, s[10:11] offset:256
	global_load_dwordx4 v[40:43], v227, s[10:11]
	global_load_dwordx4 v[44:47], v227, s[10:11] offset:256
	global_load_dwordx4 v[48:51], v228, s[10:11]
	global_load_dwordx4 v[52:55], v228, s[10:11] offset:256
	global_load_dwordx4 v[56:59], v229, s[10:11]
	global_load_dwordx4 v[60:63], v229, s[10:11] offset:256
	s_waitcnt vmcnt(8)
	v_mfma_scale_f32_16x16x128_f8f6f4 v[64:67], v[0:3], v[162:169], 0, v133, v133 op_sel_hi:[0,0,0] cbsz:4
	v_mfma_scale_f32_16x16x128_f8f6f4 v[64:67], v[4:7], v[170:177], v[64:67], v133, v133 op_sel_hi:[0,0,0] cbsz:4
	v_mfma_scale_f32_16x16x128_f8f6f4 v[68:71], v[8:11], v[162:169], 0, v133, v133 op_sel_hi:[0,0,0] cbsz:4
	v_mfma_scale_f32_16x16x128_f8f6f4 v[68:71], v[12:15], v[170:177], v[68:71], v133, v133 op_sel_hi:[0,0,0] cbsz:4
	v_mfma_scale_f32_16x16x128_f8f6f4 v[72:75], v[16:19], v[162:169], 0, v133, v133 op_sel_hi:[0,0,0] cbsz:4
	v_mfma_scale_f32_16x16x128_f8f6f4 v[72:75], v[20:23], v[170:177], v[72:75], v133, v133 op_sel_hi:[0,0,0] cbsz:4
	v_mfma_scale_f32_16x16x128_f8f6f4 v[76:79], v[24:27], v[162:169], 0, v133, v133 op_sel_hi:[0,0,0] cbsz:4
	v_mfma_scale_f32_16x16x128_f8f6f4 v[76:79], v[28:31], v[170:177], v[76:79], v133, v133 op_sel_hi:[0,0,0] cbsz:4
	s_nop 3
	v_mul_f32_e32 v230, v158, v80
	v_mul_f32_e32 v231, v158, v84
	v_mul_f32_e32 v232, v158, v88
	v_mul_f32_e32 v233, v158, v92
	v_fmac_f32_e32 v230, v159, v81
	v_fmac_f32_e32 v231, v159, v85
	v_fmac_f32_e32 v232, v159, v89
	v_fmac_f32_e32 v233, v159, v93
	v_fmac_f32_e32 v230, v160, v82
	v_fmac_f32_e32 v231, v160, v86
	v_fmac_f32_e32 v232, v160, v90
	v_fmac_f32_e32 v233, v160, v94
	v_fmac_f32_e32 v230, v161, v83
	v_fmac_f32_e32 v231, v161, v87
	v_fmac_f32_e32 v232, v161, v91
	v_fmac_f32_e32 v233, v161, v95
	v_add_f32_dpp v230, v230, v230 quad_perm:[1,0,3,2] row_mask:0xf bank_mask:0xf
	v_add_f32_dpp v231, v231, v231 quad_perm:[1,0,3,2] row_mask:0xf bank_mask:0xf
	v_add_f32_dpp v232, v232, v232 quad_perm:[1,0,3,2] row_mask:0xf bank_mask:0xf
	v_add_f32_dpp v233, v233, v233 quad_perm:[1,0,3,2] row_mask:0xf bank_mask:0xf
	v_add_f32_dpp v230, v230, v230 quad_perm:[2,3,0,1] row_mask:0xf bank_mask:0xf
	v_add_f32_dpp v231, v231, v231 quad_perm:[2,3,0,1] row_mask:0xf bank_mask:0xf
	v_add_f32_dpp v232, v232, v232 quad_perm:[2,3,0,1] row_mask:0xf bank_mask:0xf
	v_add_f32_dpp v233, v233, v233 quad_perm:[2,3,0,1] row_mask:0xf bank_mask:0xf
	v_add_f32_dpp v230, v230, v230 row_half_mirror row_mask:0xf bank_mask:0xf
	v_add_f32_dpp v231, v231, v231 row_half_mirror row_mask:0xf bank_mask:0xf
	v_add_f32_dpp v232, v232, v232 row_half_mirror row_mask:0xf bank_mask:0xf
	v_add_f32_dpp v233, v233, v233 row_half_mirror row_mask:0xf bank_mask:0xf
	s_mov_b32 exec_lo, 0x10001
	s_mov_b32 exec_hi, 0x10001
	ds_write_b32 v238, v230 offset:1920
	ds_write_b32 v238, v231 offset:1936
	ds_write_b32 v238, v232 offset:1952
	ds_write_b32 v238, v233 offset:1968
	s_mov_b64 exec, -1
	ds_read2_b32 v[96:97], v236 offset0:112 offset1:116
	ds_read2_b32 v[98:99], v236 offset0:120 offset1:124
	s_waitcnt lgkmcnt(0)
	v_lshl_add_u32 v96, v96, 9, v144
	v_lshl_add_u32 v97, v97, 9, v144
	v_lshl_add_u32 v98, v98, 9, v144
	v_lshl_add_u32 v99, v99, 9, v144
	global_load_dwordx4 v[0:3], v96, s[10:11]
	global_load_dwordx4 v[4:7], v96, s[10:11] offset:256
	global_load_dwordx4 v[8:11], v97, s[10:11]
	global_load_dwordx4 v[12:15], v97, s[10:11] offset:256
	global_load_dwordx4 v[16:19], v98, s[10:11]
	global_load_dwordx4 v[20:23], v98, s[10:11] offset:256
	global_load_dwordx4 v[24:27], v99, s[10:11]
	global_load_dwordx4 v[28:31], v99, s[10:11] offset:256
	s_waitcnt vmcnt(8)
	v_mfma_scale_f32_16x16x128_f8f6f4 v[80:83], v[32:35], v[178:185], 0, v133, v133 op_sel_hi:[0,0,0] cbsz:4
	v_mfma_scale_f32_16x16x128_f8f6f4 v[80:83], v[36:39], v[186:193], v[80:83], v133, v133 op_sel_hi:[0,0,0] cbsz:4
	v_mfma_scale_f32_16x16x128_f8f6f4 v[84:87], v[40:43], v[178:185], 0, v133, v133 op_sel_hi:[0,0,0] cbsz:4
	v_mfma_scale_f32_16x16x128_f8f6f4 v[84:87], v[44:47], v[186:193], v[84:87], v133, v133 op_sel_hi:[0,0,0] cbsz:4
	v_mfma_scale_f32_16x16x128_f8f6f4 v[88:91], v[48:51], v[178:185], 0, v133, v133 op_sel_hi:[0,0,0] cbsz:4
	v_mfma_scale_f32_16x16x128_f8f6f4 v[88:91], v[52:55], v[186:193], v[88:91], v133, v133 op_sel_hi:[0,0,0] cbsz:4
	v_mfma_scale_f32_16x16x128_f8f6f4 v[92:95], v[56:59], v[178:185], 0, v133, v133 op_sel_hi:[0,0,0] cbsz:4
	v_mfma_scale_f32_16x16x128_f8f6f4 v[92:95], v[60:63], v[186:193], v[92:95], v133, v133 op_sel_hi:[0,0,0] cbsz:4
	s_nop 3
	v_mul_f32_e32 v230, v158, v64
	v_mul_f32_e32 v231, v158, v68
	v_mul_f32_e32 v232, v158, v72
	v_mul_f32_e32 v233, v158, v76
	v_fmac_f32_e32 v230, v159, v65
	v_fmac_f32_e32 v231, v159, v69
	v_fmac_f32_e32 v232, v159, v73
	v_fmac_f32_e32 v233, v159, v77
	v_fmac_f32_e32 v230, v160, v66
	v_fmac_f32_e32 v231, v160, v70
	v_fmac_f32_e32 v232, v160, v74
	v_fmac_f32_e32 v233, v160, v78
	v_fmac_f32_e32 v230, v161, v67
	v_fmac_f32_e32 v231, v161, v71
	v_fmac_f32_e32 v232, v161, v75
	v_fmac_f32_e32 v233, v161, v79
	v_add_f32_dpp v230, v230, v230 quad_perm:[1,0,3,2] row_mask:0xf bank_mask:0xf
	v_add_f32_dpp v231, v231, v231 quad_perm:[1,0,3,2] row_mask:0xf bank_mask:0xf
	v_add_f32_dpp v232, v232, v232 quad_perm:[1,0,3,2] row_mask:0xf bank_mask:0xf
	v_add_f32_dpp v233, v233, v233 quad_perm:[1,0,3,2] row_mask:0xf bank_mask:0xf
	v_add_f32_dpp v230, v230, v230 quad_perm:[2,3,0,1] row_mask:0xf bank_mask:0xf
	v_add_f32_dpp v231, v231, v231 quad_perm:[2,3,0,1] row_mask:0xf bank_mask:0xf
	v_add_f32_dpp v232, v232, v232 quad_perm:[2,3,0,1] row_mask:0xf bank_mask:0xf
	v_add_f32_dpp v233, v233, v233 quad_perm:[2,3,0,1] row_mask:0xf bank_mask:0xf
	v_add_f32_dpp v230, v230, v230 row_half_mirror row_mask:0xf bank_mask:0xf
	v_add_f32_dpp v231, v231, v231 row_half_mirror row_mask:0xf bank_mask:0xf
	v_add_f32_dpp v232, v232, v232 row_half_mirror row_mask:0xf bank_mask:0xf
	v_add_f32_dpp v233, v233, v233 row_half_mirror row_mask:0xf bank_mask:0xf
	s_mov_b32 exec_lo, 0x10001
	s_mov_b32 exec_hi, 0x10001
	ds_write_b32 v238, v230 offset:448
	ds_write_b32 v238, v231 offset:464
	ds_write_b32 v238, v232 offset:480
	ds_write_b32 v238, v233 offset:496
	s_mov_b64 exec, -1
	ds_read2_b32 v[226:227], v237 offset0:112 offset1:116
	ds_read2_b32 v[228:229], v237 offset0:120 offset1:124
	s_waitcnt lgkmcnt(0)
; __device__ __forceinline__ void peer_token(const Params& P, int t, int lane, int* sidx, float* sval, const int* sid, const float* sgate, const unsigned* szero) {
;     ...
;         for (int T = 0; T < 8; ++T) {
;             if (T + 1 < 8) {
; #pragma unroll
;                 for (int hh = 0; hh < 2; ++hh) off2[hh] = (unsigned)sid[16 * (T + 1) + 8 * hh + (lr & 7)] * 512u + lofs;
; #pragma unroll
;                 for (int hh = 0; hh < 2; ++hh)
; #pragma unroll
;                     for (int st = 0; st < 4; ++st) abuf[(T + 1) & 1][hh][st] = *(const uint4*)(Ub + (off2[hh] + 128 * st));
;             }
; #pragma unroll
;             for (int hh = 0; hh < 2; ++hh) {
;                 f32x4 au = (f32x4){0.f, 0.f, 0.f, 0.f};
; #pragma unroll
;                 for (int st = 0; st < 4; ++st) {
;                     const uint4 a4 = abuf[T & 1][hh][st];
;                     const v8i Av = {(int)a4.x, (int)a4.y, (int)a4.z, (int)a4.w, 0, 0, 0, 0};
;                     au = __builtin_amdgcn_mfma_scale_f32_16x16x128_f8f6f4(Av, Bv[st], au, 4, 0, 0, 0x7f7f7f7f, 0, 0x7f7f7f7f);
;                 }
;                 if (owner) *(f32x4*)(sact + 16 * T + 8 * hh) = au;
;             }
	v_lshl_add_u32 v226, v226, 9, v144
	v_lshl_add_u32 v227, v227, 9, v144
	v_lshl_add_u32 v228, v228, 9, v144
	v_lshl_add_u32 v229, v229, 9, v144
	global_load_dwordx4 v[32:35], v226, s[10:11]
	global_load_dwordx4 v[36:39], v226, s[10:11] offset:256
	global_load_dwordx4 v[40:43], v227, s[10:11]
	global_load_dwordx4 v[44:47], v227, s[10:11] offset:256
	global_load_dwordx4 v[48:51], v228, s[10:11]
	global_load_dwordx4 v[52:55], v228, s[10:11] offset:256
	global_load_dwordx4 v[56:59], v229, s[10:11]
	global_load_dwordx4 v[60:63], v229, s[10:11] offset:256
	s_waitcnt vmcnt(8)
	v_mfma_scale_f32_16x16x128_f8f6f4 v[64:67], v[0:3], v[194:201], 0, v133, v133 op_sel_hi:[0,0,0] cbsz:4
	v_mfma_scale_f32_16x16x128_f8f6f4 v[64:67], v[4:7], v[202:209], v[64:67], v133, v133 op_sel_hi:[0,0,0] cbsz:4
	v_mfma_scale_f32_16x16x128_f8f6f4 v[68:71], v[8:11], v[194:201], 0, v133, v133 op_sel_hi:[0,0,0] cbsz:4
	v_mfma_scale_f32_16x16x128_f8f6f4 v[68:71], v[12:15], v[202:209], v[68:71], v133, v133 op_sel_hi:[0,0,0] cbsz:4
	v_mfma_scale_f32_16x16x128_f8f6f4 v[72:75], v[16:19], v[194:201], 0, v133, v133 op_sel_hi:[0,0,0] cbsz:4
	v_mfma_scale_f32_16x16x128_f8f6f4 v[72:75], v[20:23], v[202:209], v[72:75], v133, v133 op_sel_hi:[0,0,0] cbsz:4
	v_mfma_scale_f32_16x16x128_f8f6f4 v[76:79], v[24:27], v[194:201], 0, v133, v133 op_sel_hi:[0,0,0] cbsz:4
	v_mfma_scale_f32_16x16x128_f8f6f4 v[76:79], v[28:31], v[202:209], v[76:79], v133, v133 op_sel_hi:[0,0,0] cbsz:4
	s_nop 3
	v_mul_f32_e32 v230, v158, v80
	v_mul_f32_e32 v231, v158, v84
	v_mul_f32_e32 v232, v158, v88
	v_mul_f32_e32 v233, v158, v92
	v_fmac_f32_e32 v230, v159, v81
	v_fmac_f32_e32 v231, v159, v85
	v_fmac_f32_e32 v232, v159, v89
	v_fmac_f32_e32 v233, v159, v93
	v_fmac_f32_e32 v230, v160, v82
	v_fmac_f32_e32 v231, v160, v86
	v_fmac_f32_e32 v232, v160, v90
	v_fmac_f32_e32 v233, v160, v94
	v_fmac_f32_e32 v230, v161, v83
	v_fmac_f32_e32 v231, v161, v87
	v_fmac_f32_e32 v232, v161, v91
	v_fmac_f32_e32 v233, v161, v95
	v_add_f32_dpp v230, v230, v230 quad_perm:[1,0,3,2] row_mask:0xf bank_mask:0xf
	v_add_f32_dpp v231, v231, v231 quad_perm:[1,0,3,2] row_mask:0xf bank_mask:0xf
	v_add_f32_dpp v232, v232, v232 quad_perm:[1,0,3,2] row_mask:0xf bank_mask:0xf
	v_add_f32_dpp v233, v233, v233 quad_perm:[1,0,3,2] row_mask:0xf bank_mask:0xf
	v_add_f32_dpp v230, v230, v230 quad_perm:[2,3,0,1] row_mask:0xf bank_mask:0xf
	v_add_f32_dpp v231, v231, v231 quad_perm:[2,3,0,1] row_mask:0xf bank_mask:0xf
	v_add_f32_dpp v232, v232, v232 quad_perm:[2,3,0,1] row_mask:0xf bank_mask:0xf
	v_add_f32_dpp v233, v233, v233 quad_perm:[2,3,0,1] row_mask:0xf bank_mask:0xf
	v_add_f32_dpp v230, v230, v230 row_half_mirror row_mask:0xf bank_mask:0xf
	v_add_f32_dpp v231, v231, v231 row_half_mirror row_mask:0xf bank_mask:0xf
	v_add_f32_dpp v232, v232, v232 row_half_mirror row_mask:0xf bank_mask:0xf
	v_add_f32_dpp v233, v233, v233 row_half_mirror row_mask:0xf bank_mask:0xf
	s_mov_b32 exec_lo, 0x10001
	s_mov_b32 exec_hi, 0x10001
	ds_write_b32 v238, v230 offset:960
	ds_write_b32 v238, v231 offset:976
	ds_write_b32 v238, v232 offset:992
	ds_write_b32 v238, v233 offset:1008
	s_mov_b64 exec, -1
	s_waitcnt vmcnt(0)
	v_mfma_scale_f32_16x16x128_f8f6f4 v[80:83], v[32:35], v[210:217], 0, v133, v133 op_sel_hi:[0,0,0] cbsz:4
	v_mfma_scale_f32_16x16x128_f8f6f4 v[80:83], v[36:39], v[218:225], v[80:83], v133, v133 op_sel_hi:[0,0,0] cbsz:4
	v_mfma_scale_f32_16x16x128_f8f6f4 v[84:87], v[40:43], v[210:217], 0, v133, v133 op_sel_hi:[0,0,0] cbsz:4
	v_mfma_scale_f32_16x16x128_f8f6f4 v[84:87], v[44:47], v[218:225], v[84:87], v133, v133 op_sel_hi:[0,0,0] cbsz:4
	v_mfma_scale_f32_16x16x128_f8f6f4 v[88:91], v[48:51], v[210:217], 0, v133, v133 op_sel_hi:[0,0,0] cbsz:4
	v_mfma_scale_f32_16x16x128_f8f6f4 v[88:91], v[52:55], v[218:225], v[88:91], v133, v133 op_sel_hi:[0,0,0] cbsz:4
	v_mfma_scale_f32_16x16x128_f8f6f4 v[92:95], v[56:59], v[210:217], 0, v133, v133 op_sel_hi:[0,0,0] cbsz:4
	v_mfma_scale_f32_16x16x128_f8f6f4 v[92:95], v[60:63], v[218:225], v[92:95], v133, v133 op_sel_hi:[0,0,0] cbsz:4
	s_nop 3
	v_mul_f32_e32 v230, v158, v64
	v_mul_f32_e32 v231, v158, v68
	v_mul_f32_e32 v232, v158, v72
	v_mul_f32_e32 v233, v158, v76
	v_fmac_f32_e32 v230, v159, v65
	v_fmac_f32_e32 v231, v159, v69
	v_fmac_f32_e32 v232, v159, v73
	v_fmac_f32_e32 v233, v159, v77
	v_fmac_f32_e32 v230, v160, v66
	v_fmac_f32_e32 v231, v160, v70
	v_fmac_f32_e32 v232, v160, v74
	v_fmac_f32_e32 v233, v160, v78
	v_fmac_f32_e32 v230, v161, v67
	v_fmac_f32_e32 v231, v161, v71
	v_fmac_f32_e32 v232, v161, v75
	v_fmac_f32_e32 v233, v161, v79
	v_add_f32_dpp v230, v230, v230 quad_perm:[1,0,3,2] row_mask:0xf bank_mask:0xf
	v_add_f32_dpp v231, v231, v231 quad_perm:[1,0,3,2] row_mask:0xf bank_mask:0xf
	v_add_f32_dpp v232, v232, v232 quad_perm:[1,0,3,2] row_mask:0xf bank_mask:0xf
	v_add_f32_dpp v233, v233, v233 quad_perm:[1,0,3,2] row_mask:0xf bank_mask:0xf
	v_add_f32_dpp v230, v230, v230 quad_perm:[2,3,0,1] row_mask:0xf bank_mask:0xf
	v_add_f32_dpp v231, v231, v231 quad_perm:[2,3,0,1] row_mask:0xf bank_mask:0xf
	v_add_f32_dpp v232, v232, v232 quad_perm:[2,3,0,1] row_mask:0xf bank_mask:0xf
	v_add_f32_dpp v233, v233, v233 quad_perm:[2,3,0,1] row_mask:0xf bank_mask:0xf
	v_add_f32_dpp v230, v230, v230 row_half_mirror row_mask:0xf bank_mask:0xf
	v_add_f32_dpp v231, v231, v231 row_half_mirror row_mask:0xf bank_mask:0xf
	v_add_f32_dpp v232, v232, v232 row_half_mirror row_mask:0xf bank_mask:0xf
	v_add_f32_dpp v233, v233, v233 row_half_mirror row_mask:0xf bank_mask:0xf
	s_mov_b32 exec_lo, 0x10001
	s_mov_b32 exec_hi, 0x10001
	ds_write_b32 v238, v230 offset:1472
	ds_write_b32 v238, v231 offset:1488
	ds_write_b32 v238, v232 offset:1504
; __device__ __forceinline__ void peer_token(const Params& P, int t, int lane, int* sidx, float* sval, const int* sid, const float* sgate, const unsigned* szero) {
;     ...
; #pragma unroll
;             for (int hh = 0; hh < 2; ++hh) {
;                 f32x4 au = (f32x4){0.f, 0.f, 0.f, 0.f};
; #pragma unroll
;                 for (int st = 0; st < 4; ++st) {
;                     const uint4 a4 = abuf[T & 1][hh][st];
;                     const v8i Av = {(int)a4.x, (int)a4.y, (int)a4.z, (int)a4.w, 0, 0, 0, 0};
;                     au = __builtin_amdgcn_mfma_scale_f32_16x16x128_f8f6f4(Av, Bv[st], au, 4, 0, 0, 0x7f7f7f7f, 0, 0x7f7f7f7f);
;                 }
;                 if (owner) *(f32x4*)(sact + 16 * T + 8 * hh) = au;
;             }
;     ...
;     {
;         float* sw = (float*)sidx;
;         float wv[2];
; #pragma unroll
;         for (int hh = 0; hh < 2; ++hh) {
;             const int e = lane + 64 * hh, id = sid[e];
;             const float a = ((sw[e] + sw[128 + e]) + (sw[256 + e] + sw[384 + e])) * usc[id] * rstd;
;             wv[hh] = sgate[e] * vsc[id] * 0.5f * a * (1.f + erff(a * 0.70710678118654752f));
;         }
;         __builtin_amdgcn_s_waitcnt(0xc07f);
;         __builtin_amdgcn_wave_barrier();
;         sw[lane] = wv[0]; sw[lane + 64] = wv[1];
;     }
	ds_write_b32 v238, v233 offset:1520
	s_mov_b64 exec, -1
	s_nop 11
	v_mul_f32_e32 v230, v158, v80
	v_mul_f32_e32 v231, v158, v84
	v_mul_f32_e32 v232, v158, v88
	v_mul_f32_e32 v233, v158, v92
	v_fmac_f32_e32 v230, v159, v81
	v_fmac_f32_e32 v231, v159, v85
	v_fmac_f32_e32 v232, v159, v89
	v_fmac_f32_e32 v233, v159, v93
	v_fmac_f32_e32 v230, v160, v82
	v_fmac_f32_e32 v231, v160, v86
	v_fmac_f32_e32 v232, v160, v90
	v_fmac_f32_e32 v233, v160, v94
	v_fmac_f32_e32 v230, v161, v83
	v_fmac_f32_e32 v231, v161, v87
	v_fmac_f32_e32 v232, v161, v91
	v_fmac_f32_e32 v233, v161, v95
	v_add_f32_dpp v230, v230, v230 quad_perm:[1,0,3,2] row_mask:0xf bank_mask:0xf
	v_add_f32_dpp v231, v231, v231 quad_perm:[1,0,3,2] row_mask:0xf bank_mask:0xf
	v_add_f32_dpp v232, v232, v232 quad_perm:[1,0,3,2] row_mask:0xf bank_mask:0xf
	v_add_f32_dpp v233, v233, v233 quad_perm:[1,0,3,2] row_mask:0xf bank_mask:0xf
	v_add_f32_dpp v230, v230, v230 quad_perm:[2,3,0,1] row_mask:0xf bank_mask:0xf
	v_add_f32_dpp v231, v231, v231 quad_perm:[2,3,0,1] row_mask:0xf bank_mask:0xf
	v_add_f32_dpp v232, v232, v232 quad_perm:[2,3,0,1] row_mask:0xf bank_mask:0xf
	v_add_f32_dpp v233, v233, v233 quad_perm:[2,3,0,1] row_mask:0xf bank_mask:0xf
	v_add_f32_dpp v230, v230, v230 row_half_mirror row_mask:0xf bank_mask:0xf
	v_add_f32_dpp v231, v231, v231 row_half_mirror row_mask:0xf bank_mask:0xf
	v_add_f32_dpp v232, v232, v232 row_half_mirror row_mask:0xf bank_mask:0xf
	v_add_f32_dpp v233, v233, v233 row_half_mirror row_mask:0xf bank_mask:0xf
	s_mov_b32 exec_lo, 0x10001
	s_mov_b32 exec_hi, 0x10001
	ds_write_b32 v238, v230 offset:1984
	ds_write_b32 v238, v231 offset:2000
	ds_write_b32 v238, v232 offset:2016
	ds_write_b32 v238, v233 offset:2032
	s_mov_b64 exec, -1
	s_waitcnt lgkmcnt(0)
	s_cmp_eq_u32 s85, 4
	s_cbranch_scc1 .LBB0_1382
	s_mov_b32 s85, 0
.Lc8_loop:
	s_mul_i32 s16, s85, s22
	v_add_u32_e32 v112, s16, v130
	v_ashrrev_i32_e32 v113, 31, v112
	v_lshl_add_u64 v[16:17], v[112:113], 2, s[4:5]
	global_load_dword v140, v[16:17], off
	v_lshl_add_u32 v139, s85, 10, v114
	s_lshl_b32 s90, s85, 9
	v_add_u32_e32 v198, s90, v156
	v_lshl_add_u32 v2, v131, 2, v139
	s_waitcnt lgkmcnt(0)
	ds_read2st64_b32 v[0:1], v2 offset1:2
	s_waitcnt lgkmcnt(0)
	v_ashrrev_i32_e32 v5, 31, v0
	v_mov_b32_e32 v4, v0
	v_lshlrev_b64 v[4:5], 2, v[4:5]
	v_lshl_add_u64 v[6:7], s[8:9], 0, v[4:5]
	global_load_dword v3, v[6:7], off
	v_lshl_add_u64 v[4:5], s[6:7], 0, v[4:5]
	global_load_dword v0, v[4:5], off
	ds_read_b32 v4, v198
	s_waitcnt lgkmcnt(0)
	s_waitcnt vmcnt(1)
	v_mul_f32_e32 v3, v3, v4
	v_mul_f32_e32 v4, v140, v3
	v_mul_f32_e32 v5, 0x3f3504f3, v4
	v_cmp_nlt_f32_e64 s[18:19], |v5|, 1.0
	s_and_saveexec_b64 s[86:87], s[18:19]
	s_xor_b64 s[18:19], exec, s[86:87]
	s_cbranch_execz .LBB0_1417
	v_fma_f32 v3, |v5|, s74, v136
	v_fma_f32 v3, |v5|, v3, s75
	v_fma_f32 v3, |v5|, v3, s76
	v_fma_f32 v3, |v5|, v3, s77
	v_fma_f32 v3, |v5|, v3, s78
	v_fma_f32 v3, |v5|, v3, s79
	v_fma_f32 v3, |v5|, v3, |v5|
	v_mul_f32_e32 v6, 0xbfb8aa3b, v3
	v_fma_f32 v7, v3, s80, -v6
	v_rndne_f32_e32 v8, v6
	v_fmac_f32_e32 v7, 0xb2a5705f, v3
	v_sub_f32_e32 v6, v6, v8
	v_add_f32_e32 v6, v6, v7
	v_cvt_i32_f32_e32 v7, v8
	v_exp_f32_e32 v6, v6
	v_cmp_nlt_f32_e32 vcc, s81, v3
	v_ldexp_f32 v6, v6, v7
	s_nop 0
	v_cndmask_b32_e32 v6, 0, v6, vcc
	v_cmp_ngt_f32_e32 vcc, s82, v3
	s_nop 1
	v_cndmask_b32_e32 v3, v137, v6, vcc
	v_sub_f32_e32 v6, 1.0, v3
.LBB0_1417:
	s_andn2_saveexec_b64 s[18:19], s[18:19]
	v_mul_f32_e32 v3, v5, v5
	v_fmamk_f32 v6, v3, 0xba1345e1, v134
	v_fmaak_f32 v6, v3, v6, 0xbcdac9b8
	v_fmaak_f32 v6, v3, v6, 0x3de703be
	v_fmaak_f32 v6, v3, v6, 0xbec09330
	v_fmaak_f32 v3, v3, v6, 0x3e0375d0
	v_fma_f32 v6, |v5|, v3, |v5|
	s_or_b64 exec, exec, s[18:19]
	ds_read2st64_b32 v[2:3], v2 offset0:1 offset1:3
	s_waitcnt lgkmcnt(0)
	v_ashrrev_i32_e32 v9, 31, v2
	v_mov_b32_e32 v8, v2
	v_lshlrev_b64 v[8:9], 2, v[8:9]
	v_lshl_add_u64 v[10:11], s[8:9], 0, v[8:9]
	global_load_dword v7, v[10:11], off
	v_lshl_add_u64 v[8:9], s[6:7], 0, v[8:9]
	global_load_dword v2, v[8:9], off
	ds_read_b32 v8, v198 offset:256
	s_waitcnt lgkmcnt(0)
	s_waitcnt vmcnt(1)
	v_mul_f32_e32 v7, v7, v8
	v_mul_f32_e32 v7, v140, v7
	v_mul_f32_e32 v8, 0x3f3504f3, v7
	v_cmp_nlt_f32_e64 s[18:19], |v8|, 1.0
	s_and_saveexec_b64 s[86:87], s[18:19]
	s_xor_b64 s[18:19], exec, s[86:87]
	s_cbranch_execz .LBB0_1421
	v_fma_f32 v9, |v8|, s74, v136
	v_fma_f32 v9, |v8|, v9, s75
	v_fma_f32 v9, |v8|, v9, s76
	v_fma_f32 v9, |v8|, v9, s77
	v_fma_f32 v9, |v8|, v9, s78
	v_fma_f32 v9, |v8|, v9, s79
	v_fma_f32 v9, |v8|, v9, |v8|
	v_mul_f32_e32 v10, 0xbfb8aa3b, v9
	v_fma_f32 v11, v9, s80, -v10
	v_rndne_f32_e32 v12, v10
	v_fmac_f32_e32 v11, 0xb2a5705f, v9
	v_sub_f32_e32 v10, v10, v12
	v_add_f32_e32 v10, v10, v11
	v_cvt_i32_f32_e32 v11, v12
	v_exp_f32_e32 v10, v10
	v_cmp_nlt_f32_e32 vcc, s81, v9
	v_ldexp_f32 v10, v10, v11
	s_nop 0
	v_cndmask_b32_e32 v10, 0, v10, vcc
	v_cmp_ngt_f32_e32 vcc, s82, v9
	s_nop 1
	v_cndmask_b32_e32 v9, v137, v10, vcc
	v_sub_f32_e32 v9, 1.0, v9
.LBB0_1421:
	s_andn2_saveexec_b64 s[18:19], s[18:19]
	v_mul_f32_e32 v9, v8, v8
	v_fmamk_f32 v10, v9, 0xba1345e1, v134
	v_fmaak_f32 v10, v9, v10, 0xbcdac9b8
	v_fmaak_f32 v10, v9, v10, 0x3de703be
	v_fmaak_f32 v10, v9, v10, 0xbec09330
	v_fmaak_f32 v9, v9, v10, 0x3e0375d0
	v_fma_f32 v9, |v8|, v9, |v8|
	s_or_b64 exec, exec, s[18:19]
	v_mul_f32_e32 v0, v1, v0
	v_mul_f32_e32 v0, 0.5, v0
	v_bfi_b32 v1, s83, v6, v5
	v_mul_f32_e32 v0, v4, v0
	v_add_f32_e32 v1, 1.0, v1
	v_mul_f32_e32 v0, v0, v1
	s_waitcnt vmcnt(0)
	v_mul_f32_e32 v1, v3, v2
	v_mul_f32_e32 v1, 0.5, v1
	v_bfi_b32 v2, s83, v9, v8
	v_mul_f32_e32 v1, v7, v1
	v_add_f32_e32 v2, 1.0, v2
	v_mul_f32_e32 v1, v1, v2
	v_lshl_add_u32 v2, v131, 2, v139
	s_waitcnt lgkmcnt(0)
	ds_write2st64_b32 v2, v0, v1 offset0:2 offset1:3
	s_waitcnt lgkmcnt(0)
	s_add_i32 s85, s85, 1
	s_cmp_lt_u32 s85, 8
	s_cbranch_scc1 .Lc8_loop

; __global__ void __launch_bounds__(256, 2) mega(Params P) {
	.amdhsa_kernel _ZN12_GLOBAL__N_14megaENS_6ParamsE
		.amdhsa_group_segment_fixed_size 0
		.amdhsa_private_segment_fixed_size 0
		.amdhsa_kernarg_size 408
		.amdhsa_user_sgpr_count 2
		.amdhsa_user_sgpr_dispatch_ptr 0
		.amdhsa_user_sgpr_queue_ptr 0
		.amdhsa_user_sgpr_kernarg_segment_ptr 1
		.amdhsa_user_sgpr_dispatch_id 0
		.amdhsa_user_sgpr_kernarg_preload_length 0
		.amdhsa_user_sgpr_kernarg_preload_offset 0
		.amdhsa_user_sgpr_private_segment_size 0
		.amdhsa_uses_dynamic_stack 0
		.amdhsa_enable_private_segment 0
		.amdhsa_system_sgpr_workgroup_id_x 1
		.amdhsa_system_sgpr_workgroup_id_y 0
		.amdhsa_system_sgpr_workgroup_id_z 0
		.amdhsa_system_sgpr_workgroup_info 0
		.amdhsa_system_vgpr_workitem_id 0
		.amdhsa_next_free_vgpr 240
		.amdhsa_next_free_sgpr 98
		.amdhsa_accum_offset 240
		.amdhsa_reserve_vcc 1
		.amdhsa_float_round_mode_32 0
		.amdhsa_float_round_mode_16_64 0
		.amdhsa_float_denorm_mode_32 3
		.amdhsa_float_denorm_mode_16_64 3
		.amdhsa_dx10_clamp 1
		.amdhsa_ieee_mode 1
		.amdhsa_fp16_overflow 0
		.amdhsa_tg_split 0
		.amdhsa_exception_fp_ieee_invalid_op 0
		.amdhsa_exception_fp_denorm_src 0
		.amdhsa_exception_fp_ieee_div_zero 0
		.amdhsa_exception_fp_ieee_overflow 0
		.amdhsa_exception_fp_ieee_underflow 0
		.amdhsa_exception_fp_ieee_inexact 0
		.amdhsa_exception_int_div_zero 0
	.end_amdhsa_kernel

; __global__ void __launch_bounds__(256, 2) mega(Params P) {
amdhsa.kernels:
  - .agpr_count:     0
    .args:
      - .offset:         0
        .size:           152
        .value_kind:     by_value
      - .offset:         152
        .size:           4
        .value_kind:     hidden_block_count_x
      - .offset:         156
        .size:           4
        .value_kind:     hidden_block_count_y
      - .offset:         160
        .size:           4
        .value_kind:     hidden_block_count_z
      - .offset:         164
        .size:           2
        .value_kind:     hidden_group_size_x
      - .offset:         166
        .size:           2
        .value_kind:     hidden_group_size_y
      - .offset:         168
        .size:           2
        .value_kind:     hidden_group_size_z
      - .offset:         170
        .size:           2
        .value_kind:     hidden_remainder_x
      - .offset:         172
        .size:           2
        .value_kind:     hidden_remainder_y
      - .offset:         174
        .size:           2
        .value_kind:     hidden_remainder_z
      - .offset:         192
        .size:           8
        .value_kind:     hidden_global_offset_x
      - .offset:         200
        .size:           8
        .value_kind:     hidden_global_offset_y
      - .offset:         208
        .size:           8
        .value_kind:     hidden_global_offset_z
      - .offset:         216
        .size:           2
        .value_kind:     hidden_grid_dims
      - .offset:         272
        .size:           4
        .value_kind:     hidden_dynamic_lds_size
    .group_segment_fixed_size: 0
    .kernarg_segment_align: 8
    .kernarg_segment_size: 408
    .language:       OpenCL C
    .language_version:
      - 2
      - 0
    .max_flat_workgroup_size: 256
    .name:           _ZN12_GLOBAL__N_14megaENS_6ParamsE
    .private_segment_fixed_size: 0
    .sgpr_count:     104
    .sgpr_spill_count: 84
    .symbol:         _ZN12_GLOBAL__N_14megaENS_6ParamsE.kd
    .uniform_work_group_size: 1
    .uses_dynamic_stack: false
    .vgpr_count:     240
    .vgpr_spill_count: 0
    .wavefront_size: 64
